# rows_update phases 6/9/13/16 rewritten by hand: 9 rows per wave, loads 2 rows ahead, DPP reductions, gains hoisted
# speedup vs baseline: 1.0149x; 1.0031x over previous
.LBB0_550:
	s_cmp_lt_i32 s24, 7
	s_cselect_b64 s[4:5], -1, 0
	s_cmp_gt_i32 s25, 6
	s_cselect_b64 s[6:7], -1, 0
	s_and_b64 s[4:5], s[4:5], s[6:7]
	s_andn2_b64 vcc, exec, s[4:5]
	v_lshlrev_b32_e32 v147, 4, v129
	s_cbranch_vccnz .LBB0_655
	s_mov_b64 exec, -1
	s_load_dword s3, s[0:1], 0x148
	s_add_u32 s8, s0, 0x148
	s_addc_u32 s9, s1, 0
	s_load_dwordx2 s[78:79], s[0:1], 0x30
	s_load_dwordx2 s[80:81], s[0:1], 0x38
	v_lshrrev_b32_e32 v0, 6, v129
	v_and_b32_e32 v1, 63, v129
	v_readfirstlane_b32 s68, v0
	v_lshlrev_b32_e32 v0, 4, v1
	v_lshlrev_b32_e32 v1, 3, v1
	v_mov_b32_e32 v2, 0x3a800000
	v_mov_b32_e32 v3, 0x358637bd
	s_lshl_b32 s69, s2, 3
	s_add_u32 s68, s68, s69
	s_waitcnt lgkmcnt(0)
	global_load_dwordx4 v[4:7], v0, s[78:79] offset:0
	global_load_dwordx4 v[8:11], v0, s[78:79] offset:1024
	global_load_dwordx4 v[12:15], v0, s[78:79] offset:2048
	global_load_dwordx4 v[16:19], v0, s[78:79] offset:3072
	global_load_dwordx4 v[100:103], v0, s[80:81] offset:0
	global_load_dwordx4 v[104:107], v0, s[80:81] offset:1024
	global_load_dwordx4 v[108:111], v0, s[80:81] offset:2048
	global_load_dwordx4 v[112:115], v0, s[80:81] offset:3072
	s_lshl_b32 s86, s68, 11
	s_add_u32 s70, s46, s86
	s_addc_u32 s71, s47, 0
	s_add_u32 s72, s50, s86
	s_addc_u32 s73, s51, 0
	s_mov_b64 s[74:75], s[72:73]
	s_add_u32 s76, s44, s86
	s_addc_u32 s77, s45, 0
	s_cmpk_lt_u32 s68, 0x200
	s_cselect_b32 s82, 1, 0
	global_load_dwordx2 v[20:21], v1, s[70:71] offset:0
	global_load_dwordx2 v[22:23], v1, s[70:71] offset:512
	global_load_dwordx2 v[24:25], v1, s[70:71] offset:1024
	global_load_dwordx2 v[26:27], v1, s[70:71] offset:1536
	global_load_dwordx2 v[28:29], v1, s[72:73] offset:0
	global_load_dwordx2 v[30:31], v1, s[72:73] offset:512
	global_load_dwordx2 v[32:33], v1, s[72:73] offset:1024
	global_load_dwordx2 v[34:35], v1, s[72:73] offset:1536
	s_add_u32 s70, s70, 0x400000
	s_addc_u32 s71, s71, 0
	s_add_u32 s72, s72, 0x400000
	s_addc_u32 s73, s73, 0
	global_load_dwordx2 v[36:37], v1, s[70:71] offset:0
	global_load_dwordx2 v[38:39], v1, s[70:71] offset:512
	global_load_dwordx2 v[40:41], v1, s[70:71] offset:1024
	global_load_dwordx2 v[42:43], v1, s[70:71] offset:1536
	global_load_dwordx2 v[44:45], v1, s[72:73] offset:0
	global_load_dwordx2 v[46:47], v1, s[72:73] offset:512
	global_load_dwordx2 v[48:49], v1, s[72:73] offset:1024
	global_load_dwordx2 v[50:51], v1, s[72:73] offset:1536
	s_add_u32 s70, s70, 0x400000
	s_addc_u32 s71, s71, 0
	s_add_u32 s72, s72, 0x400000
	s_addc_u32 s73, s73, 0
	global_load_dwordx2 v[52:53], v1, s[70:71] offset:0
	global_load_dwordx2 v[54:55], v1, s[70:71] offset:512
	global_load_dwordx2 v[56:57], v1, s[70:71] offset:1024
	global_load_dwordx2 v[58:59], v1, s[70:71] offset:1536
	global_load_dwordx2 v[60:61], v1, s[72:73] offset:0
	global_load_dwordx2 v[62:63], v1, s[72:73] offset:512
	global_load_dwordx2 v[64:65], v1, s[72:73] offset:1024
	global_load_dwordx2 v[66:67], v1, s[72:73] offset:1536
	s_add_u32 s70, s70, 0x400000
	s_addc_u32 s71, s71, 0
	s_add_u32 s72, s72, 0x400000
	s_addc_u32 s73, s73, 0
	s_waitcnt vmcnt(16)
	v_lshlrev_b32_e32 v68, 16, v20
	v_and_b32_e32 v69, 0xffff0000, v20
	v_lshlrev_b32_e32 v70, 16, v21
	v_and_b32_e32 v71, 0xffff0000, v21
	v_lshlrev_b32_e32 v72, 16, v22
	v_and_b32_e32 v73, 0xffff0000, v22
	v_lshlrev_b32_e32 v74, 16, v23
	v_and_b32_e32 v75, 0xffff0000, v23
	v_lshlrev_b32_e32 v76, 16, v24
	v_and_b32_e32 v77, 0xffff0000, v24
	v_lshlrev_b32_e32 v78, 16, v25
	v_and_b32_e32 v79, 0xffff0000, v25
	v_lshlrev_b32_e32 v80, 16, v26
	v_and_b32_e32 v81, 0xffff0000, v26
	v_lshlrev_b32_e32 v82, 16, v27
	v_and_b32_e32 v83, 0xffff0000, v27
	v_mul_f32_e32 v86, v68, v68
	v_mul_f32_e32 v87, v72, v72
	v_mul_f32_e32 v88, v76, v76
	v_mul_f32_e32 v89, v80, v80
	v_fmac_f32_e32 v86, v69, v69
	v_fmac_f32_e32 v87, v73, v73
	v_fmac_f32_e32 v88, v77, v77
	v_fmac_f32_e32 v89, v81, v81
	v_fmac_f32_e32 v86, v70, v70
	v_fmac_f32_e32 v87, v74, v74
	v_fmac_f32_e32 v88, v78, v78
	v_fmac_f32_e32 v89, v82, v82
	v_fmac_f32_e32 v86, v71, v71
	v_fmac_f32_e32 v87, v75, v75
	v_fmac_f32_e32 v88, v79, v79
	v_fmac_f32_e32 v89, v83, v83
	v_add_f32_e32 v84, v86, v87
	v_add_f32_e32 v84, v84, v88
	v_add_f32_e32 v84, v84, v89
	v_lshlrev_b32_e32 v160, 16, v28
	v_and_b32_e32 v161, 0xffff0000, v28
	v_add_f32_dpp v84, v84, v84 quad_perm:[1,0,3,2] row_mask:0xf bank_mask:0xf
	v_lshlrev_b32_e32 v162, 16, v29
	v_and_b32_e32 v163, 0xffff0000, v29
	v_add_f32_dpp v84, v84, v84 quad_perm:[2,3,0,1] row_mask:0xf bank_mask:0xf
	v_lshlrev_b32_e32 v164, 16, v30
	v_and_b32_e32 v165, 0xffff0000, v30
	v_add_f32_dpp v84, v84, v84 row_half_mirror row_mask:0xf bank_mask:0xf
	v_lshlrev_b32_e32 v166, 16, v31
	v_and_b32_e32 v167, 0xffff0000, v31
	v_add_f32_dpp v84, v84, v84 row_mirror row_mask:0xf bank_mask:0xf
	v_lshlrev_b32_e32 v168, 16, v32
	v_and_b32_e32 v169, 0xffff0000, v32
	v_add_f32_dpp v84, v84, v84 row_bcast:15 row_mask:0xa bank_mask:0xf
	v_lshlrev_b32_e32 v170, 16, v33
	v_and_b32_e32 v171, 0xffff0000, v33
	v_add_f32_dpp v84, v84, v84 row_bcast:31 row_mask:0xc bank_mask:0xf
	v_lshlrev_b32_e32 v172, 16, v34
	v_and_b32_e32 v173, 0xffff0000, v34
	v_lshlrev_b32_e32 v174, 16, v35
	v_and_b32_e32 v175, 0xffff0000, v35
	s_nop 0
	v_readlane_b32 s83, v84, 63
	s_nop 2
	v_fma_f32 v84, s83, v2, v3
	v_rsq_f32_e32 v84, v84
	s_nop 0
	v_mul_f32_e32 v68, v68, v84
	v_mul_f32_e32 v69, v69, v84
	v_mul_f32_e32 v70, v70, v84
	v_mul_f32_e32 v71, v71, v84
	v_mul_f32_e32 v72, v72, v84
	v_mul_f32_e32 v73, v73, v84
	v_mul_f32_e32 v74, v74, v84
	v_mul_f32_e32 v75, v75, v84
	v_mul_f32_e32 v76, v76, v84
	v_mul_f32_e32 v77, v77, v84
	v_mul_f32_e32 v78, v78, v84
	v_mul_f32_e32 v79, v79, v84
	v_mul_f32_e32 v80, v80, v84
	v_mul_f32_e32 v81, v81, v84
	v_mul_f32_e32 v82, v82, v84
	v_mul_f32_e32 v83, v83, v84
	v_fma_f32 v68, v68, v4, v160
	v_fma_f32 v69, v69, v5, v161
	v_fma_f32 v70, v70, v6, v162
	v_fma_f32 v71, v71, v7, v163
	v_fma_f32 v72, v72, v8, v164
	v_fma_f32 v73, v73, v9, v165
	v_fma_f32 v74, v74, v10, v166
	v_fma_f32 v75, v75, v11, v167
	v_fma_f32 v76, v76, v12, v168
	v_fma_f32 v77, v77, v13, v169
	v_fma_f32 v78, v78, v14, v170
	v_fma_f32 v79, v79, v15, v171
	v_fma_f32 v80, v80, v16, v172
	v_fma_f32 v81, v81, v17, v173
	v_fma_f32 v82, v82, v18, v174
	v_fma_f32 v83, v83, v19, v175
	v_mul_f32_e32 v86, v68, v68
	v_mul_f32_e32 v87, v72, v72
	v_mul_f32_e32 v88, v76, v76
	v_mul_f32_e32 v89, v80, v80
	v_fmac_f32_e32 v86, v69, v69
	v_fmac_f32_e32 v87, v73, v73
	v_fmac_f32_e32 v88, v77, v77
	v_fmac_f32_e32 v89, v81, v81
	v_fmac_f32_e32 v86, v70, v70
	v_fmac_f32_e32 v87, v74, v74
	v_fmac_f32_e32 v88, v78, v78
	v_fmac_f32_e32 v89, v82, v82
	v_fmac_f32_e32 v86, v71, v71
	v_fmac_f32_e32 v87, v75, v75
	v_fmac_f32_e32 v88, v79, v79
	v_fmac_f32_e32 v89, v83, v83
	v_add_f32_e32 v85, v86, v87
	v_add_f32_e32 v85, v85, v88
	v_add_f32_e32 v85, v85, v89
	v_cvt_pk_bf16_f32 v90, v68, v69
	v_cvt_pk_bf16_f32 v91, v70, v71
	v_add_f32_dpp v85, v85, v85 quad_perm:[1,0,3,2] row_mask:0xf bank_mask:0xf
	v_cvt_pk_bf16_f32 v92, v72, v73
	v_cvt_pk_bf16_f32 v93, v74, v75
	v_add_f32_dpp v85, v85, v85 quad_perm:[2,3,0,1] row_mask:0xf bank_mask:0xf
	v_cvt_pk_bf16_f32 v94, v76, v77
	v_cvt_pk_bf16_f32 v95, v78, v79
	v_add_f32_dpp v85, v85, v85 row_half_mirror row_mask:0xf bank_mask:0xf
	v_cvt_pk_bf16_f32 v96, v80, v81
	v_cvt_pk_bf16_f32 v97, v82, v83
	v_add_f32_dpp v85, v85, v85 row_mirror row_mask:0xf bank_mask:0xf
	s_nop 1
	v_add_f32_dpp v85, v85, v85 row_bcast:15 row_mask:0xa bank_mask:0xf
	s_nop 1
	v_add_f32_dpp v85, v85, v85 row_bcast:31 row_mask:0xc bank_mask:0xf
	global_store_dwordx2 v1, v[90:91], s[74:75] offset:0
	global_store_dwordx2 v1, v[92:93], s[74:75] offset:512
	global_store_dwordx2 v1, v[94:95], s[74:75] offset:1024
	global_store_dwordx2 v1, v[96:97], s[74:75] offset:1536
	v_readlane_b32 s84, v85, 63
	s_add_u32 s74, s74, 0x400000
	s_addc_u32 s75, s75, 0
	s_nop 0
	v_fma_f32 v85, s84, v2, v3
	v_rsq_f32_e32 v85, v85
	s_nop 0
	v_mul_f32_e32 v68, v68, v85
	v_mul_f32_e32 v69, v69, v85
	v_mul_f32_e32 v70, v70, v85
	v_mul_f32_e32 v71, v71, v85
	v_mul_f32_e32 v72, v72, v85
	v_mul_f32_e32 v73, v73, v85
	v_mul_f32_e32 v74, v74, v85
	v_mul_f32_e32 v75, v75, v85
	v_mul_f32_e32 v76, v76, v85
	v_mul_f32_e32 v77, v77, v85
	v_mul_f32_e32 v78, v78, v85
	v_mul_f32_e32 v79, v79, v85
	v_mul_f32_e32 v80, v80, v85
	v_mul_f32_e32 v81, v81, v85
	v_mul_f32_e32 v82, v82, v85
	v_mul_f32_e32 v83, v83, v85
	v_mul_f32_e32 v68, v68, v100
	v_mul_f32_e32 v69, v69, v101
	v_mul_f32_e32 v70, v70, v102
	v_mul_f32_e32 v71, v71, v103
	v_mul_f32_e32 v72, v72, v104
	v_mul_f32_e32 v73, v73, v105
	v_mul_f32_e32 v74, v74, v106
	v_mul_f32_e32 v75, v75, v107
	v_mul_f32_e32 v76, v76, v108
	v_mul_f32_e32 v77, v77, v109
	v_mul_f32_e32 v78, v78, v110
	v_mul_f32_e32 v79, v79, v111
	v_mul_f32_e32 v80, v80, v112
	v_mul_f32_e32 v81, v81, v113
	v_mul_f32_e32 v82, v82, v114
	v_mul_f32_e32 v83, v83, v115
	v_cvt_pk_bf16_f32 v176, v68, v69
	v_cvt_pk_bf16_f32 v177, v70, v71
	v_cvt_pk_bf16_f32 v178, v72, v73
	v_cvt_pk_bf16_f32 v179, v74, v75
	v_cvt_pk_bf16_f32 v180, v76, v77
	v_cvt_pk_bf16_f32 v181, v78, v79
	v_cvt_pk_bf16_f32 v182, v80, v81
	v_cvt_pk_bf16_f32 v183, v82, v83
	global_store_dwordx2 v1, v[176:177], s[76:77] offset:0
	global_store_dwordx2 v1, v[178:179], s[76:77] offset:512
	global_store_dwordx2 v1, v[180:181], s[76:77] offset:1024
	global_store_dwordx2 v1, v[182:183], s[76:77] offset:1536
	s_add_u32 s76, s76, 0x400000
	s_addc_u32 s77, s77, 0
	global_load_dwordx2 v[20:21], v1, s[70:71] offset:0
	global_load_dwordx2 v[22:23], v1, s[70:71] offset:512
	global_load_dwordx2 v[24:25], v1, s[70:71] offset:1024
	global_load_dwordx2 v[26:27], v1, s[70:71] offset:1536
	global_load_dwordx2 v[28:29], v1, s[72:73] offset:0
	global_load_dwordx2 v[30:31], v1, s[72:73] offset:512
	global_load_dwordx2 v[32:33], v1, s[72:73] offset:1024
	global_load_dwordx2 v[34:35], v1, s[72:73] offset:1536
	s_add_u32 s70, s70, 0x400000
	s_addc_u32 s71, s71, 0
	s_add_u32 s72, s72, 0x400000
	s_addc_u32 s73, s73, 0
	s_waitcnt vmcnt(24)
	v_lshlrev_b32_e32 v68, 16, v36
	v_and_b32_e32 v69, 0xffff0000, v36
	v_lshlrev_b32_e32 v70, 16, v37
	v_and_b32_e32 v71, 0xffff0000, v37
	v_lshlrev_b32_e32 v72, 16, v38
	v_and_b32_e32 v73, 0xffff0000, v38
	v_lshlrev_b32_e32 v74, 16, v39
	v_and_b32_e32 v75, 0xffff0000, v39
	v_lshlrev_b32_e32 v76, 16, v40
	v_and_b32_e32 v77, 0xffff0000, v40
	v_lshlrev_b32_e32 v78, 16, v41
	v_and_b32_e32 v79, 0xffff0000, v41
	v_lshlrev_b32_e32 v80, 16, v42
	v_and_b32_e32 v81, 0xffff0000, v42
	v_lshlrev_b32_e32 v82, 16, v43
	v_and_b32_e32 v83, 0xffff0000, v43
	v_mul_f32_e32 v86, v68, v68
	v_mul_f32_e32 v87, v72, v72
	v_mul_f32_e32 v88, v76, v76
	v_mul_f32_e32 v89, v80, v80
	v_fmac_f32_e32 v86, v69, v69
	v_fmac_f32_e32 v87, v73, v73
	v_fmac_f32_e32 v88, v77, v77
	v_fmac_f32_e32 v89, v81, v81
	v_fmac_f32_e32 v86, v70, v70
	v_fmac_f32_e32 v87, v74, v74
	v_fmac_f32_e32 v88, v78, v78
	v_fmac_f32_e32 v89, v82, v82
	v_fmac_f32_e32 v86, v71, v71
	v_fmac_f32_e32 v87, v75, v75
	v_fmac_f32_e32 v88, v79, v79
	v_fmac_f32_e32 v89, v83, v83
	v_add_f32_e32 v84, v86, v87
	v_add_f32_e32 v84, v84, v88
	v_add_f32_e32 v84, v84, v89
	v_lshlrev_b32_e32 v160, 16, v44
	v_and_b32_e32 v161, 0xffff0000, v44
	v_add_f32_dpp v84, v84, v84 quad_perm:[1,0,3,2] row_mask:0xf bank_mask:0xf
	v_lshlrev_b32_e32 v162, 16, v45
	v_and_b32_e32 v163, 0xffff0000, v45
	v_add_f32_dpp v84, v84, v84 quad_perm:[2,3,0,1] row_mask:0xf bank_mask:0xf
	v_lshlrev_b32_e32 v164, 16, v46
	v_and_b32_e32 v165, 0xffff0000, v46
	v_add_f32_dpp v84, v84, v84 row_half_mirror row_mask:0xf bank_mask:0xf
	v_lshlrev_b32_e32 v166, 16, v47
	v_and_b32_e32 v167, 0xffff0000, v47
	v_add_f32_dpp v84, v84, v84 row_mirror row_mask:0xf bank_mask:0xf
	v_lshlrev_b32_e32 v168, 16, v48
	v_and_b32_e32 v169, 0xffff0000, v48
	v_add_f32_dpp v84, v84, v84 row_bcast:15 row_mask:0xa bank_mask:0xf
	v_lshlrev_b32_e32 v170, 16, v49
	v_and_b32_e32 v171, 0xffff0000, v49
	v_add_f32_dpp v84, v84, v84 row_bcast:31 row_mask:0xc bank_mask:0xf
	v_lshlrev_b32_e32 v172, 16, v50
	v_and_b32_e32 v173, 0xffff0000, v50
	v_lshlrev_b32_e32 v174, 16, v51
	v_and_b32_e32 v175, 0xffff0000, v51
	s_nop 0
	v_readlane_b32 s83, v84, 63
	s_nop 2
	v_fma_f32 v84, s83, v2, v3
	v_rsq_f32_e32 v84, v84
	s_nop 0
	v_mul_f32_e32 v68, v68, v84
	v_mul_f32_e32 v69, v69, v84
	v_mul_f32_e32 v70, v70, v84
	v_mul_f32_e32 v71, v71, v84
	v_mul_f32_e32 v72, v72, v84
	v_mul_f32_e32 v73, v73, v84
	v_mul_f32_e32 v74, v74, v84
	v_mul_f32_e32 v75, v75, v84
	v_mul_f32_e32 v76, v76, v84
	v_mul_f32_e32 v77, v77, v84
	v_mul_f32_e32 v78, v78, v84
	v_mul_f32_e32 v79, v79, v84
	v_mul_f32_e32 v80, v80, v84
	v_mul_f32_e32 v81, v81, v84
	v_mul_f32_e32 v82, v82, v84
	v_mul_f32_e32 v83, v83, v84
	v_fma_f32 v68, v68, v4, v160
	v_fma_f32 v69, v69, v5, v161
	v_fma_f32 v70, v70, v6, v162
	v_fma_f32 v71, v71, v7, v163
	v_fma_f32 v72, v72, v8, v164
	v_fma_f32 v73, v73, v9, v165
	v_fma_f32 v74, v74, v10, v166
	v_fma_f32 v75, v75, v11, v167
	v_fma_f32 v76, v76, v12, v168
	v_fma_f32 v77, v77, v13, v169
	v_fma_f32 v78, v78, v14, v170
	v_fma_f32 v79, v79, v15, v171
	v_fma_f32 v80, v80, v16, v172
	v_fma_f32 v81, v81, v17, v173
	v_fma_f32 v82, v82, v18, v174
	v_fma_f32 v83, v83, v19, v175
	v_mul_f32_e32 v86, v68, v68
	v_mul_f32_e32 v87, v72, v72
	v_mul_f32_e32 v88, v76, v76
	v_mul_f32_e32 v89, v80, v80
	v_fmac_f32_e32 v86, v69, v69
	v_fmac_f32_e32 v87, v73, v73
	v_fmac_f32_e32 v88, v77, v77
	v_fmac_f32_e32 v89, v81, v81
	v_fmac_f32_e32 v86, v70, v70
	v_fmac_f32_e32 v87, v74, v74
	v_fmac_f32_e32 v88, v78, v78
	v_fmac_f32_e32 v89, v82, v82
	v_fmac_f32_e32 v86, v71, v71
	v_fmac_f32_e32 v87, v75, v75
	v_fmac_f32_e32 v88, v79, v79
	v_fmac_f32_e32 v89, v83, v83
	v_add_f32_e32 v85, v86, v87
	v_add_f32_e32 v85, v85, v88
	v_add_f32_e32 v85, v85, v89
	v_cvt_pk_bf16_f32 v90, v68, v69
	v_cvt_pk_bf16_f32 v91, v70, v71
	v_add_f32_dpp v85, v85, v85 quad_perm:[1,0,3,2] row_mask:0xf bank_mask:0xf
	v_cvt_pk_bf16_f32 v92, v72, v73
	v_cvt_pk_bf16_f32 v93, v74, v75
	v_add_f32_dpp v85, v85, v85 quad_perm:[2,3,0,1] row_mask:0xf bank_mask:0xf
	v_cvt_pk_bf16_f32 v94, v76, v77
	v_cvt_pk_bf16_f32 v95, v78, v79
	v_add_f32_dpp v85, v85, v85 row_half_mirror row_mask:0xf bank_mask:0xf
	v_cvt_pk_bf16_f32 v96, v80, v81
	v_cvt_pk_bf16_f32 v97, v82, v83
	v_add_f32_dpp v85, v85, v85 row_mirror row_mask:0xf bank_mask:0xf
	s_nop 1
	v_add_f32_dpp v85, v85, v85 row_bcast:15 row_mask:0xa bank_mask:0xf
	s_nop 1
	v_add_f32_dpp v85, v85, v85 row_bcast:31 row_mask:0xc bank_mask:0xf
	global_store_dwordx2 v1, v[90:91], s[74:75] offset:0
	global_store_dwordx2 v1, v[92:93], s[74:75] offset:512
	global_store_dwordx2 v1, v[94:95], s[74:75] offset:1024
	global_store_dwordx2 v1, v[96:97], s[74:75] offset:1536
	v_readlane_b32 s84, v85, 63
	s_add_u32 s74, s74, 0x400000
	s_addc_u32 s75, s75, 0
	s_nop 0
	v_fma_f32 v85, s84, v2, v3
	v_rsq_f32_e32 v85, v85
	s_nop 0
	v_mul_f32_e32 v68, v68, v85
	v_mul_f32_e32 v69, v69, v85
	v_mul_f32_e32 v70, v70, v85
	v_mul_f32_e32 v71, v71, v85
	v_mul_f32_e32 v72, v72, v85
	v_mul_f32_e32 v73, v73, v85
	v_mul_f32_e32 v74, v74, v85
	v_mul_f32_e32 v75, v75, v85
	v_mul_f32_e32 v76, v76, v85
	v_mul_f32_e32 v77, v77, v85
	v_mul_f32_e32 v78, v78, v85
	v_mul_f32_e32 v79, v79, v85
	v_mul_f32_e32 v80, v80, v85
	v_mul_f32_e32 v81, v81, v85
	v_mul_f32_e32 v82, v82, v85
	v_mul_f32_e32 v83, v83, v85
	v_mul_f32_e32 v68, v68, v100
	v_mul_f32_e32 v69, v69, v101
	v_mul_f32_e32 v70, v70, v102
	v_mul_f32_e32 v71, v71, v103
	v_mul_f32_e32 v72, v72, v104
	v_mul_f32_e32 v73, v73, v105
	v_mul_f32_e32 v74, v74, v106
	v_mul_f32_e32 v75, v75, v107
	v_mul_f32_e32 v76, v76, v108
	v_mul_f32_e32 v77, v77, v109
	v_mul_f32_e32 v78, v78, v110
	v_mul_f32_e32 v79, v79, v111
	v_mul_f32_e32 v80, v80, v112
	v_mul_f32_e32 v81, v81, v113
	v_mul_f32_e32 v82, v82, v114
	v_mul_f32_e32 v83, v83, v115
	v_cvt_pk_bf16_f32 v176, v68, v69
	v_cvt_pk_bf16_f32 v177, v70, v71
	v_cvt_pk_bf16_f32 v178, v72, v73
	v_cvt_pk_bf16_f32 v179, v74, v75
	v_cvt_pk_bf16_f32 v180, v76, v77
	v_cvt_pk_bf16_f32 v181, v78, v79
	v_cvt_pk_bf16_f32 v182, v80, v81
	v_cvt_pk_bf16_f32 v183, v82, v83
	global_store_dwordx2 v1, v[176:177], s[76:77] offset:0
	global_store_dwordx2 v1, v[178:179], s[76:77] offset:512
	global_store_dwordx2 v1, v[180:181], s[76:77] offset:1024
	global_store_dwordx2 v1, v[182:183], s[76:77] offset:1536
	s_add_u32 s76, s76, 0x400000
	s_addc_u32 s77, s77, 0
	global_load_dwordx2 v[36:37], v1, s[70:71] offset:0
	global_load_dwordx2 v[38:39], v1, s[70:71] offset:512
	global_load_dwordx2 v[40:41], v1, s[70:71] offset:1024
	global_load_dwordx2 v[42:43], v1, s[70:71] offset:1536
	global_load_dwordx2 v[44:45], v1, s[72:73] offset:0
	global_load_dwordx2 v[46:47], v1, s[72:73] offset:512
	global_load_dwordx2 v[48:49], v1, s[72:73] offset:1024
	global_load_dwordx2 v[50:51], v1, s[72:73] offset:1536
	s_add_u32 s70, s70, 0x400000
	s_addc_u32 s71, s71, 0
	s_add_u32 s72, s72, 0x400000
	s_addc_u32 s73, s73, 0
	s_waitcnt vmcnt(32)
	v_lshlrev_b32_e32 v68, 16, v52
	v_and_b32_e32 v69, 0xffff0000, v52
	v_lshlrev_b32_e32 v70, 16, v53
	v_and_b32_e32 v71, 0xffff0000, v53
	v_lshlrev_b32_e32 v72, 16, v54
	v_and_b32_e32 v73, 0xffff0000, v54
	v_lshlrev_b32_e32 v74, 16, v55
	v_and_b32_e32 v75, 0xffff0000, v55
	v_lshlrev_b32_e32 v76, 16, v56
	v_and_b32_e32 v77, 0xffff0000, v56
	v_lshlrev_b32_e32 v78, 16, v57
	v_and_b32_e32 v79, 0xffff0000, v57
	v_lshlrev_b32_e32 v80, 16, v58
	v_and_b32_e32 v81, 0xffff0000, v58
	v_lshlrev_b32_e32 v82, 16, v59
	v_and_b32_e32 v83, 0xffff0000, v59
	v_mul_f32_e32 v86, v68, v68
	v_mul_f32_e32 v87, v72, v72
	v_mul_f32_e32 v88, v76, v76
	v_mul_f32_e32 v89, v80, v80
	v_fmac_f32_e32 v86, v69, v69
	v_fmac_f32_e32 v87, v73, v73
	v_fmac_f32_e32 v88, v77, v77
	v_fmac_f32_e32 v89, v81, v81
	v_fmac_f32_e32 v86, v70, v70
	v_fmac_f32_e32 v87, v74, v74
	v_fmac_f32_e32 v88, v78, v78
	v_fmac_f32_e32 v89, v82, v82
	v_fmac_f32_e32 v86, v71, v71
	v_fmac_f32_e32 v87, v75, v75
	v_fmac_f32_e32 v88, v79, v79
	v_fmac_f32_e32 v89, v83, v83
	v_add_f32_e32 v84, v86, v87
	v_add_f32_e32 v84, v84, v88
	v_add_f32_e32 v84, v84, v89
	v_lshlrev_b32_e32 v160, 16, v60
	v_and_b32_e32 v161, 0xffff0000, v60
	v_add_f32_dpp v84, v84, v84 quad_perm:[1,0,3,2] row_mask:0xf bank_mask:0xf
	v_lshlrev_b32_e32 v162, 16, v61
	v_and_b32_e32 v163, 0xffff0000, v61
	v_add_f32_dpp v84, v84, v84 quad_perm:[2,3,0,1] row_mask:0xf bank_mask:0xf
	v_lshlrev_b32_e32 v164, 16, v62
	v_and_b32_e32 v165, 0xffff0000, v62
	v_add_f32_dpp v84, v84, v84 row_half_mirror row_mask:0xf bank_mask:0xf
	v_lshlrev_b32_e32 v166, 16, v63
	v_and_b32_e32 v167, 0xffff0000, v63
	v_add_f32_dpp v84, v84, v84 row_mirror row_mask:0xf bank_mask:0xf
	v_lshlrev_b32_e32 v168, 16, v64
	v_and_b32_e32 v169, 0xffff0000, v64
	v_add_f32_dpp v84, v84, v84 row_bcast:15 row_mask:0xa bank_mask:0xf
	v_lshlrev_b32_e32 v170, 16, v65
	v_and_b32_e32 v171, 0xffff0000, v65
	v_add_f32_dpp v84, v84, v84 row_bcast:31 row_mask:0xc bank_mask:0xf
	v_lshlrev_b32_e32 v172, 16, v66
	v_and_b32_e32 v173, 0xffff0000, v66
	v_lshlrev_b32_e32 v174, 16, v67
	v_and_b32_e32 v175, 0xffff0000, v67
	s_nop 0
	v_readlane_b32 s83, v84, 63
	s_nop 2
	v_fma_f32 v84, s83, v2, v3
	v_rsq_f32_e32 v84, v84
	s_nop 0
	v_mul_f32_e32 v68, v68, v84
	v_mul_f32_e32 v69, v69, v84
	v_mul_f32_e32 v70, v70, v84
	v_mul_f32_e32 v71, v71, v84
	v_mul_f32_e32 v72, v72, v84
	v_mul_f32_e32 v73, v73, v84
	v_mul_f32_e32 v74, v74, v84
	v_mul_f32_e32 v75, v75, v84
	v_mul_f32_e32 v76, v76, v84
	v_mul_f32_e32 v77, v77, v84
	v_mul_f32_e32 v78, v78, v84
	v_mul_f32_e32 v79, v79, v84
	v_mul_f32_e32 v80, v80, v84
	v_mul_f32_e32 v81, v81, v84
	v_mul_f32_e32 v82, v82, v84
	v_mul_f32_e32 v83, v83, v84
	v_fma_f32 v68, v68, v4, v160
	v_fma_f32 v69, v69, v5, v161
	v_fma_f32 v70, v70, v6, v162
	v_fma_f32 v71, v71, v7, v163
	v_fma_f32 v72, v72, v8, v164
	v_fma_f32 v73, v73, v9, v165
	v_fma_f32 v74, v74, v10, v166
	v_fma_f32 v75, v75, v11, v167
	v_fma_f32 v76, v76, v12, v168
	v_fma_f32 v77, v77, v13, v169
	v_fma_f32 v78, v78, v14, v170
	v_fma_f32 v79, v79, v15, v171
	v_fma_f32 v80, v80, v16, v172
	v_fma_f32 v81, v81, v17, v173
	v_fma_f32 v82, v82, v18, v174
	v_fma_f32 v83, v83, v19, v175
	v_mul_f32_e32 v86, v68, v68
	v_mul_f32_e32 v87, v72, v72
	v_mul_f32_e32 v88, v76, v76
	v_mul_f32_e32 v89, v80, v80
	v_fmac_f32_e32 v86, v69, v69
	v_fmac_f32_e32 v87, v73, v73
	v_fmac_f32_e32 v88, v77, v77
	v_fmac_f32_e32 v89, v81, v81
	v_fmac_f32_e32 v86, v70, v70
	v_fmac_f32_e32 v87, v74, v74
	v_fmac_f32_e32 v88, v78, v78
	v_fmac_f32_e32 v89, v82, v82
	v_fmac_f32_e32 v86, v71, v71
	v_fmac_f32_e32 v87, v75, v75
	v_fmac_f32_e32 v88, v79, v79
	v_fmac_f32_e32 v89, v83, v83
	v_add_f32_e32 v85, v86, v87
	v_add_f32_e32 v85, v85, v88
	v_add_f32_e32 v85, v85, v89
	v_cvt_pk_bf16_f32 v90, v68, v69
	v_cvt_pk_bf16_f32 v91, v70, v71
	v_add_f32_dpp v85, v85, v85 quad_perm:[1,0,3,2] row_mask:0xf bank_mask:0xf
	v_cvt_pk_bf16_f32 v92, v72, v73
	v_cvt_pk_bf16_f32 v93, v74, v75
	v_add_f32_dpp v85, v85, v85 quad_perm:[2,3,0,1] row_mask:0xf bank_mask:0xf
	v_cvt_pk_bf16_f32 v94, v76, v77
	v_cvt_pk_bf16_f32 v95, v78, v79
	v_add_f32_dpp v85, v85, v85 row_half_mirror row_mask:0xf bank_mask:0xf
	v_cvt_pk_bf16_f32 v96, v80, v81
	v_cvt_pk_bf16_f32 v97, v82, v83
	v_add_f32_dpp v85, v85, v85 row_mirror row_mask:0xf bank_mask:0xf
	s_nop 1
	v_add_f32_dpp v85, v85, v85 row_bcast:15 row_mask:0xa bank_mask:0xf
	s_nop 1
	v_add_f32_dpp v85, v85, v85 row_bcast:31 row_mask:0xc bank_mask:0xf
	global_store_dwordx2 v1, v[90:91], s[74:75] offset:0
	global_store_dwordx2 v1, v[92:93], s[74:75] offset:512
	global_store_dwordx2 v1, v[94:95], s[74:75] offset:1024
	global_store_dwordx2 v1, v[96:97], s[74:75] offset:1536
	v_readlane_b32 s84, v85, 63
	s_add_u32 s74, s74, 0x400000
	s_addc_u32 s75, s75, 0
	s_nop 0
	v_fma_f32 v85, s84, v2, v3
	v_rsq_f32_e32 v85, v85
	s_nop 0
	v_mul_f32_e32 v68, v68, v85
	v_mul_f32_e32 v69, v69, v85
	v_mul_f32_e32 v70, v70, v85
	v_mul_f32_e32 v71, v71, v85
	v_mul_f32_e32 v72, v72, v85
	v_mul_f32_e32 v73, v73, v85
	v_mul_f32_e32 v74, v74, v85
	v_mul_f32_e32 v75, v75, v85
	v_mul_f32_e32 v76, v76, v85
	v_mul_f32_e32 v77, v77, v85
	v_mul_f32_e32 v78, v78, v85
	v_mul_f32_e32 v79, v79, v85
	v_mul_f32_e32 v80, v80, v85
	v_mul_f32_e32 v81, v81, v85
	v_mul_f32_e32 v82, v82, v85
	v_mul_f32_e32 v83, v83, v85
	v_mul_f32_e32 v68, v68, v100
	v_mul_f32_e32 v69, v69, v101
	v_mul_f32_e32 v70, v70, v102
	v_mul_f32_e32 v71, v71, v103
	v_mul_f32_e32 v72, v72, v104
	v_mul_f32_e32 v73, v73, v105
	v_mul_f32_e32 v74, v74, v106
	v_mul_f32_e32 v75, v75, v107
	v_mul_f32_e32 v76, v76, v108
	v_mul_f32_e32 v77, v77, v109
	v_mul_f32_e32 v78, v78, v110
	v_mul_f32_e32 v79, v79, v111
	v_mul_f32_e32 v80, v80, v112
	v_mul_f32_e32 v81, v81, v113
	v_mul_f32_e32 v82, v82, v114
	v_mul_f32_e32 v83, v83, v115
	v_cvt_pk_bf16_f32 v176, v68, v69
	v_cvt_pk_bf16_f32 v177, v70, v71
	v_cvt_pk_bf16_f32 v178, v72, v73
	v_cvt_pk_bf16_f32 v179, v74, v75
	v_cvt_pk_bf16_f32 v180, v76, v77
	v_cvt_pk_bf16_f32 v181, v78, v79
	v_cvt_pk_bf16_f32 v182, v80, v81
	v_cvt_pk_bf16_f32 v183, v82, v83
	global_store_dwordx2 v1, v[176:177], s[76:77] offset:0
	global_store_dwordx2 v1, v[178:179], s[76:77] offset:512
	global_store_dwordx2 v1, v[180:181], s[76:77] offset:1024
	global_store_dwordx2 v1, v[182:183], s[76:77] offset:1536
	s_add_u32 s76, s76, 0x400000
	s_addc_u32 s77, s77, 0
	global_load_dwordx2 v[52:53], v1, s[70:71] offset:0
	global_load_dwordx2 v[54:55], v1, s[70:71] offset:512
	global_load_dwordx2 v[56:57], v1, s[70:71] offset:1024
	global_load_dwordx2 v[58:59], v1, s[70:71] offset:1536
	global_load_dwordx2 v[60:61], v1, s[72:73] offset:0
	global_load_dwordx2 v[62:63], v1, s[72:73] offset:512
	global_load_dwordx2 v[64:65], v1, s[72:73] offset:1024
	global_load_dwordx2 v[66:67], v1, s[72:73] offset:1536
	s_add_u32 s70, s70, 0x400000
	s_addc_u32 s71, s71, 0
	s_add_u32 s72, s72, 0x400000
	s_addc_u32 s73, s73, 0
	s_waitcnt vmcnt(32)
	v_lshlrev_b32_e32 v68, 16, v20
	v_and_b32_e32 v69, 0xffff0000, v20
	v_lshlrev_b32_e32 v70, 16, v21
	v_and_b32_e32 v71, 0xffff0000, v21
	v_lshlrev_b32_e32 v72, 16, v22
	v_and_b32_e32 v73, 0xffff0000, v22
	v_lshlrev_b32_e32 v74, 16, v23
	v_and_b32_e32 v75, 0xffff0000, v23
	v_lshlrev_b32_e32 v76, 16, v24
	v_and_b32_e32 v77, 0xffff0000, v24
	v_lshlrev_b32_e32 v78, 16, v25
	v_and_b32_e32 v79, 0xffff0000, v25
	v_lshlrev_b32_e32 v80, 16, v26
	v_and_b32_e32 v81, 0xffff0000, v26
	v_lshlrev_b32_e32 v82, 16, v27
	v_and_b32_e32 v83, 0xffff0000, v27
	v_mul_f32_e32 v86, v68, v68
	v_mul_f32_e32 v87, v72, v72
	v_mul_f32_e32 v88, v76, v76
	v_mul_f32_e32 v89, v80, v80
	v_fmac_f32_e32 v86, v69, v69
	v_fmac_f32_e32 v87, v73, v73
	v_fmac_f32_e32 v88, v77, v77
	v_fmac_f32_e32 v89, v81, v81
	v_fmac_f32_e32 v86, v70, v70
	v_fmac_f32_e32 v87, v74, v74
	v_fmac_f32_e32 v88, v78, v78
	v_fmac_f32_e32 v89, v82, v82
	v_fmac_f32_e32 v86, v71, v71
	v_fmac_f32_e32 v87, v75, v75
	v_fmac_f32_e32 v88, v79, v79
	v_fmac_f32_e32 v89, v83, v83
	v_add_f32_e32 v84, v86, v87
	v_add_f32_e32 v84, v84, v88
	v_add_f32_e32 v84, v84, v89
	v_lshlrev_b32_e32 v160, 16, v28
	v_and_b32_e32 v161, 0xffff0000, v28
	v_add_f32_dpp v84, v84, v84 quad_perm:[1,0,3,2] row_mask:0xf bank_mask:0xf
	v_lshlrev_b32_e32 v162, 16, v29
	v_and_b32_e32 v163, 0xffff0000, v29
	v_add_f32_dpp v84, v84, v84 quad_perm:[2,3,0,1] row_mask:0xf bank_mask:0xf
	v_lshlrev_b32_e32 v164, 16, v30
	v_and_b32_e32 v165, 0xffff0000, v30
	v_add_f32_dpp v84, v84, v84 row_half_mirror row_mask:0xf bank_mask:0xf
	v_lshlrev_b32_e32 v166, 16, v31
	v_and_b32_e32 v167, 0xffff0000, v31
	v_add_f32_dpp v84, v84, v84 row_mirror row_mask:0xf bank_mask:0xf
	v_lshlrev_b32_e32 v168, 16, v32
	v_and_b32_e32 v169, 0xffff0000, v32
	v_add_f32_dpp v84, v84, v84 row_bcast:15 row_mask:0xa bank_mask:0xf
	v_lshlrev_b32_e32 v170, 16, v33
	v_and_b32_e32 v171, 0xffff0000, v33
	v_add_f32_dpp v84, v84, v84 row_bcast:31 row_mask:0xc bank_mask:0xf
	v_lshlrev_b32_e32 v172, 16, v34
	v_and_b32_e32 v173, 0xffff0000, v34
	v_lshlrev_b32_e32 v174, 16, v35
	v_and_b32_e32 v175, 0xffff0000, v35
	s_nop 0
	v_readlane_b32 s83, v84, 63
	s_nop 2
	v_fma_f32 v84, s83, v2, v3
	v_rsq_f32_e32 v84, v84
	s_nop 0
	v_mul_f32_e32 v68, v68, v84
	v_mul_f32_e32 v69, v69, v84
	v_mul_f32_e32 v70, v70, v84
	v_mul_f32_e32 v71, v71, v84
	v_mul_f32_e32 v72, v72, v84
	v_mul_f32_e32 v73, v73, v84
	v_mul_f32_e32 v74, v74, v84
	v_mul_f32_e32 v75, v75, v84
	v_mul_f32_e32 v76, v76, v84
	v_mul_f32_e32 v77, v77, v84
	v_mul_f32_e32 v78, v78, v84
	v_mul_f32_e32 v79, v79, v84
	v_mul_f32_e32 v80, v80, v84
	v_mul_f32_e32 v81, v81, v84
	v_mul_f32_e32 v82, v82, v84
	v_mul_f32_e32 v83, v83, v84
	v_fma_f32 v68, v68, v4, v160
	v_fma_f32 v69, v69, v5, v161
	v_fma_f32 v70, v70, v6, v162
	v_fma_f32 v71, v71, v7, v163
	v_fma_f32 v72, v72, v8, v164
	v_fma_f32 v73, v73, v9, v165
	v_fma_f32 v74, v74, v10, v166
	v_fma_f32 v75, v75, v11, v167
	v_fma_f32 v76, v76, v12, v168
	v_fma_f32 v77, v77, v13, v169
	v_fma_f32 v78, v78, v14, v170
	v_fma_f32 v79, v79, v15, v171
	v_fma_f32 v80, v80, v16, v172
	v_fma_f32 v81, v81, v17, v173
	v_fma_f32 v82, v82, v18, v174
	v_fma_f32 v83, v83, v19, v175
	v_mul_f32_e32 v86, v68, v68
	v_mul_f32_e32 v87, v72, v72
	v_mul_f32_e32 v88, v76, v76
	v_mul_f32_e32 v89, v80, v80
	v_fmac_f32_e32 v86, v69, v69
	v_fmac_f32_e32 v87, v73, v73
	v_fmac_f32_e32 v88, v77, v77
	v_fmac_f32_e32 v89, v81, v81
	v_fmac_f32_e32 v86, v70, v70
	v_fmac_f32_e32 v87, v74, v74
	v_fmac_f32_e32 v88, v78, v78
	v_fmac_f32_e32 v89, v82, v82
	v_fmac_f32_e32 v86, v71, v71
	v_fmac_f32_e32 v87, v75, v75
	v_fmac_f32_e32 v88, v79, v79
	v_fmac_f32_e32 v89, v83, v83
	v_add_f32_e32 v85, v86, v87
	v_add_f32_e32 v85, v85, v88
	v_add_f32_e32 v85, v85, v89
	v_cvt_pk_bf16_f32 v90, v68, v69
	v_cvt_pk_bf16_f32 v91, v70, v71
	v_add_f32_dpp v85, v85, v85 quad_perm:[1,0,3,2] row_mask:0xf bank_mask:0xf
	v_cvt_pk_bf16_f32 v92, v72, v73
	v_cvt_pk_bf16_f32 v93, v74, v75
	v_add_f32_dpp v85, v85, v85 quad_perm:[2,3,0,1] row_mask:0xf bank_mask:0xf
	v_cvt_pk_bf16_f32 v94, v76, v77
	v_cvt_pk_bf16_f32 v95, v78, v79
	v_add_f32_dpp v85, v85, v85 row_half_mirror row_mask:0xf bank_mask:0xf
	v_cvt_pk_bf16_f32 v96, v80, v81
	v_cvt_pk_bf16_f32 v97, v82, v83
	v_add_f32_dpp v85, v85, v85 row_mirror row_mask:0xf bank_mask:0xf
	s_nop 1
	v_add_f32_dpp v85, v85, v85 row_bcast:15 row_mask:0xa bank_mask:0xf
	s_nop 1
	v_add_f32_dpp v85, v85, v85 row_bcast:31 row_mask:0xc bank_mask:0xf
	global_store_dwordx2 v1, v[90:91], s[74:75] offset:0
	global_store_dwordx2 v1, v[92:93], s[74:75] offset:512
	global_store_dwordx2 v1, v[94:95], s[74:75] offset:1024
	global_store_dwordx2 v1, v[96:97], s[74:75] offset:1536
	v_readlane_b32 s84, v85, 63
	s_add_u32 s74, s74, 0x400000
	s_addc_u32 s75, s75, 0
	s_nop 0
	v_fma_f32 v85, s84, v2, v3
	v_rsq_f32_e32 v85, v85
	s_nop 0
	v_mul_f32_e32 v68, v68, v85
	v_mul_f32_e32 v69, v69, v85
	v_mul_f32_e32 v70, v70, v85
	v_mul_f32_e32 v71, v71, v85
	v_mul_f32_e32 v72, v72, v85
	v_mul_f32_e32 v73, v73, v85
	v_mul_f32_e32 v74, v74, v85
	v_mul_f32_e32 v75, v75, v85
	v_mul_f32_e32 v76, v76, v85
	v_mul_f32_e32 v77, v77, v85
	v_mul_f32_e32 v78, v78, v85
	v_mul_f32_e32 v79, v79, v85
	v_mul_f32_e32 v80, v80, v85
	v_mul_f32_e32 v81, v81, v85
	v_mul_f32_e32 v82, v82, v85
	v_mul_f32_e32 v83, v83, v85
	v_mul_f32_e32 v68, v68, v100
	v_mul_f32_e32 v69, v69, v101
	v_mul_f32_e32 v70, v70, v102
	v_mul_f32_e32 v71, v71, v103
	v_mul_f32_e32 v72, v72, v104
	v_mul_f32_e32 v73, v73, v105
	v_mul_f32_e32 v74, v74, v106
	v_mul_f32_e32 v75, v75, v107
	v_mul_f32_e32 v76, v76, v108
	v_mul_f32_e32 v77, v77, v109
	v_mul_f32_e32 v78, v78, v110
	v_mul_f32_e32 v79, v79, v111
	v_mul_f32_e32 v80, v80, v112
	v_mul_f32_e32 v81, v81, v113
	v_mul_f32_e32 v82, v82, v114
	v_mul_f32_e32 v83, v83, v115
	v_cvt_pk_bf16_f32 v176, v68, v69
	v_cvt_pk_bf16_f32 v177, v70, v71
	v_cvt_pk_bf16_f32 v178, v72, v73
	v_cvt_pk_bf16_f32 v179, v74, v75
	v_cvt_pk_bf16_f32 v180, v76, v77
	v_cvt_pk_bf16_f32 v181, v78, v79
	v_cvt_pk_bf16_f32 v182, v80, v81
	v_cvt_pk_bf16_f32 v183, v82, v83
	global_store_dwordx2 v1, v[176:177], s[76:77] offset:0
	global_store_dwordx2 v1, v[178:179], s[76:77] offset:512
	global_store_dwordx2 v1, v[180:181], s[76:77] offset:1024
	global_store_dwordx2 v1, v[182:183], s[76:77] offset:1536
	s_add_u32 s76, s76, 0x400000
	s_addc_u32 s77, s77, 0
	global_load_dwordx2 v[20:21], v1, s[70:71] offset:0
	global_load_dwordx2 v[22:23], v1, s[70:71] offset:512
	global_load_dwordx2 v[24:25], v1, s[70:71] offset:1024
	global_load_dwordx2 v[26:27], v1, s[70:71] offset:1536
	global_load_dwordx2 v[28:29], v1, s[72:73] offset:0
	global_load_dwordx2 v[30:31], v1, s[72:73] offset:512
	global_load_dwordx2 v[32:33], v1, s[72:73] offset:1024
	global_load_dwordx2 v[34:35], v1, s[72:73] offset:1536
	s_add_u32 s70, s70, 0x400000
	s_addc_u32 s71, s71, 0
	s_add_u32 s72, s72, 0x400000
	s_addc_u32 s73, s73, 0
	s_waitcnt vmcnt(32)
	v_lshlrev_b32_e32 v68, 16, v36
	v_and_b32_e32 v69, 0xffff0000, v36
	v_lshlrev_b32_e32 v70, 16, v37
	v_and_b32_e32 v71, 0xffff0000, v37
	v_lshlrev_b32_e32 v72, 16, v38
	v_and_b32_e32 v73, 0xffff0000, v38
	v_lshlrev_b32_e32 v74, 16, v39
	v_and_b32_e32 v75, 0xffff0000, v39
	v_lshlrev_b32_e32 v76, 16, v40
	v_and_b32_e32 v77, 0xffff0000, v40
	v_lshlrev_b32_e32 v78, 16, v41
	v_and_b32_e32 v79, 0xffff0000, v41
	v_lshlrev_b32_e32 v80, 16, v42
	v_and_b32_e32 v81, 0xffff0000, v42
	v_lshlrev_b32_e32 v82, 16, v43
	v_and_b32_e32 v83, 0xffff0000, v43
	v_mul_f32_e32 v86, v68, v68
	v_mul_f32_e32 v87, v72, v72
	v_mul_f32_e32 v88, v76, v76
	v_mul_f32_e32 v89, v80, v80
	v_fmac_f32_e32 v86, v69, v69
	v_fmac_f32_e32 v87, v73, v73
	v_fmac_f32_e32 v88, v77, v77
	v_fmac_f32_e32 v89, v81, v81
	v_fmac_f32_e32 v86, v70, v70
	v_fmac_f32_e32 v87, v74, v74
	v_fmac_f32_e32 v88, v78, v78
	v_fmac_f32_e32 v89, v82, v82
	v_fmac_f32_e32 v86, v71, v71
	v_fmac_f32_e32 v87, v75, v75
	v_fmac_f32_e32 v88, v79, v79
	v_fmac_f32_e32 v89, v83, v83
	v_add_f32_e32 v84, v86, v87
	v_add_f32_e32 v84, v84, v88
	v_add_f32_e32 v84, v84, v89
	v_lshlrev_b32_e32 v160, 16, v44
	v_and_b32_e32 v161, 0xffff0000, v44
	v_add_f32_dpp v84, v84, v84 quad_perm:[1,0,3,2] row_mask:0xf bank_mask:0xf
	v_lshlrev_b32_e32 v162, 16, v45
	v_and_b32_e32 v163, 0xffff0000, v45
	v_add_f32_dpp v84, v84, v84 quad_perm:[2,3,0,1] row_mask:0xf bank_mask:0xf
	v_lshlrev_b32_e32 v164, 16, v46
	v_and_b32_e32 v165, 0xffff0000, v46
	v_add_f32_dpp v84, v84, v84 row_half_mirror row_mask:0xf bank_mask:0xf
	v_lshlrev_b32_e32 v166, 16, v47
	v_and_b32_e32 v167, 0xffff0000, v47
	v_add_f32_dpp v84, v84, v84 row_mirror row_mask:0xf bank_mask:0xf
	v_lshlrev_b32_e32 v168, 16, v48
	v_and_b32_e32 v169, 0xffff0000, v48
	v_add_f32_dpp v84, v84, v84 row_bcast:15 row_mask:0xa bank_mask:0xf
	v_lshlrev_b32_e32 v170, 16, v49
	v_and_b32_e32 v171, 0xffff0000, v49
	v_add_f32_dpp v84, v84, v84 row_bcast:31 row_mask:0xc bank_mask:0xf
	v_lshlrev_b32_e32 v172, 16, v50
	v_and_b32_e32 v173, 0xffff0000, v50
	v_lshlrev_b32_e32 v174, 16, v51
	v_and_b32_e32 v175, 0xffff0000, v51
	s_nop 0
	v_readlane_b32 s83, v84, 63
	s_nop 2
	v_fma_f32 v84, s83, v2, v3
	v_rsq_f32_e32 v84, v84
	s_nop 0
	v_mul_f32_e32 v68, v68, v84
	v_mul_f32_e32 v69, v69, v84
	v_mul_f32_e32 v70, v70, v84
	v_mul_f32_e32 v71, v71, v84
	v_mul_f32_e32 v72, v72, v84
	v_mul_f32_e32 v73, v73, v84
	v_mul_f32_e32 v74, v74, v84
	v_mul_f32_e32 v75, v75, v84
	v_mul_f32_e32 v76, v76, v84
	v_mul_f32_e32 v77, v77, v84
	v_mul_f32_e32 v78, v78, v84
	v_mul_f32_e32 v79, v79, v84
	v_mul_f32_e32 v80, v80, v84
	v_mul_f32_e32 v81, v81, v84
	v_mul_f32_e32 v82, v82, v84
	v_mul_f32_e32 v83, v83, v84
	v_fma_f32 v68, v68, v4, v160
	v_fma_f32 v69, v69, v5, v161
	v_fma_f32 v70, v70, v6, v162
	v_fma_f32 v71, v71, v7, v163
	v_fma_f32 v72, v72, v8, v164
	v_fma_f32 v73, v73, v9, v165
	v_fma_f32 v74, v74, v10, v166
	v_fma_f32 v75, v75, v11, v167
	v_fma_f32 v76, v76, v12, v168
	v_fma_f32 v77, v77, v13, v169
	v_fma_f32 v78, v78, v14, v170
	v_fma_f32 v79, v79, v15, v171
	v_fma_f32 v80, v80, v16, v172
	v_fma_f32 v81, v81, v17, v173
	v_fma_f32 v82, v82, v18, v174
	v_fma_f32 v83, v83, v19, v175
	v_mul_f32_e32 v86, v68, v68
	v_mul_f32_e32 v87, v72, v72
	v_mul_f32_e32 v88, v76, v76
	v_mul_f32_e32 v89, v80, v80
	v_fmac_f32_e32 v86, v69, v69
	v_fmac_f32_e32 v87, v73, v73
	v_fmac_f32_e32 v88, v77, v77
	v_fmac_f32_e32 v89, v81, v81
	v_fmac_f32_e32 v86, v70, v70
	v_fmac_f32_e32 v87, v74, v74
	v_fmac_f32_e32 v88, v78, v78
	v_fmac_f32_e32 v89, v82, v82
	v_fmac_f32_e32 v86, v71, v71
	v_fmac_f32_e32 v87, v75, v75
	v_fmac_f32_e32 v88, v79, v79
	v_fmac_f32_e32 v89, v83, v83
	v_add_f32_e32 v85, v86, v87
	v_add_f32_e32 v85, v85, v88
	v_add_f32_e32 v85, v85, v89
	v_cvt_pk_bf16_f32 v90, v68, v69
	v_cvt_pk_bf16_f32 v91, v70, v71
	v_add_f32_dpp v85, v85, v85 quad_perm:[1,0,3,2] row_mask:0xf bank_mask:0xf
	v_cvt_pk_bf16_f32 v92, v72, v73
	v_cvt_pk_bf16_f32 v93, v74, v75
	v_add_f32_dpp v85, v85, v85 quad_perm:[2,3,0,1] row_mask:0xf bank_mask:0xf
	v_cvt_pk_bf16_f32 v94, v76, v77
	v_cvt_pk_bf16_f32 v95, v78, v79
	v_add_f32_dpp v85, v85, v85 row_half_mirror row_mask:0xf bank_mask:0xf
	v_cvt_pk_bf16_f32 v96, v80, v81
	v_cvt_pk_bf16_f32 v97, v82, v83
	v_add_f32_dpp v85, v85, v85 row_mirror row_mask:0xf bank_mask:0xf
	s_nop 1
	v_add_f32_dpp v85, v85, v85 row_bcast:15 row_mask:0xa bank_mask:0xf
	s_nop 1
	v_add_f32_dpp v85, v85, v85 row_bcast:31 row_mask:0xc bank_mask:0xf
	global_store_dwordx2 v1, v[90:91], s[74:75] offset:0
	global_store_dwordx2 v1, v[92:93], s[74:75] offset:512
	global_store_dwordx2 v1, v[94:95], s[74:75] offset:1024
	global_store_dwordx2 v1, v[96:97], s[74:75] offset:1536
	v_readlane_b32 s84, v85, 63
	s_add_u32 s74, s74, 0x400000
	s_addc_u32 s75, s75, 0
	s_nop 0
	v_fma_f32 v85, s84, v2, v3
	v_rsq_f32_e32 v85, v85
	s_nop 0
	v_mul_f32_e32 v68, v68, v85
	v_mul_f32_e32 v69, v69, v85
	v_mul_f32_e32 v70, v70, v85
	v_mul_f32_e32 v71, v71, v85
	v_mul_f32_e32 v72, v72, v85
	v_mul_f32_e32 v73, v73, v85
	v_mul_f32_e32 v74, v74, v85
	v_mul_f32_e32 v75, v75, v85
	v_mul_f32_e32 v76, v76, v85
	v_mul_f32_e32 v77, v77, v85
	v_mul_f32_e32 v78, v78, v85
	v_mul_f32_e32 v79, v79, v85
	v_mul_f32_e32 v80, v80, v85
	v_mul_f32_e32 v81, v81, v85
	v_mul_f32_e32 v82, v82, v85
	v_mul_f32_e32 v83, v83, v85
	v_mul_f32_e32 v68, v68, v100
	v_mul_f32_e32 v69, v69, v101
	v_mul_f32_e32 v70, v70, v102
	v_mul_f32_e32 v71, v71, v103
	v_mul_f32_e32 v72, v72, v104
	v_mul_f32_e32 v73, v73, v105
	v_mul_f32_e32 v74, v74, v106
	v_mul_f32_e32 v75, v75, v107
	v_mul_f32_e32 v76, v76, v108
	v_mul_f32_e32 v77, v77, v109
	v_mul_f32_e32 v78, v78, v110
	v_mul_f32_e32 v79, v79, v111
	v_mul_f32_e32 v80, v80, v112
	v_mul_f32_e32 v81, v81, v113
	v_mul_f32_e32 v82, v82, v114
	v_mul_f32_e32 v83, v83, v115
	v_cvt_pk_bf16_f32 v176, v68, v69
	v_cvt_pk_bf16_f32 v177, v70, v71
	v_cvt_pk_bf16_f32 v178, v72, v73
	v_cvt_pk_bf16_f32 v179, v74, v75
	v_cvt_pk_bf16_f32 v180, v76, v77
	v_cvt_pk_bf16_f32 v181, v78, v79
	v_cvt_pk_bf16_f32 v182, v80, v81
	v_cvt_pk_bf16_f32 v183, v82, v83
	global_store_dwordx2 v1, v[176:177], s[76:77] offset:0
	global_store_dwordx2 v1, v[178:179], s[76:77] offset:512
	global_store_dwordx2 v1, v[180:181], s[76:77] offset:1024
	global_store_dwordx2 v1, v[182:183], s[76:77] offset:1536
	s_add_u32 s76, s76, 0x400000
	s_addc_u32 s77, s77, 0
	global_load_dwordx2 v[36:37], v1, s[70:71] offset:0
	global_load_dwordx2 v[38:39], v1, s[70:71] offset:512
	global_load_dwordx2 v[40:41], v1, s[70:71] offset:1024
	global_load_dwordx2 v[42:43], v1, s[70:71] offset:1536
	global_load_dwordx2 v[44:45], v1, s[72:73] offset:0
	global_load_dwordx2 v[46:47], v1, s[72:73] offset:512
	global_load_dwordx2 v[48:49], v1, s[72:73] offset:1024
	global_load_dwordx2 v[50:51], v1, s[72:73] offset:1536
	s_add_u32 s70, s70, 0x400000
	s_addc_u32 s71, s71, 0
	s_add_u32 s72, s72, 0x400000
	s_addc_u32 s73, s73, 0
	s_waitcnt vmcnt(32)
	v_lshlrev_b32_e32 v68, 16, v52
	v_and_b32_e32 v69, 0xffff0000, v52
	v_lshlrev_b32_e32 v70, 16, v53
	v_and_b32_e32 v71, 0xffff0000, v53
	v_lshlrev_b32_e32 v72, 16, v54
	v_and_b32_e32 v73, 0xffff0000, v54
	v_lshlrev_b32_e32 v74, 16, v55
	v_and_b32_e32 v75, 0xffff0000, v55
	v_lshlrev_b32_e32 v76, 16, v56
	v_and_b32_e32 v77, 0xffff0000, v56
	v_lshlrev_b32_e32 v78, 16, v57
	v_and_b32_e32 v79, 0xffff0000, v57
	v_lshlrev_b32_e32 v80, 16, v58
	v_and_b32_e32 v81, 0xffff0000, v58
	v_lshlrev_b32_e32 v82, 16, v59
	v_and_b32_e32 v83, 0xffff0000, v59
	v_mul_f32_e32 v86, v68, v68
	v_mul_f32_e32 v87, v72, v72
	v_mul_f32_e32 v88, v76, v76
	v_mul_f32_e32 v89, v80, v80
	v_fmac_f32_e32 v86, v69, v69
	v_fmac_f32_e32 v87, v73, v73
	v_fmac_f32_e32 v88, v77, v77
	v_fmac_f32_e32 v89, v81, v81
	v_fmac_f32_e32 v86, v70, v70
	v_fmac_f32_e32 v87, v74, v74
	v_fmac_f32_e32 v88, v78, v78
	v_fmac_f32_e32 v89, v82, v82
	v_fmac_f32_e32 v86, v71, v71
	v_fmac_f32_e32 v87, v75, v75
	v_fmac_f32_e32 v88, v79, v79
	v_fmac_f32_e32 v89, v83, v83
	v_add_f32_e32 v84, v86, v87
	v_add_f32_e32 v84, v84, v88
	v_add_f32_e32 v84, v84, v89
	v_lshlrev_b32_e32 v160, 16, v60
	v_and_b32_e32 v161, 0xffff0000, v60
	v_add_f32_dpp v84, v84, v84 quad_perm:[1,0,3,2] row_mask:0xf bank_mask:0xf
	v_lshlrev_b32_e32 v162, 16, v61
	v_and_b32_e32 v163, 0xffff0000, v61
	v_add_f32_dpp v84, v84, v84 quad_perm:[2,3,0,1] row_mask:0xf bank_mask:0xf
	v_lshlrev_b32_e32 v164, 16, v62
	v_and_b32_e32 v165, 0xffff0000, v62
	v_add_f32_dpp v84, v84, v84 row_half_mirror row_mask:0xf bank_mask:0xf
	v_lshlrev_b32_e32 v166, 16, v63
	v_and_b32_e32 v167, 0xffff0000, v63
	v_add_f32_dpp v84, v84, v84 row_mirror row_mask:0xf bank_mask:0xf
	v_lshlrev_b32_e32 v168, 16, v64
	v_and_b32_e32 v169, 0xffff0000, v64
	v_add_f32_dpp v84, v84, v84 row_bcast:15 row_mask:0xa bank_mask:0xf
	v_lshlrev_b32_e32 v170, 16, v65
	v_and_b32_e32 v171, 0xffff0000, v65
	v_add_f32_dpp v84, v84, v84 row_bcast:31 row_mask:0xc bank_mask:0xf
	v_lshlrev_b32_e32 v172, 16, v66
	v_and_b32_e32 v173, 0xffff0000, v66
	v_lshlrev_b32_e32 v174, 16, v67
	v_and_b32_e32 v175, 0xffff0000, v67
	s_nop 0
	v_readlane_b32 s83, v84, 63
	s_nop 2
	v_fma_f32 v84, s83, v2, v3
	v_rsq_f32_e32 v84, v84
	s_nop 0
	v_mul_f32_e32 v68, v68, v84
	v_mul_f32_e32 v69, v69, v84
	v_mul_f32_e32 v70, v70, v84
	v_mul_f32_e32 v71, v71, v84
	v_mul_f32_e32 v72, v72, v84
	v_mul_f32_e32 v73, v73, v84
	v_mul_f32_e32 v74, v74, v84
	v_mul_f32_e32 v75, v75, v84
	v_mul_f32_e32 v76, v76, v84
	v_mul_f32_e32 v77, v77, v84
	v_mul_f32_e32 v78, v78, v84
	v_mul_f32_e32 v79, v79, v84
	v_mul_f32_e32 v80, v80, v84
	v_mul_f32_e32 v81, v81, v84
	v_mul_f32_e32 v82, v82, v84
	v_mul_f32_e32 v83, v83, v84
	v_fma_f32 v68, v68, v4, v160
	v_fma_f32 v69, v69, v5, v161
	v_fma_f32 v70, v70, v6, v162
	v_fma_f32 v71, v71, v7, v163
	v_fma_f32 v72, v72, v8, v164
	v_fma_f32 v73, v73, v9, v165
	v_fma_f32 v74, v74, v10, v166
	v_fma_f32 v75, v75, v11, v167
	v_fma_f32 v76, v76, v12, v168
	v_fma_f32 v77, v77, v13, v169
	v_fma_f32 v78, v78, v14, v170
	v_fma_f32 v79, v79, v15, v171
	v_fma_f32 v80, v80, v16, v172
	v_fma_f32 v81, v81, v17, v173
	v_fma_f32 v82, v82, v18, v174
	v_fma_f32 v83, v83, v19, v175
	v_mul_f32_e32 v86, v68, v68
	v_mul_f32_e32 v87, v72, v72
	v_mul_f32_e32 v88, v76, v76
	v_mul_f32_e32 v89, v80, v80
	v_fmac_f32_e32 v86, v69, v69
	v_fmac_f32_e32 v87, v73, v73
	v_fmac_f32_e32 v88, v77, v77
	v_fmac_f32_e32 v89, v81, v81
	v_fmac_f32_e32 v86, v70, v70
	v_fmac_f32_e32 v87, v74, v74
	v_fmac_f32_e32 v88, v78, v78
	v_fmac_f32_e32 v89, v82, v82
	v_fmac_f32_e32 v86, v71, v71
	v_fmac_f32_e32 v87, v75, v75
	v_fmac_f32_e32 v88, v79, v79
	v_fmac_f32_e32 v89, v83, v83
	v_add_f32_e32 v85, v86, v87
	v_add_f32_e32 v85, v85, v88
	v_add_f32_e32 v85, v85, v89
	v_cvt_pk_bf16_f32 v90, v68, v69
	v_cvt_pk_bf16_f32 v91, v70, v71
	v_add_f32_dpp v85, v85, v85 quad_perm:[1,0,3,2] row_mask:0xf bank_mask:0xf
	v_cvt_pk_bf16_f32 v92, v72, v73
	v_cvt_pk_bf16_f32 v93, v74, v75
	v_add_f32_dpp v85, v85, v85 quad_perm:[2,3,0,1] row_mask:0xf bank_mask:0xf
	v_cvt_pk_bf16_f32 v94, v76, v77
	v_cvt_pk_bf16_f32 v95, v78, v79
	v_add_f32_dpp v85, v85, v85 row_half_mirror row_mask:0xf bank_mask:0xf
	v_cvt_pk_bf16_f32 v96, v80, v81
	v_cvt_pk_bf16_f32 v97, v82, v83
	v_add_f32_dpp v85, v85, v85 row_mirror row_mask:0xf bank_mask:0xf
	s_nop 1
	v_add_f32_dpp v85, v85, v85 row_bcast:15 row_mask:0xa bank_mask:0xf
	s_nop 1
	v_add_f32_dpp v85, v85, v85 row_bcast:31 row_mask:0xc bank_mask:0xf
	global_store_dwordx2 v1, v[90:91], s[74:75] offset:0
	global_store_dwordx2 v1, v[92:93], s[74:75] offset:512
	global_store_dwordx2 v1, v[94:95], s[74:75] offset:1024
	global_store_dwordx2 v1, v[96:97], s[74:75] offset:1536
	v_readlane_b32 s84, v85, 63
	s_add_u32 s74, s74, 0x400000
	s_addc_u32 s75, s75, 0
	s_nop 0
	v_fma_f32 v85, s84, v2, v3
	v_rsq_f32_e32 v85, v85
	s_nop 0
	v_mul_f32_e32 v68, v68, v85
	v_mul_f32_e32 v69, v69, v85
	v_mul_f32_e32 v70, v70, v85
	v_mul_f32_e32 v71, v71, v85
	v_mul_f32_e32 v72, v72, v85
	v_mul_f32_e32 v73, v73, v85
	v_mul_f32_e32 v74, v74, v85
	v_mul_f32_e32 v75, v75, v85
	v_mul_f32_e32 v76, v76, v85
	v_mul_f32_e32 v77, v77, v85
	v_mul_f32_e32 v78, v78, v85
	v_mul_f32_e32 v79, v79, v85
	v_mul_f32_e32 v80, v80, v85
	v_mul_f32_e32 v81, v81, v85
	v_mul_f32_e32 v82, v82, v85
	v_mul_f32_e32 v83, v83, v85
	v_mul_f32_e32 v68, v68, v100
	v_mul_f32_e32 v69, v69, v101
	v_mul_f32_e32 v70, v70, v102
	v_mul_f32_e32 v71, v71, v103
	v_mul_f32_e32 v72, v72, v104
	v_mul_f32_e32 v73, v73, v105
	v_mul_f32_e32 v74, v74, v106
	v_mul_f32_e32 v75, v75, v107
	v_mul_f32_e32 v76, v76, v108
	v_mul_f32_e32 v77, v77, v109
	v_mul_f32_e32 v78, v78, v110
	v_mul_f32_e32 v79, v79, v111
	v_mul_f32_e32 v80, v80, v112
	v_mul_f32_e32 v81, v81, v113
	v_mul_f32_e32 v82, v82, v114
	v_mul_f32_e32 v83, v83, v115
	v_cvt_pk_bf16_f32 v176, v68, v69
	v_cvt_pk_bf16_f32 v177, v70, v71
	v_cvt_pk_bf16_f32 v178, v72, v73
	v_cvt_pk_bf16_f32 v179, v74, v75
	v_cvt_pk_bf16_f32 v180, v76, v77
	v_cvt_pk_bf16_f32 v181, v78, v79
	v_cvt_pk_bf16_f32 v182, v80, v81
	v_cvt_pk_bf16_f32 v183, v82, v83
	global_store_dwordx2 v1, v[176:177], s[76:77] offset:0
	global_store_dwordx2 v1, v[178:179], s[76:77] offset:512
	global_store_dwordx2 v1, v[180:181], s[76:77] offset:1024
	global_store_dwordx2 v1, v[182:183], s[76:77] offset:1536
	s_add_u32 s76, s76, 0x400000
	s_addc_u32 s77, s77, 0
	s_cmp_eq_u32 s82, 0
	s_cbranch_scc0 .Lrows_p6_r8ok
	s_sub_u32 s70, s70, 0x400000
	s_subb_u32 s71, s71, 0
	s_sub_u32 s72, s72, 0x400000
	s_subb_u32 s73, s73, 0
.Lrows_p6_r8ok:
	global_load_dwordx2 v[52:53], v1, s[70:71] offset:0
	global_load_dwordx2 v[54:55], v1, s[70:71] offset:512
	global_load_dwordx2 v[56:57], v1, s[70:71] offset:1024
	global_load_dwordx2 v[58:59], v1, s[70:71] offset:1536
	global_load_dwordx2 v[60:61], v1, s[72:73] offset:0
	global_load_dwordx2 v[62:63], v1, s[72:73] offset:512
	global_load_dwordx2 v[64:65], v1, s[72:73] offset:1024
	global_load_dwordx2 v[66:67], v1, s[72:73] offset:1536
	s_add_u32 s70, s70, 0x400000
	s_addc_u32 s71, s71, 0
	s_add_u32 s72, s72, 0x400000
	s_addc_u32 s73, s73, 0
	s_waitcnt vmcnt(32)
	v_lshlrev_b32_e32 v68, 16, v20
	v_and_b32_e32 v69, 0xffff0000, v20
	v_lshlrev_b32_e32 v70, 16, v21
	v_and_b32_e32 v71, 0xffff0000, v21
	v_lshlrev_b32_e32 v72, 16, v22
	v_and_b32_e32 v73, 0xffff0000, v22
	v_lshlrev_b32_e32 v74, 16, v23
	v_and_b32_e32 v75, 0xffff0000, v23
	v_lshlrev_b32_e32 v76, 16, v24
	v_and_b32_e32 v77, 0xffff0000, v24
	v_lshlrev_b32_e32 v78, 16, v25
	v_and_b32_e32 v79, 0xffff0000, v25
	v_lshlrev_b32_e32 v80, 16, v26
	v_and_b32_e32 v81, 0xffff0000, v26
	v_lshlrev_b32_e32 v82, 16, v27
	v_and_b32_e32 v83, 0xffff0000, v27
	v_mul_f32_e32 v86, v68, v68
	v_mul_f32_e32 v87, v72, v72
	v_mul_f32_e32 v88, v76, v76
	v_mul_f32_e32 v89, v80, v80
	v_fmac_f32_e32 v86, v69, v69
	v_fmac_f32_e32 v87, v73, v73
	v_fmac_f32_e32 v88, v77, v77
	v_fmac_f32_e32 v89, v81, v81
	v_fmac_f32_e32 v86, v70, v70
	v_fmac_f32_e32 v87, v74, v74
	v_fmac_f32_e32 v88, v78, v78
	v_fmac_f32_e32 v89, v82, v82
	v_fmac_f32_e32 v86, v71, v71
	v_fmac_f32_e32 v87, v75, v75
	v_fmac_f32_e32 v88, v79, v79
	v_fmac_f32_e32 v89, v83, v83
	v_add_f32_e32 v84, v86, v87
	v_add_f32_e32 v84, v84, v88
	v_add_f32_e32 v84, v84, v89
	v_lshlrev_b32_e32 v160, 16, v28
	v_and_b32_e32 v161, 0xffff0000, v28
	v_add_f32_dpp v84, v84, v84 quad_perm:[1,0,3,2] row_mask:0xf bank_mask:0xf
	v_lshlrev_b32_e32 v162, 16, v29
	v_and_b32_e32 v163, 0xffff0000, v29
	v_add_f32_dpp v84, v84, v84 quad_perm:[2,3,0,1] row_mask:0xf bank_mask:0xf
	v_lshlrev_b32_e32 v164, 16, v30
	v_and_b32_e32 v165, 0xffff0000, v30
	v_add_f32_dpp v84, v84, v84 row_half_mirror row_mask:0xf bank_mask:0xf
	v_lshlrev_b32_e32 v166, 16, v31
	v_and_b32_e32 v167, 0xffff0000, v31
	v_add_f32_dpp v84, v84, v84 row_mirror row_mask:0xf bank_mask:0xf
	v_lshlrev_b32_e32 v168, 16, v32
	v_and_b32_e32 v169, 0xffff0000, v32
	v_add_f32_dpp v84, v84, v84 row_bcast:15 row_mask:0xa bank_mask:0xf
	v_lshlrev_b32_e32 v170, 16, v33
	v_and_b32_e32 v171, 0xffff0000, v33
	v_add_f32_dpp v84, v84, v84 row_bcast:31 row_mask:0xc bank_mask:0xf
	v_lshlrev_b32_e32 v172, 16, v34
	v_and_b32_e32 v173, 0xffff0000, v34
	v_lshlrev_b32_e32 v174, 16, v35
	v_and_b32_e32 v175, 0xffff0000, v35
	s_nop 0
	v_readlane_b32 s83, v84, 63
	s_nop 2
	v_fma_f32 v84, s83, v2, v3
	v_rsq_f32_e32 v84, v84
	s_nop 0
	v_mul_f32_e32 v68, v68, v84
	v_mul_f32_e32 v69, v69, v84
	v_mul_f32_e32 v70, v70, v84
	v_mul_f32_e32 v71, v71, v84
	v_mul_f32_e32 v72, v72, v84
	v_mul_f32_e32 v73, v73, v84
	v_mul_f32_e32 v74, v74, v84
	v_mul_f32_e32 v75, v75, v84
	v_mul_f32_e32 v76, v76, v84
	v_mul_f32_e32 v77, v77, v84
	v_mul_f32_e32 v78, v78, v84
	v_mul_f32_e32 v79, v79, v84
	v_mul_f32_e32 v80, v80, v84
	v_mul_f32_e32 v81, v81, v84
	v_mul_f32_e32 v82, v82, v84
	v_mul_f32_e32 v83, v83, v84
	v_fma_f32 v68, v68, v4, v160
	v_fma_f32 v69, v69, v5, v161
	v_fma_f32 v70, v70, v6, v162
	v_fma_f32 v71, v71, v7, v163
	v_fma_f32 v72, v72, v8, v164
	v_fma_f32 v73, v73, v9, v165
	v_fma_f32 v74, v74, v10, v166
	v_fma_f32 v75, v75, v11, v167
	v_fma_f32 v76, v76, v12, v168
	v_fma_f32 v77, v77, v13, v169
	v_fma_f32 v78, v78, v14, v170
	v_fma_f32 v79, v79, v15, v171
	v_fma_f32 v80, v80, v16, v172
	v_fma_f32 v81, v81, v17, v173
	v_fma_f32 v82, v82, v18, v174
	v_fma_f32 v83, v83, v19, v175
	v_mul_f32_e32 v86, v68, v68
	v_mul_f32_e32 v87, v72, v72
	v_mul_f32_e32 v88, v76, v76
	v_mul_f32_e32 v89, v80, v80
	v_fmac_f32_e32 v86, v69, v69
	v_fmac_f32_e32 v87, v73, v73
	v_fmac_f32_e32 v88, v77, v77
	v_fmac_f32_e32 v89, v81, v81
	v_fmac_f32_e32 v86, v70, v70
	v_fmac_f32_e32 v87, v74, v74
	v_fmac_f32_e32 v88, v78, v78
	v_fmac_f32_e32 v89, v82, v82
	v_fmac_f32_e32 v86, v71, v71
	v_fmac_f32_e32 v87, v75, v75
	v_fmac_f32_e32 v88, v79, v79
	v_fmac_f32_e32 v89, v83, v83
	v_add_f32_e32 v85, v86, v87
	v_add_f32_e32 v85, v85, v88
	v_add_f32_e32 v85, v85, v89
	v_cvt_pk_bf16_f32 v90, v68, v69
	v_cvt_pk_bf16_f32 v91, v70, v71
	v_add_f32_dpp v85, v85, v85 quad_perm:[1,0,3,2] row_mask:0xf bank_mask:0xf
	v_cvt_pk_bf16_f32 v92, v72, v73
	v_cvt_pk_bf16_f32 v93, v74, v75
	v_add_f32_dpp v85, v85, v85 quad_perm:[2,3,0,1] row_mask:0xf bank_mask:0xf
	v_cvt_pk_bf16_f32 v94, v76, v77
	v_cvt_pk_bf16_f32 v95, v78, v79
	v_add_f32_dpp v85, v85, v85 row_half_mirror row_mask:0xf bank_mask:0xf
	v_cvt_pk_bf16_f32 v96, v80, v81
	v_cvt_pk_bf16_f32 v97, v82, v83
	v_add_f32_dpp v85, v85, v85 row_mirror row_mask:0xf bank_mask:0xf
	s_nop 1
	v_add_f32_dpp v85, v85, v85 row_bcast:15 row_mask:0xa bank_mask:0xf
	s_nop 1
	v_add_f32_dpp v85, v85, v85 row_bcast:31 row_mask:0xc bank_mask:0xf
	global_store_dwordx2 v1, v[90:91], s[74:75] offset:0
	global_store_dwordx2 v1, v[92:93], s[74:75] offset:512
	global_store_dwordx2 v1, v[94:95], s[74:75] offset:1024
	global_store_dwordx2 v1, v[96:97], s[74:75] offset:1536
	v_readlane_b32 s84, v85, 63
	s_add_u32 s74, s74, 0x400000
	s_addc_u32 s75, s75, 0
	s_nop 0
	v_fma_f32 v85, s84, v2, v3
	v_rsq_f32_e32 v85, v85
	s_nop 0
	v_mul_f32_e32 v68, v68, v85
	v_mul_f32_e32 v69, v69, v85
	v_mul_f32_e32 v70, v70, v85
	v_mul_f32_e32 v71, v71, v85
	v_mul_f32_e32 v72, v72, v85
	v_mul_f32_e32 v73, v73, v85
	v_mul_f32_e32 v74, v74, v85
	v_mul_f32_e32 v75, v75, v85
	v_mul_f32_e32 v76, v76, v85
	v_mul_f32_e32 v77, v77, v85
	v_mul_f32_e32 v78, v78, v85
	v_mul_f32_e32 v79, v79, v85
	v_mul_f32_e32 v80, v80, v85
	v_mul_f32_e32 v81, v81, v85
	v_mul_f32_e32 v82, v82, v85
	v_mul_f32_e32 v83, v83, v85
	v_mul_f32_e32 v68, v68, v100
	v_mul_f32_e32 v69, v69, v101
	v_mul_f32_e32 v70, v70, v102
	v_mul_f32_e32 v71, v71, v103
	v_mul_f32_e32 v72, v72, v104
	v_mul_f32_e32 v73, v73, v105
	v_mul_f32_e32 v74, v74, v106
	v_mul_f32_e32 v75, v75, v107
	v_mul_f32_e32 v76, v76, v108
	v_mul_f32_e32 v77, v77, v109
	v_mul_f32_e32 v78, v78, v110
	v_mul_f32_e32 v79, v79, v111
	v_mul_f32_e32 v80, v80, v112
	v_mul_f32_e32 v81, v81, v113
	v_mul_f32_e32 v82, v82, v114
	v_mul_f32_e32 v83, v83, v115
	v_cvt_pk_bf16_f32 v176, v68, v69
	v_cvt_pk_bf16_f32 v177, v70, v71
	v_cvt_pk_bf16_f32 v178, v72, v73
	v_cvt_pk_bf16_f32 v179, v74, v75
	v_cvt_pk_bf16_f32 v180, v76, v77
	v_cvt_pk_bf16_f32 v181, v78, v79
	v_cvt_pk_bf16_f32 v182, v80, v81
	v_cvt_pk_bf16_f32 v183, v82, v83
	global_store_dwordx2 v1, v[176:177], s[76:77] offset:0
	global_store_dwordx2 v1, v[178:179], s[76:77] offset:512
	global_store_dwordx2 v1, v[180:181], s[76:77] offset:1024
	global_store_dwordx2 v1, v[182:183], s[76:77] offset:1536
	s_add_u32 s76, s76, 0x400000
	s_addc_u32 s77, s77, 0
	s_waitcnt vmcnt(24)
	v_lshlrev_b32_e32 v68, 16, v36
	v_and_b32_e32 v69, 0xffff0000, v36
	v_lshlrev_b32_e32 v70, 16, v37
	v_and_b32_e32 v71, 0xffff0000, v37
	v_lshlrev_b32_e32 v72, 16, v38
	v_and_b32_e32 v73, 0xffff0000, v38
	v_lshlrev_b32_e32 v74, 16, v39
	v_and_b32_e32 v75, 0xffff0000, v39
	v_lshlrev_b32_e32 v76, 16, v40
	v_and_b32_e32 v77, 0xffff0000, v40
	v_lshlrev_b32_e32 v78, 16, v41
	v_and_b32_e32 v79, 0xffff0000, v41
	v_lshlrev_b32_e32 v80, 16, v42
	v_and_b32_e32 v81, 0xffff0000, v42
	v_lshlrev_b32_e32 v82, 16, v43
	v_and_b32_e32 v83, 0xffff0000, v43
	v_mul_f32_e32 v86, v68, v68
	v_mul_f32_e32 v87, v72, v72
	v_mul_f32_e32 v88, v76, v76
	v_mul_f32_e32 v89, v80, v80
	v_fmac_f32_e32 v86, v69, v69
	v_fmac_f32_e32 v87, v73, v73
	v_fmac_f32_e32 v88, v77, v77
	v_fmac_f32_e32 v89, v81, v81
	v_fmac_f32_e32 v86, v70, v70
	v_fmac_f32_e32 v87, v74, v74
	v_fmac_f32_e32 v88, v78, v78
	v_fmac_f32_e32 v89, v82, v82
	v_fmac_f32_e32 v86, v71, v71
	v_fmac_f32_e32 v87, v75, v75
	v_fmac_f32_e32 v88, v79, v79
	v_fmac_f32_e32 v89, v83, v83
	v_add_f32_e32 v84, v86, v87
	v_add_f32_e32 v84, v84, v88
	v_add_f32_e32 v84, v84, v89
	v_lshlrev_b32_e32 v160, 16, v44
	v_and_b32_e32 v161, 0xffff0000, v44
	v_add_f32_dpp v84, v84, v84 quad_perm:[1,0,3,2] row_mask:0xf bank_mask:0xf
	v_lshlrev_b32_e32 v162, 16, v45
	v_and_b32_e32 v163, 0xffff0000, v45
	v_add_f32_dpp v84, v84, v84 quad_perm:[2,3,0,1] row_mask:0xf bank_mask:0xf
	v_lshlrev_b32_e32 v164, 16, v46
	v_and_b32_e32 v165, 0xffff0000, v46
	v_add_f32_dpp v84, v84, v84 row_half_mirror row_mask:0xf bank_mask:0xf
	v_lshlrev_b32_e32 v166, 16, v47
	v_and_b32_e32 v167, 0xffff0000, v47
	v_add_f32_dpp v84, v84, v84 row_mirror row_mask:0xf bank_mask:0xf
	v_lshlrev_b32_e32 v168, 16, v48
	v_and_b32_e32 v169, 0xffff0000, v48
	v_add_f32_dpp v84, v84, v84 row_bcast:15 row_mask:0xa bank_mask:0xf
	v_lshlrev_b32_e32 v170, 16, v49
	v_and_b32_e32 v171, 0xffff0000, v49
	v_add_f32_dpp v84, v84, v84 row_bcast:31 row_mask:0xc bank_mask:0xf
	v_lshlrev_b32_e32 v172, 16, v50
	v_and_b32_e32 v173, 0xffff0000, v50
	v_lshlrev_b32_e32 v174, 16, v51
	v_and_b32_e32 v175, 0xffff0000, v51
	s_nop 0
	v_readlane_b32 s83, v84, 63
	s_nop 2
	v_fma_f32 v84, s83, v2, v3
	v_rsq_f32_e32 v84, v84
	s_nop 0
	v_mul_f32_e32 v68, v68, v84
	v_mul_f32_e32 v69, v69, v84
	v_mul_f32_e32 v70, v70, v84
	v_mul_f32_e32 v71, v71, v84
	v_mul_f32_e32 v72, v72, v84
	v_mul_f32_e32 v73, v73, v84
	v_mul_f32_e32 v74, v74, v84
	v_mul_f32_e32 v75, v75, v84
	v_mul_f32_e32 v76, v76, v84
	v_mul_f32_e32 v77, v77, v84
	v_mul_f32_e32 v78, v78, v84
	v_mul_f32_e32 v79, v79, v84
	v_mul_f32_e32 v80, v80, v84
	v_mul_f32_e32 v81, v81, v84
	v_mul_f32_e32 v82, v82, v84
	v_mul_f32_e32 v83, v83, v84
	v_fma_f32 v68, v68, v4, v160
	v_fma_f32 v69, v69, v5, v161
	v_fma_f32 v70, v70, v6, v162
	v_fma_f32 v71, v71, v7, v163
	v_fma_f32 v72, v72, v8, v164
	v_fma_f32 v73, v73, v9, v165
	v_fma_f32 v74, v74, v10, v166
	v_fma_f32 v75, v75, v11, v167
	v_fma_f32 v76, v76, v12, v168
	v_fma_f32 v77, v77, v13, v169
	v_fma_f32 v78, v78, v14, v170
	v_fma_f32 v79, v79, v15, v171
	v_fma_f32 v80, v80, v16, v172
	v_fma_f32 v81, v81, v17, v173
	v_fma_f32 v82, v82, v18, v174
	v_fma_f32 v83, v83, v19, v175
	v_mul_f32_e32 v86, v68, v68
	v_mul_f32_e32 v87, v72, v72
	v_mul_f32_e32 v88, v76, v76
	v_mul_f32_e32 v89, v80, v80
	v_fmac_f32_e32 v86, v69, v69
	v_fmac_f32_e32 v87, v73, v73
	v_fmac_f32_e32 v88, v77, v77
	v_fmac_f32_e32 v89, v81, v81
	v_fmac_f32_e32 v86, v70, v70
	v_fmac_f32_e32 v87, v74, v74
	v_fmac_f32_e32 v88, v78, v78
	v_fmac_f32_e32 v89, v82, v82
	v_fmac_f32_e32 v86, v71, v71
	v_fmac_f32_e32 v87, v75, v75
	v_fmac_f32_e32 v88, v79, v79
	v_fmac_f32_e32 v89, v83, v83
	v_add_f32_e32 v85, v86, v87
	v_add_f32_e32 v85, v85, v88
	v_add_f32_e32 v85, v85, v89
	v_cvt_pk_bf16_f32 v90, v68, v69
	v_cvt_pk_bf16_f32 v91, v70, v71
	v_add_f32_dpp v85, v85, v85 quad_perm:[1,0,3,2] row_mask:0xf bank_mask:0xf
	v_cvt_pk_bf16_f32 v92, v72, v73
	v_cvt_pk_bf16_f32 v93, v74, v75
	v_add_f32_dpp v85, v85, v85 quad_perm:[2,3,0,1] row_mask:0xf bank_mask:0xf
	v_cvt_pk_bf16_f32 v94, v76, v77
	v_cvt_pk_bf16_f32 v95, v78, v79
	v_add_f32_dpp v85, v85, v85 row_half_mirror row_mask:0xf bank_mask:0xf
	v_cvt_pk_bf16_f32 v96, v80, v81
	v_cvt_pk_bf16_f32 v97, v82, v83
	v_add_f32_dpp v85, v85, v85 row_mirror row_mask:0xf bank_mask:0xf
	s_nop 1
	v_add_f32_dpp v85, v85, v85 row_bcast:15 row_mask:0xa bank_mask:0xf
	s_nop 1
	v_add_f32_dpp v85, v85, v85 row_bcast:31 row_mask:0xc bank_mask:0xf
	global_store_dwordx2 v1, v[90:91], s[74:75] offset:0
	global_store_dwordx2 v1, v[92:93], s[74:75] offset:512
	global_store_dwordx2 v1, v[94:95], s[74:75] offset:1024
	global_store_dwordx2 v1, v[96:97], s[74:75] offset:1536
	v_readlane_b32 s84, v85, 63
	s_add_u32 s74, s74, 0x400000
	s_addc_u32 s75, s75, 0
	s_nop 0
	v_fma_f32 v85, s84, v2, v3
	v_rsq_f32_e32 v85, v85
	s_nop 0
	v_mul_f32_e32 v68, v68, v85
	v_mul_f32_e32 v69, v69, v85
	v_mul_f32_e32 v70, v70, v85
	v_mul_f32_e32 v71, v71, v85
	v_mul_f32_e32 v72, v72, v85
	v_mul_f32_e32 v73, v73, v85
	v_mul_f32_e32 v74, v74, v85
	v_mul_f32_e32 v75, v75, v85
	v_mul_f32_e32 v76, v76, v85
	v_mul_f32_e32 v77, v77, v85
	v_mul_f32_e32 v78, v78, v85
	v_mul_f32_e32 v79, v79, v85
	v_mul_f32_e32 v80, v80, v85
	v_mul_f32_e32 v81, v81, v85
	v_mul_f32_e32 v82, v82, v85
	v_mul_f32_e32 v83, v83, v85
	v_mul_f32_e32 v68, v68, v100
	v_mul_f32_e32 v69, v69, v101
	v_mul_f32_e32 v70, v70, v102
	v_mul_f32_e32 v71, v71, v103
	v_mul_f32_e32 v72, v72, v104
	v_mul_f32_e32 v73, v73, v105
	v_mul_f32_e32 v74, v74, v106
	v_mul_f32_e32 v75, v75, v107
	v_mul_f32_e32 v76, v76, v108
	v_mul_f32_e32 v77, v77, v109
	v_mul_f32_e32 v78, v78, v110
	v_mul_f32_e32 v79, v79, v111
	v_mul_f32_e32 v80, v80, v112
	v_mul_f32_e32 v81, v81, v113
	v_mul_f32_e32 v82, v82, v114
	v_mul_f32_e32 v83, v83, v115
	v_cvt_pk_bf16_f32 v176, v68, v69
	v_cvt_pk_bf16_f32 v177, v70, v71
	v_cvt_pk_bf16_f32 v178, v72, v73
	v_cvt_pk_bf16_f32 v179, v74, v75
	v_cvt_pk_bf16_f32 v180, v76, v77
	v_cvt_pk_bf16_f32 v181, v78, v79
	v_cvt_pk_bf16_f32 v182, v80, v81
	v_cvt_pk_bf16_f32 v183, v82, v83
	global_store_dwordx2 v1, v[176:177], s[76:77] offset:0
	global_store_dwordx2 v1, v[178:179], s[76:77] offset:512
	global_store_dwordx2 v1, v[180:181], s[76:77] offset:1024
	global_store_dwordx2 v1, v[182:183], s[76:77] offset:1536
	s_add_u32 s76, s76, 0x400000
	s_addc_u32 s77, s77, 0
	s_cmp_eq_u32 s82, 0
	s_cbranch_scc1 .Lrows_p6_done
	s_waitcnt vmcnt(16)
	v_lshlrev_b32_e32 v68, 16, v52
	v_and_b32_e32 v69, 0xffff0000, v52
	v_lshlrev_b32_e32 v70, 16, v53
	v_and_b32_e32 v71, 0xffff0000, v53
	v_lshlrev_b32_e32 v72, 16, v54
	v_and_b32_e32 v73, 0xffff0000, v54
	v_lshlrev_b32_e32 v74, 16, v55
	v_and_b32_e32 v75, 0xffff0000, v55
	v_lshlrev_b32_e32 v76, 16, v56
	v_and_b32_e32 v77, 0xffff0000, v56
	v_lshlrev_b32_e32 v78, 16, v57
	v_and_b32_e32 v79, 0xffff0000, v57
	v_lshlrev_b32_e32 v80, 16, v58
	v_and_b32_e32 v81, 0xffff0000, v58
	v_lshlrev_b32_e32 v82, 16, v59
	v_and_b32_e32 v83, 0xffff0000, v59
	v_mul_f32_e32 v86, v68, v68
	v_mul_f32_e32 v87, v72, v72
	v_mul_f32_e32 v88, v76, v76
	v_mul_f32_e32 v89, v80, v80
	v_fmac_f32_e32 v86, v69, v69
	v_fmac_f32_e32 v87, v73, v73
	v_fmac_f32_e32 v88, v77, v77
	v_fmac_f32_e32 v89, v81, v81
	v_fmac_f32_e32 v86, v70, v70
	v_fmac_f32_e32 v87, v74, v74
	v_fmac_f32_e32 v88, v78, v78
	v_fmac_f32_e32 v89, v82, v82
	v_fmac_f32_e32 v86, v71, v71
	v_fmac_f32_e32 v87, v75, v75
	v_fmac_f32_e32 v88, v79, v79
	v_fmac_f32_e32 v89, v83, v83
	v_add_f32_e32 v84, v86, v87
	v_add_f32_e32 v84, v84, v88
	v_add_f32_e32 v84, v84, v89
	v_lshlrev_b32_e32 v160, 16, v60
	v_and_b32_e32 v161, 0xffff0000, v60
	v_add_f32_dpp v84, v84, v84 quad_perm:[1,0,3,2] row_mask:0xf bank_mask:0xf
	v_lshlrev_b32_e32 v162, 16, v61
	v_and_b32_e32 v163, 0xffff0000, v61
	v_add_f32_dpp v84, v84, v84 quad_perm:[2,3,0,1] row_mask:0xf bank_mask:0xf
	v_lshlrev_b32_e32 v164, 16, v62
	v_and_b32_e32 v165, 0xffff0000, v62
	v_add_f32_dpp v84, v84, v84 row_half_mirror row_mask:0xf bank_mask:0xf
	v_lshlrev_b32_e32 v166, 16, v63
	v_and_b32_e32 v167, 0xffff0000, v63
	v_add_f32_dpp v84, v84, v84 row_mirror row_mask:0xf bank_mask:0xf
	v_lshlrev_b32_e32 v168, 16, v64
	v_and_b32_e32 v169, 0xffff0000, v64
	v_add_f32_dpp v84, v84, v84 row_bcast:15 row_mask:0xa bank_mask:0xf
	v_lshlrev_b32_e32 v170, 16, v65
	v_and_b32_e32 v171, 0xffff0000, v65
	v_add_f32_dpp v84, v84, v84 row_bcast:31 row_mask:0xc bank_mask:0xf
	v_lshlrev_b32_e32 v172, 16, v66
	v_and_b32_e32 v173, 0xffff0000, v66
	v_lshlrev_b32_e32 v174, 16, v67
	v_and_b32_e32 v175, 0xffff0000, v67
	s_nop 0
	v_readlane_b32 s83, v84, 63
	s_nop 2
	v_fma_f32 v84, s83, v2, v3
	v_rsq_f32_e32 v84, v84
	s_nop 0
	v_mul_f32_e32 v68, v68, v84
	v_mul_f32_e32 v69, v69, v84
	v_mul_f32_e32 v70, v70, v84
	v_mul_f32_e32 v71, v71, v84
	v_mul_f32_e32 v72, v72, v84
	v_mul_f32_e32 v73, v73, v84
	v_mul_f32_e32 v74, v74, v84
	v_mul_f32_e32 v75, v75, v84
	v_mul_f32_e32 v76, v76, v84
	v_mul_f32_e32 v77, v77, v84
	v_mul_f32_e32 v78, v78, v84
	v_mul_f32_e32 v79, v79, v84
	v_mul_f32_e32 v80, v80, v84
	v_mul_f32_e32 v81, v81, v84
	v_mul_f32_e32 v82, v82, v84
	v_mul_f32_e32 v83, v83, v84
	v_fma_f32 v68, v68, v4, v160
	v_fma_f32 v69, v69, v5, v161
	v_fma_f32 v70, v70, v6, v162
	v_fma_f32 v71, v71, v7, v163
	v_fma_f32 v72, v72, v8, v164
	v_fma_f32 v73, v73, v9, v165
	v_fma_f32 v74, v74, v10, v166
	v_fma_f32 v75, v75, v11, v167
	v_fma_f32 v76, v76, v12, v168
	v_fma_f32 v77, v77, v13, v169
	v_fma_f32 v78, v78, v14, v170
	v_fma_f32 v79, v79, v15, v171
	v_fma_f32 v80, v80, v16, v172
	v_fma_f32 v81, v81, v17, v173
	v_fma_f32 v82, v82, v18, v174
	v_fma_f32 v83, v83, v19, v175
	v_mul_f32_e32 v86, v68, v68
	v_mul_f32_e32 v87, v72, v72
	v_mul_f32_e32 v88, v76, v76
	v_mul_f32_e32 v89, v80, v80
	v_fmac_f32_e32 v86, v69, v69
	v_fmac_f32_e32 v87, v73, v73
	v_fmac_f32_e32 v88, v77, v77
	v_fmac_f32_e32 v89, v81, v81
	v_fmac_f32_e32 v86, v70, v70
	v_fmac_f32_e32 v87, v74, v74
	v_fmac_f32_e32 v88, v78, v78
	v_fmac_f32_e32 v89, v82, v82
	v_fmac_f32_e32 v86, v71, v71
	v_fmac_f32_e32 v87, v75, v75
	v_fmac_f32_e32 v88, v79, v79
	v_fmac_f32_e32 v89, v83, v83
	v_add_f32_e32 v85, v86, v87
	v_add_f32_e32 v85, v85, v88
	v_add_f32_e32 v85, v85, v89
	v_cvt_pk_bf16_f32 v90, v68, v69
	v_cvt_pk_bf16_f32 v91, v70, v71
	v_add_f32_dpp v85, v85, v85 quad_perm:[1,0,3,2] row_mask:0xf bank_mask:0xf
	v_cvt_pk_bf16_f32 v92, v72, v73
	v_cvt_pk_bf16_f32 v93, v74, v75
	v_add_f32_dpp v85, v85, v85 quad_perm:[2,3,0,1] row_mask:0xf bank_mask:0xf
	v_cvt_pk_bf16_f32 v94, v76, v77
	v_cvt_pk_bf16_f32 v95, v78, v79
	v_add_f32_dpp v85, v85, v85 row_half_mirror row_mask:0xf bank_mask:0xf
	v_cvt_pk_bf16_f32 v96, v80, v81
	v_cvt_pk_bf16_f32 v97, v82, v83
	v_add_f32_dpp v85, v85, v85 row_mirror row_mask:0xf bank_mask:0xf
	s_nop 1
	v_add_f32_dpp v85, v85, v85 row_bcast:15 row_mask:0xa bank_mask:0xf
	s_nop 1
	v_add_f32_dpp v85, v85, v85 row_bcast:31 row_mask:0xc bank_mask:0xf
	global_store_dwordx2 v1, v[90:91], s[74:75] offset:0
	global_store_dwordx2 v1, v[92:93], s[74:75] offset:512
	global_store_dwordx2 v1, v[94:95], s[74:75] offset:1024
	global_store_dwordx2 v1, v[96:97], s[74:75] offset:1536
	v_readlane_b32 s84, v85, 63
	s_add_u32 s74, s74, 0x400000
	s_addc_u32 s75, s75, 0
	s_nop 0
	v_fma_f32 v85, s84, v2, v3
	v_rsq_f32_e32 v85, v85
	s_nop 0
	v_mul_f32_e32 v68, v68, v85
	v_mul_f32_e32 v69, v69, v85
	v_mul_f32_e32 v70, v70, v85
	v_mul_f32_e32 v71, v71, v85
	v_mul_f32_e32 v72, v72, v85
	v_mul_f32_e32 v73, v73, v85
	v_mul_f32_e32 v74, v74, v85
	v_mul_f32_e32 v75, v75, v85
	v_mul_f32_e32 v76, v76, v85
	v_mul_f32_e32 v77, v77, v85
	v_mul_f32_e32 v78, v78, v85
	v_mul_f32_e32 v79, v79, v85
	v_mul_f32_e32 v80, v80, v85
	v_mul_f32_e32 v81, v81, v85
	v_mul_f32_e32 v82, v82, v85
	v_mul_f32_e32 v83, v83, v85
	v_mul_f32_e32 v68, v68, v100
	v_mul_f32_e32 v69, v69, v101
	v_mul_f32_e32 v70, v70, v102
	v_mul_f32_e32 v71, v71, v103
	v_mul_f32_e32 v72, v72, v104
	v_mul_f32_e32 v73, v73, v105
	v_mul_f32_e32 v74, v74, v106
	v_mul_f32_e32 v75, v75, v107
	v_mul_f32_e32 v76, v76, v108
	v_mul_f32_e32 v77, v77, v109
	v_mul_f32_e32 v78, v78, v110
	v_mul_f32_e32 v79, v79, v111
	v_mul_f32_e32 v80, v80, v112
	v_mul_f32_e32 v81, v81, v113
	v_mul_f32_e32 v82, v82, v114
	v_mul_f32_e32 v83, v83, v115
	v_cvt_pk_bf16_f32 v176, v68, v69
	v_cvt_pk_bf16_f32 v177, v70, v71
	v_cvt_pk_bf16_f32 v178, v72, v73
	v_cvt_pk_bf16_f32 v179, v74, v75
	v_cvt_pk_bf16_f32 v180, v76, v77
	v_cvt_pk_bf16_f32 v181, v78, v79
	v_cvt_pk_bf16_f32 v182, v80, v81
	v_cvt_pk_bf16_f32 v183, v82, v83
	global_store_dwordx2 v1, v[176:177], s[76:77] offset:0
	global_store_dwordx2 v1, v[178:179], s[76:77] offset:512
	global_store_dwordx2 v1, v[180:181], s[76:77] offset:1024
	global_store_dwordx2 v1, v[182:183], s[76:77] offset:1536
	s_add_u32 s76, s76, 0x400000
	s_addc_u32 s77, s77, 0
.Lrows_p6_done:
.LBB0_601:
	s_or_b64 exec, exec, s[10:11]
	s_cmp_lt_i32 s25, 8
	s_cbranch_scc1 .LBB0_655
	s_waitcnt vmcnt(0)
	s_waitcnt lgkmcnt(0)
	s_barrier
	s_and_saveexec_b64 s[4:5], s[92:93]
	s_cbranch_execz .LBB0_654
	s_add_i32 s6, 0, 0x20000
	s_waitcnt vmcnt(3)
	v_mov_b32_e32 v0, s6
	s_waitcnt vmcnt(0) expcnt(0) lgkmcnt(0)
	ds_read_b32 v2, v0
	s_add_i32 s6, 0, 0x20004
	v_mov_b32_e32 v0, s6
	ds_read_b32 v0, v0
	s_waitcnt lgkmcnt(1)
	v_cmp_ne_u32_e32 vcc, 0, v2
	s_cbranch_vccnz .LBB0_618
	s_load_dwordx2 s[10:11], s[8:9], 0x4
	s_add_u32 s6, s48, 0x1000
	s_addc_u32 s7, s49, 0
	s_add_u32 s8, s48, 0x1100
	s_addc_u32 s9, s49, 0
	s_waitcnt lgkmcnt(0)
	s_mul_i32 s3, s10, s3
	s_add_u32 s10, s48, 0x1200
	s_mul_i32 s3, s3, s11
	s_addc_u32 s11, s49, 0
	s_add_u32 s12, s48, 0x1300
	s_addc_u32 s13, s49, 0
	s_mov_b32 s20, 1
	v_mov_b32_e32 v16, 0
	s_branch .LBB0_606

.LBB0_842:
	s_cmp_lt_i32 s24, 10
	s_cselect_b64 s[4:5], -1, 0
	s_cmp_gt_i32 s25, 9
	s_cselect_b64 s[6:7], -1, 0
	s_and_b64 s[4:5], s[4:5], s[6:7]
	s_andn2_b64 vcc, exec, s[4:5]
	s_cbranch_vccnz .LBB0_904
	s_mov_b64 exec, -1
	s_load_dword s3, s[0:1], 0x148
	s_add_u32 s6, s0, 0x148
	s_addc_u32 s7, s1, 0
	s_load_dwordx2 s[78:79], s[0:1], 0x40
	s_load_dwordx2 s[80:81], s[0:1], 0x28
	v_lshrrev_b32_e32 v0, 6, v129
	v_and_b32_e32 v1, 63, v129
	v_readfirstlane_b32 s68, v0
	v_lshlrev_b32_e32 v0, 4, v1
	v_lshlrev_b32_e32 v1, 3, v1
	v_mov_b32_e32 v2, 0x3a800000
	v_mov_b32_e32 v3, 0x358637bd
	s_lshl_b32 s69, s2, 3
	s_add_u32 s68, s68, s69
	s_waitcnt lgkmcnt(0)
	s_add_u32 s80, s80, 0x1000
	s_addc_u32 s81, s81, 0
	global_load_dwordx4 v[4:7], v0, s[78:79] offset:0
	global_load_dwordx4 v[8:11], v0, s[78:79] offset:1024
	global_load_dwordx4 v[12:15], v0, s[78:79] offset:2048
	global_load_dwordx4 v[16:19], v0, s[78:79] offset:3072
	global_load_dwordx4 v[100:103], v0, s[80:81] offset:0
	global_load_dwordx4 v[104:107], v0, s[80:81] offset:1024
	global_load_dwordx4 v[108:111], v0, s[80:81] offset:2048
	global_load_dwordx4 v[112:115], v0, s[80:81] offset:3072
	s_lshl_b32 s86, s68, 11
	s_add_u32 s70, s44, s86
	s_addc_u32 s71, s45, 0
	s_add_u32 s72, s50, s86
	s_addc_u32 s73, s51, 0
	s_mov_b64 s[74:75], s[72:73]
	s_add_u32 s76, s44, s86
	s_addc_u32 s77, s45, 0
	s_cmpk_lt_u32 s68, 0x200
	s_cselect_b32 s82, 1, 0
	global_load_dwordx2 v[20:21], v1, s[70:71] offset:0
	global_load_dwordx2 v[22:23], v1, s[70:71] offset:512
	global_load_dwordx2 v[24:25], v1, s[70:71] offset:1024
	global_load_dwordx2 v[26:27], v1, s[70:71] offset:1536
	global_load_dwordx2 v[28:29], v1, s[72:73] offset:0
	global_load_dwordx2 v[30:31], v1, s[72:73] offset:512
	global_load_dwordx2 v[32:33], v1, s[72:73] offset:1024
	global_load_dwordx2 v[34:35], v1, s[72:73] offset:1536
	s_add_u32 s70, s70, 0x400000
	s_addc_u32 s71, s71, 0
	s_add_u32 s72, s72, 0x400000
	s_addc_u32 s73, s73, 0
	global_load_dwordx2 v[36:37], v1, s[70:71] offset:0
	global_load_dwordx2 v[38:39], v1, s[70:71] offset:512
	global_load_dwordx2 v[40:41], v1, s[70:71] offset:1024
	global_load_dwordx2 v[42:43], v1, s[70:71] offset:1536
	global_load_dwordx2 v[44:45], v1, s[72:73] offset:0
	global_load_dwordx2 v[46:47], v1, s[72:73] offset:512
	global_load_dwordx2 v[48:49], v1, s[72:73] offset:1024
	global_load_dwordx2 v[50:51], v1, s[72:73] offset:1536
	s_add_u32 s70, s70, 0x400000
	s_addc_u32 s71, s71, 0
	s_add_u32 s72, s72, 0x400000
	s_addc_u32 s73, s73, 0
	global_load_dwordx2 v[52:53], v1, s[70:71] offset:0
	global_load_dwordx2 v[54:55], v1, s[70:71] offset:512
	global_load_dwordx2 v[56:57], v1, s[70:71] offset:1024
	global_load_dwordx2 v[58:59], v1, s[70:71] offset:1536
	global_load_dwordx2 v[60:61], v1, s[72:73] offset:0
	global_load_dwordx2 v[62:63], v1, s[72:73] offset:512
	global_load_dwordx2 v[64:65], v1, s[72:73] offset:1024
	global_load_dwordx2 v[66:67], v1, s[72:73] offset:1536
	s_add_u32 s70, s70, 0x400000
	s_addc_u32 s71, s71, 0
	s_add_u32 s72, s72, 0x400000
	s_addc_u32 s73, s73, 0
	s_waitcnt vmcnt(16)
	v_lshlrev_b32_e32 v68, 16, v20
	v_and_b32_e32 v69, 0xffff0000, v20
	v_lshlrev_b32_e32 v70, 16, v21
	v_and_b32_e32 v71, 0xffff0000, v21
	v_lshlrev_b32_e32 v72, 16, v22
	v_and_b32_e32 v73, 0xffff0000, v22
	v_lshlrev_b32_e32 v74, 16, v23
	v_and_b32_e32 v75, 0xffff0000, v23
	v_lshlrev_b32_e32 v76, 16, v24
	v_and_b32_e32 v77, 0xffff0000, v24
	v_lshlrev_b32_e32 v78, 16, v25
	v_and_b32_e32 v79, 0xffff0000, v25
	v_lshlrev_b32_e32 v80, 16, v26
	v_and_b32_e32 v81, 0xffff0000, v26
	v_lshlrev_b32_e32 v82, 16, v27
	v_and_b32_e32 v83, 0xffff0000, v27
	v_mul_f32_e32 v86, v68, v68
	v_mul_f32_e32 v87, v72, v72
	v_mul_f32_e32 v88, v76, v76
	v_mul_f32_e32 v89, v80, v80
	v_fmac_f32_e32 v86, v69, v69
	v_fmac_f32_e32 v87, v73, v73
	v_fmac_f32_e32 v88, v77, v77
	v_fmac_f32_e32 v89, v81, v81
	v_fmac_f32_e32 v86, v70, v70
	v_fmac_f32_e32 v87, v74, v74
	v_fmac_f32_e32 v88, v78, v78
	v_fmac_f32_e32 v89, v82, v82
	v_fmac_f32_e32 v86, v71, v71
	v_fmac_f32_e32 v87, v75, v75
	v_fmac_f32_e32 v88, v79, v79
	v_fmac_f32_e32 v89, v83, v83
	v_add_f32_e32 v84, v86, v87
	v_add_f32_e32 v84, v84, v88
	v_add_f32_e32 v84, v84, v89
	v_lshlrev_b32_e32 v160, 16, v28
	v_and_b32_e32 v161, 0xffff0000, v28
	v_add_f32_dpp v84, v84, v84 quad_perm:[1,0,3,2] row_mask:0xf bank_mask:0xf
	v_lshlrev_b32_e32 v162, 16, v29
	v_and_b32_e32 v163, 0xffff0000, v29
	v_add_f32_dpp v84, v84, v84 quad_perm:[2,3,0,1] row_mask:0xf bank_mask:0xf
	v_lshlrev_b32_e32 v164, 16, v30
	v_and_b32_e32 v165, 0xffff0000, v30
	v_add_f32_dpp v84, v84, v84 row_half_mirror row_mask:0xf bank_mask:0xf
	v_lshlrev_b32_e32 v166, 16, v31
	v_and_b32_e32 v167, 0xffff0000, v31
	v_add_f32_dpp v84, v84, v84 row_mirror row_mask:0xf bank_mask:0xf
	v_lshlrev_b32_e32 v168, 16, v32
	v_and_b32_e32 v169, 0xffff0000, v32
	v_add_f32_dpp v84, v84, v84 row_bcast:15 row_mask:0xa bank_mask:0xf
	v_lshlrev_b32_e32 v170, 16, v33
	v_and_b32_e32 v171, 0xffff0000, v33
	v_add_f32_dpp v84, v84, v84 row_bcast:31 row_mask:0xc bank_mask:0xf
	v_lshlrev_b32_e32 v172, 16, v34
	v_and_b32_e32 v173, 0xffff0000, v34
	v_lshlrev_b32_e32 v174, 16, v35
	v_and_b32_e32 v175, 0xffff0000, v35
	s_nop 0
	v_readlane_b32 s83, v84, 63
	s_nop 2
	v_fma_f32 v84, s83, v2, v3
	v_rsq_f32_e32 v84, v84
	s_nop 0
	v_mul_f32_e32 v68, v68, v84
	v_mul_f32_e32 v69, v69, v84
	v_mul_f32_e32 v70, v70, v84
	v_mul_f32_e32 v71, v71, v84
	v_mul_f32_e32 v72, v72, v84
	v_mul_f32_e32 v73, v73, v84
	v_mul_f32_e32 v74, v74, v84
	v_mul_f32_e32 v75, v75, v84
	v_mul_f32_e32 v76, v76, v84
	v_mul_f32_e32 v77, v77, v84
	v_mul_f32_e32 v78, v78, v84
	v_mul_f32_e32 v79, v79, v84
	v_mul_f32_e32 v80, v80, v84
	v_mul_f32_e32 v81, v81, v84
	v_mul_f32_e32 v82, v82, v84
	v_mul_f32_e32 v83, v83, v84
	v_fma_f32 v68, v68, v4, v160
	v_fma_f32 v69, v69, v5, v161
	v_fma_f32 v70, v70, v6, v162
	v_fma_f32 v71, v71, v7, v163
	v_fma_f32 v72, v72, v8, v164
	v_fma_f32 v73, v73, v9, v165
	v_fma_f32 v74, v74, v10, v166
	v_fma_f32 v75, v75, v11, v167
	v_fma_f32 v76, v76, v12, v168
	v_fma_f32 v77, v77, v13, v169
	v_fma_f32 v78, v78, v14, v170
	v_fma_f32 v79, v79, v15, v171
	v_fma_f32 v80, v80, v16, v172
	v_fma_f32 v81, v81, v17, v173
	v_fma_f32 v82, v82, v18, v174
	v_fma_f32 v83, v83, v19, v175
	v_mul_f32_e32 v86, v68, v68
	v_mul_f32_e32 v87, v72, v72
	v_mul_f32_e32 v88, v76, v76
	v_mul_f32_e32 v89, v80, v80
	v_fmac_f32_e32 v86, v69, v69
	v_fmac_f32_e32 v87, v73, v73
	v_fmac_f32_e32 v88, v77, v77
	v_fmac_f32_e32 v89, v81, v81
	v_fmac_f32_e32 v86, v70, v70
	v_fmac_f32_e32 v87, v74, v74
	v_fmac_f32_e32 v88, v78, v78
	v_fmac_f32_e32 v89, v82, v82
	v_fmac_f32_e32 v86, v71, v71
	v_fmac_f32_e32 v87, v75, v75
	v_fmac_f32_e32 v88, v79, v79
	v_fmac_f32_e32 v89, v83, v83
	v_add_f32_e32 v85, v86, v87
	v_add_f32_e32 v85, v85, v88
	v_add_f32_e32 v85, v85, v89
	v_cvt_pk_bf16_f32 v90, v68, v69
	v_cvt_pk_bf16_f32 v91, v70, v71
	v_add_f32_dpp v85, v85, v85 quad_perm:[1,0,3,2] row_mask:0xf bank_mask:0xf
	v_cvt_pk_bf16_f32 v92, v72, v73
	v_cvt_pk_bf16_f32 v93, v74, v75
	v_add_f32_dpp v85, v85, v85 quad_perm:[2,3,0,1] row_mask:0xf bank_mask:0xf
	v_cvt_pk_bf16_f32 v94, v76, v77
	v_cvt_pk_bf16_f32 v95, v78, v79
	v_add_f32_dpp v85, v85, v85 row_half_mirror row_mask:0xf bank_mask:0xf
	v_cvt_pk_bf16_f32 v96, v80, v81
	v_cvt_pk_bf16_f32 v97, v82, v83
	v_add_f32_dpp v85, v85, v85 row_mirror row_mask:0xf bank_mask:0xf
	s_nop 1
	v_add_f32_dpp v85, v85, v85 row_bcast:15 row_mask:0xa bank_mask:0xf
	s_nop 1
	v_add_f32_dpp v85, v85, v85 row_bcast:31 row_mask:0xc bank_mask:0xf
	global_store_dwordx2 v1, v[90:91], s[74:75] offset:0
	global_store_dwordx2 v1, v[92:93], s[74:75] offset:512
	global_store_dwordx2 v1, v[94:95], s[74:75] offset:1024
	global_store_dwordx2 v1, v[96:97], s[74:75] offset:1536
	v_readlane_b32 s84, v85, 63
	s_add_u32 s74, s74, 0x400000
	s_addc_u32 s75, s75, 0
	s_nop 0
	v_fma_f32 v85, s84, v2, v3
	v_rsq_f32_e32 v85, v85
	s_nop 0
	v_mul_f32_e32 v68, v68, v85
	v_mul_f32_e32 v69, v69, v85
	v_mul_f32_e32 v70, v70, v85
	v_mul_f32_e32 v71, v71, v85
	v_mul_f32_e32 v72, v72, v85
	v_mul_f32_e32 v73, v73, v85
	v_mul_f32_e32 v74, v74, v85
	v_mul_f32_e32 v75, v75, v85
	v_mul_f32_e32 v76, v76, v85
	v_mul_f32_e32 v77, v77, v85
	v_mul_f32_e32 v78, v78, v85
	v_mul_f32_e32 v79, v79, v85
	v_mul_f32_e32 v80, v80, v85
	v_mul_f32_e32 v81, v81, v85
	v_mul_f32_e32 v82, v82, v85
	v_mul_f32_e32 v83, v83, v85
	v_mul_f32_e32 v68, v68, v100
	v_mul_f32_e32 v69, v69, v101
	v_mul_f32_e32 v70, v70, v102
	v_mul_f32_e32 v71, v71, v103
	v_mul_f32_e32 v72, v72, v104
	v_mul_f32_e32 v73, v73, v105
	v_mul_f32_e32 v74, v74, v106
	v_mul_f32_e32 v75, v75, v107
	v_mul_f32_e32 v76, v76, v108
	v_mul_f32_e32 v77, v77, v109
	v_mul_f32_e32 v78, v78, v110
	v_mul_f32_e32 v79, v79, v111
	v_mul_f32_e32 v80, v80, v112
	v_mul_f32_e32 v81, v81, v113
	v_mul_f32_e32 v82, v82, v114
	v_mul_f32_e32 v83, v83, v115
	v_cvt_pk_bf16_f32 v176, v68, v69
	v_cvt_pk_bf16_f32 v177, v70, v71
	v_cvt_pk_bf16_f32 v178, v72, v73
	v_cvt_pk_bf16_f32 v179, v74, v75
	v_cvt_pk_bf16_f32 v180, v76, v77
	v_cvt_pk_bf16_f32 v181, v78, v79
	v_cvt_pk_bf16_f32 v182, v80, v81
	v_cvt_pk_bf16_f32 v183, v82, v83
	global_store_dwordx2 v1, v[176:177], s[76:77] offset:0
	global_store_dwordx2 v1, v[178:179], s[76:77] offset:512
	global_store_dwordx2 v1, v[180:181], s[76:77] offset:1024
	global_store_dwordx2 v1, v[182:183], s[76:77] offset:1536
	s_add_u32 s76, s76, 0x400000
	s_addc_u32 s77, s77, 0
	global_load_dwordx2 v[20:21], v1, s[70:71] offset:0
	global_load_dwordx2 v[22:23], v1, s[70:71] offset:512
	global_load_dwordx2 v[24:25], v1, s[70:71] offset:1024
	global_load_dwordx2 v[26:27], v1, s[70:71] offset:1536
	global_load_dwordx2 v[28:29], v1, s[72:73] offset:0
	global_load_dwordx2 v[30:31], v1, s[72:73] offset:512
	global_load_dwordx2 v[32:33], v1, s[72:73] offset:1024
	global_load_dwordx2 v[34:35], v1, s[72:73] offset:1536
	s_add_u32 s70, s70, 0x400000
	s_addc_u32 s71, s71, 0
	s_add_u32 s72, s72, 0x400000
	s_addc_u32 s73, s73, 0
	s_waitcnt vmcnt(24)
	v_lshlrev_b32_e32 v68, 16, v36
	v_and_b32_e32 v69, 0xffff0000, v36
	v_lshlrev_b32_e32 v70, 16, v37
	v_and_b32_e32 v71, 0xffff0000, v37
	v_lshlrev_b32_e32 v72, 16, v38
	v_and_b32_e32 v73, 0xffff0000, v38
	v_lshlrev_b32_e32 v74, 16, v39
	v_and_b32_e32 v75, 0xffff0000, v39
	v_lshlrev_b32_e32 v76, 16, v40
	v_and_b32_e32 v77, 0xffff0000, v40
	v_lshlrev_b32_e32 v78, 16, v41
	v_and_b32_e32 v79, 0xffff0000, v41
	v_lshlrev_b32_e32 v80, 16, v42
	v_and_b32_e32 v81, 0xffff0000, v42
	v_lshlrev_b32_e32 v82, 16, v43
	v_and_b32_e32 v83, 0xffff0000, v43
	v_mul_f32_e32 v86, v68, v68
	v_mul_f32_e32 v87, v72, v72
	v_mul_f32_e32 v88, v76, v76
	v_mul_f32_e32 v89, v80, v80
	v_fmac_f32_e32 v86, v69, v69
	v_fmac_f32_e32 v87, v73, v73
	v_fmac_f32_e32 v88, v77, v77
	v_fmac_f32_e32 v89, v81, v81
	v_fmac_f32_e32 v86, v70, v70
	v_fmac_f32_e32 v87, v74, v74
	v_fmac_f32_e32 v88, v78, v78
	v_fmac_f32_e32 v89, v82, v82
	v_fmac_f32_e32 v86, v71, v71
	v_fmac_f32_e32 v87, v75, v75
	v_fmac_f32_e32 v88, v79, v79
	v_fmac_f32_e32 v89, v83, v83
	v_add_f32_e32 v84, v86, v87
	v_add_f32_e32 v84, v84, v88
	v_add_f32_e32 v84, v84, v89
	v_lshlrev_b32_e32 v160, 16, v44
	v_and_b32_e32 v161, 0xffff0000, v44
	v_add_f32_dpp v84, v84, v84 quad_perm:[1,0,3,2] row_mask:0xf bank_mask:0xf
	v_lshlrev_b32_e32 v162, 16, v45
	v_and_b32_e32 v163, 0xffff0000, v45
	v_add_f32_dpp v84, v84, v84 quad_perm:[2,3,0,1] row_mask:0xf bank_mask:0xf
	v_lshlrev_b32_e32 v164, 16, v46
	v_and_b32_e32 v165, 0xffff0000, v46
	v_add_f32_dpp v84, v84, v84 row_half_mirror row_mask:0xf bank_mask:0xf
	v_lshlrev_b32_e32 v166, 16, v47
	v_and_b32_e32 v167, 0xffff0000, v47
	v_add_f32_dpp v84, v84, v84 row_mirror row_mask:0xf bank_mask:0xf
	v_lshlrev_b32_e32 v168, 16, v48
	v_and_b32_e32 v169, 0xffff0000, v48
	v_add_f32_dpp v84, v84, v84 row_bcast:15 row_mask:0xa bank_mask:0xf
	v_lshlrev_b32_e32 v170, 16, v49
	v_and_b32_e32 v171, 0xffff0000, v49
	v_add_f32_dpp v84, v84, v84 row_bcast:31 row_mask:0xc bank_mask:0xf
	v_lshlrev_b32_e32 v172, 16, v50
	v_and_b32_e32 v173, 0xffff0000, v50
	v_lshlrev_b32_e32 v174, 16, v51
	v_and_b32_e32 v175, 0xffff0000, v51
	s_nop 0
	v_readlane_b32 s83, v84, 63
	s_nop 2
	v_fma_f32 v84, s83, v2, v3
	v_rsq_f32_e32 v84, v84
	s_nop 0
	v_mul_f32_e32 v68, v68, v84
	v_mul_f32_e32 v69, v69, v84
	v_mul_f32_e32 v70, v70, v84
	v_mul_f32_e32 v71, v71, v84
	v_mul_f32_e32 v72, v72, v84
	v_mul_f32_e32 v73, v73, v84
	v_mul_f32_e32 v74, v74, v84
	v_mul_f32_e32 v75, v75, v84
	v_mul_f32_e32 v76, v76, v84
	v_mul_f32_e32 v77, v77, v84
	v_mul_f32_e32 v78, v78, v84
	v_mul_f32_e32 v79, v79, v84
	v_mul_f32_e32 v80, v80, v84
	v_mul_f32_e32 v81, v81, v84
	v_mul_f32_e32 v82, v82, v84
	v_mul_f32_e32 v83, v83, v84
	v_fma_f32 v68, v68, v4, v160
	v_fma_f32 v69, v69, v5, v161
	v_fma_f32 v70, v70, v6, v162
	v_fma_f32 v71, v71, v7, v163
	v_fma_f32 v72, v72, v8, v164
	v_fma_f32 v73, v73, v9, v165
	v_fma_f32 v74, v74, v10, v166
	v_fma_f32 v75, v75, v11, v167
	v_fma_f32 v76, v76, v12, v168
	v_fma_f32 v77, v77, v13, v169
	v_fma_f32 v78, v78, v14, v170
	v_fma_f32 v79, v79, v15, v171
	v_fma_f32 v80, v80, v16, v172
	v_fma_f32 v81, v81, v17, v173
	v_fma_f32 v82, v82, v18, v174
	v_fma_f32 v83, v83, v19, v175
	v_mul_f32_e32 v86, v68, v68
	v_mul_f32_e32 v87, v72, v72
	v_mul_f32_e32 v88, v76, v76
	v_mul_f32_e32 v89, v80, v80
	v_fmac_f32_e32 v86, v69, v69
	v_fmac_f32_e32 v87, v73, v73
	v_fmac_f32_e32 v88, v77, v77
	v_fmac_f32_e32 v89, v81, v81
	v_fmac_f32_e32 v86, v70, v70
	v_fmac_f32_e32 v87, v74, v74
	v_fmac_f32_e32 v88, v78, v78
	v_fmac_f32_e32 v89, v82, v82
	v_fmac_f32_e32 v86, v71, v71
	v_fmac_f32_e32 v87, v75, v75
	v_fmac_f32_e32 v88, v79, v79
	v_fmac_f32_e32 v89, v83, v83
	v_add_f32_e32 v85, v86, v87
	v_add_f32_e32 v85, v85, v88
	v_add_f32_e32 v85, v85, v89
	v_cvt_pk_bf16_f32 v90, v68, v69
	v_cvt_pk_bf16_f32 v91, v70, v71
	v_add_f32_dpp v85, v85, v85 quad_perm:[1,0,3,2] row_mask:0xf bank_mask:0xf
	v_cvt_pk_bf16_f32 v92, v72, v73
	v_cvt_pk_bf16_f32 v93, v74, v75
	v_add_f32_dpp v85, v85, v85 quad_perm:[2,3,0,1] row_mask:0xf bank_mask:0xf
	v_cvt_pk_bf16_f32 v94, v76, v77
	v_cvt_pk_bf16_f32 v95, v78, v79
	v_add_f32_dpp v85, v85, v85 row_half_mirror row_mask:0xf bank_mask:0xf
	v_cvt_pk_bf16_f32 v96, v80, v81
	v_cvt_pk_bf16_f32 v97, v82, v83
	v_add_f32_dpp v85, v85, v85 row_mirror row_mask:0xf bank_mask:0xf
	s_nop 1
	v_add_f32_dpp v85, v85, v85 row_bcast:15 row_mask:0xa bank_mask:0xf
	s_nop 1
	v_add_f32_dpp v85, v85, v85 row_bcast:31 row_mask:0xc bank_mask:0xf
	global_store_dwordx2 v1, v[90:91], s[74:75] offset:0
	global_store_dwordx2 v1, v[92:93], s[74:75] offset:512
	global_store_dwordx2 v1, v[94:95], s[74:75] offset:1024
	global_store_dwordx2 v1, v[96:97], s[74:75] offset:1536
	v_readlane_b32 s84, v85, 63
	s_add_u32 s74, s74, 0x400000
	s_addc_u32 s75, s75, 0
	s_nop 0
	v_fma_f32 v85, s84, v2, v3
	v_rsq_f32_e32 v85, v85
	s_nop 0
	v_mul_f32_e32 v68, v68, v85
	v_mul_f32_e32 v69, v69, v85
	v_mul_f32_e32 v70, v70, v85
	v_mul_f32_e32 v71, v71, v85
	v_mul_f32_e32 v72, v72, v85
	v_mul_f32_e32 v73, v73, v85
	v_mul_f32_e32 v74, v74, v85
	v_mul_f32_e32 v75, v75, v85
	v_mul_f32_e32 v76, v76, v85
	v_mul_f32_e32 v77, v77, v85
	v_mul_f32_e32 v78, v78, v85
	v_mul_f32_e32 v79, v79, v85
	v_mul_f32_e32 v80, v80, v85
	v_mul_f32_e32 v81, v81, v85
	v_mul_f32_e32 v82, v82, v85
	v_mul_f32_e32 v83, v83, v85
	v_mul_f32_e32 v68, v68, v100
	v_mul_f32_e32 v69, v69, v101
	v_mul_f32_e32 v70, v70, v102
	v_mul_f32_e32 v71, v71, v103
	v_mul_f32_e32 v72, v72, v104
	v_mul_f32_e32 v73, v73, v105
	v_mul_f32_e32 v74, v74, v106
	v_mul_f32_e32 v75, v75, v107
	v_mul_f32_e32 v76, v76, v108
	v_mul_f32_e32 v77, v77, v109
	v_mul_f32_e32 v78, v78, v110
	v_mul_f32_e32 v79, v79, v111
	v_mul_f32_e32 v80, v80, v112
	v_mul_f32_e32 v81, v81, v113
	v_mul_f32_e32 v82, v82, v114
	v_mul_f32_e32 v83, v83, v115
	v_cvt_pk_bf16_f32 v176, v68, v69
	v_cvt_pk_bf16_f32 v177, v70, v71
	v_cvt_pk_bf16_f32 v178, v72, v73
	v_cvt_pk_bf16_f32 v179, v74, v75
	v_cvt_pk_bf16_f32 v180, v76, v77
	v_cvt_pk_bf16_f32 v181, v78, v79
	v_cvt_pk_bf16_f32 v182, v80, v81
	v_cvt_pk_bf16_f32 v183, v82, v83
	global_store_dwordx2 v1, v[176:177], s[76:77] offset:0
	global_store_dwordx2 v1, v[178:179], s[76:77] offset:512
	global_store_dwordx2 v1, v[180:181], s[76:77] offset:1024
	global_store_dwordx2 v1, v[182:183], s[76:77] offset:1536
	s_add_u32 s76, s76, 0x400000
	s_addc_u32 s77, s77, 0
	global_load_dwordx2 v[36:37], v1, s[70:71] offset:0
	global_load_dwordx2 v[38:39], v1, s[70:71] offset:512
	global_load_dwordx2 v[40:41], v1, s[70:71] offset:1024
	global_load_dwordx2 v[42:43], v1, s[70:71] offset:1536
	global_load_dwordx2 v[44:45], v1, s[72:73] offset:0
	global_load_dwordx2 v[46:47], v1, s[72:73] offset:512
	global_load_dwordx2 v[48:49], v1, s[72:73] offset:1024
	global_load_dwordx2 v[50:51], v1, s[72:73] offset:1536
	s_add_u32 s70, s70, 0x400000
	s_addc_u32 s71, s71, 0
	s_add_u32 s72, s72, 0x400000
	s_addc_u32 s73, s73, 0
	s_waitcnt vmcnt(32)
	v_lshlrev_b32_e32 v68, 16, v52
	v_and_b32_e32 v69, 0xffff0000, v52
	v_lshlrev_b32_e32 v70, 16, v53
	v_and_b32_e32 v71, 0xffff0000, v53
	v_lshlrev_b32_e32 v72, 16, v54
	v_and_b32_e32 v73, 0xffff0000, v54
	v_lshlrev_b32_e32 v74, 16, v55
	v_and_b32_e32 v75, 0xffff0000, v55
	v_lshlrev_b32_e32 v76, 16, v56
	v_and_b32_e32 v77, 0xffff0000, v56
	v_lshlrev_b32_e32 v78, 16, v57
	v_and_b32_e32 v79, 0xffff0000, v57
	v_lshlrev_b32_e32 v80, 16, v58
	v_and_b32_e32 v81, 0xffff0000, v58
	v_lshlrev_b32_e32 v82, 16, v59
	v_and_b32_e32 v83, 0xffff0000, v59
	v_mul_f32_e32 v86, v68, v68
	v_mul_f32_e32 v87, v72, v72
	v_mul_f32_e32 v88, v76, v76
	v_mul_f32_e32 v89, v80, v80
	v_fmac_f32_e32 v86, v69, v69
	v_fmac_f32_e32 v87, v73, v73
	v_fmac_f32_e32 v88, v77, v77
	v_fmac_f32_e32 v89, v81, v81
	v_fmac_f32_e32 v86, v70, v70
	v_fmac_f32_e32 v87, v74, v74
	v_fmac_f32_e32 v88, v78, v78
	v_fmac_f32_e32 v89, v82, v82
	v_fmac_f32_e32 v86, v71, v71
	v_fmac_f32_e32 v87, v75, v75
	v_fmac_f32_e32 v88, v79, v79
	v_fmac_f32_e32 v89, v83, v83
	v_add_f32_e32 v84, v86, v87
	v_add_f32_e32 v84, v84, v88
	v_add_f32_e32 v84, v84, v89
	v_lshlrev_b32_e32 v160, 16, v60
	v_and_b32_e32 v161, 0xffff0000, v60
	v_add_f32_dpp v84, v84, v84 quad_perm:[1,0,3,2] row_mask:0xf bank_mask:0xf
	v_lshlrev_b32_e32 v162, 16, v61
	v_and_b32_e32 v163, 0xffff0000, v61
	v_add_f32_dpp v84, v84, v84 quad_perm:[2,3,0,1] row_mask:0xf bank_mask:0xf
	v_lshlrev_b32_e32 v164, 16, v62
	v_and_b32_e32 v165, 0xffff0000, v62
	v_add_f32_dpp v84, v84, v84 row_half_mirror row_mask:0xf bank_mask:0xf
	v_lshlrev_b32_e32 v166, 16, v63
	v_and_b32_e32 v167, 0xffff0000, v63
	v_add_f32_dpp v84, v84, v84 row_mirror row_mask:0xf bank_mask:0xf
	v_lshlrev_b32_e32 v168, 16, v64
	v_and_b32_e32 v169, 0xffff0000, v64
	v_add_f32_dpp v84, v84, v84 row_bcast:15 row_mask:0xa bank_mask:0xf
	v_lshlrev_b32_e32 v170, 16, v65
	v_and_b32_e32 v171, 0xffff0000, v65
	v_add_f32_dpp v84, v84, v84 row_bcast:31 row_mask:0xc bank_mask:0xf
	v_lshlrev_b32_e32 v172, 16, v66
	v_and_b32_e32 v173, 0xffff0000, v66
	v_lshlrev_b32_e32 v174, 16, v67
	v_and_b32_e32 v175, 0xffff0000, v67
	s_nop 0
	v_readlane_b32 s83, v84, 63
	s_nop 2
	v_fma_f32 v84, s83, v2, v3
	v_rsq_f32_e32 v84, v84
	s_nop 0
	v_mul_f32_e32 v68, v68, v84
	v_mul_f32_e32 v69, v69, v84
	v_mul_f32_e32 v70, v70, v84
	v_mul_f32_e32 v71, v71, v84
	v_mul_f32_e32 v72, v72, v84
	v_mul_f32_e32 v73, v73, v84
	v_mul_f32_e32 v74, v74, v84
	v_mul_f32_e32 v75, v75, v84
	v_mul_f32_e32 v76, v76, v84
	v_mul_f32_e32 v77, v77, v84
	v_mul_f32_e32 v78, v78, v84
	v_mul_f32_e32 v79, v79, v84
	v_mul_f32_e32 v80, v80, v84
	v_mul_f32_e32 v81, v81, v84
	v_mul_f32_e32 v82, v82, v84
	v_mul_f32_e32 v83, v83, v84
	v_fma_f32 v68, v68, v4, v160
	v_fma_f32 v69, v69, v5, v161
	v_fma_f32 v70, v70, v6, v162
	v_fma_f32 v71, v71, v7, v163
	v_fma_f32 v72, v72, v8, v164
	v_fma_f32 v73, v73, v9, v165
	v_fma_f32 v74, v74, v10, v166
	v_fma_f32 v75, v75, v11, v167
	v_fma_f32 v76, v76, v12, v168
	v_fma_f32 v77, v77, v13, v169
	v_fma_f32 v78, v78, v14, v170
	v_fma_f32 v79, v79, v15, v171
	v_fma_f32 v80, v80, v16, v172
	v_fma_f32 v81, v81, v17, v173
	v_fma_f32 v82, v82, v18, v174
	v_fma_f32 v83, v83, v19, v175
	v_mul_f32_e32 v86, v68, v68
	v_mul_f32_e32 v87, v72, v72
	v_mul_f32_e32 v88, v76, v76
	v_mul_f32_e32 v89, v80, v80
	v_fmac_f32_e32 v86, v69, v69
	v_fmac_f32_e32 v87, v73, v73
	v_fmac_f32_e32 v88, v77, v77
	v_fmac_f32_e32 v89, v81, v81
	v_fmac_f32_e32 v86, v70, v70
	v_fmac_f32_e32 v87, v74, v74
	v_fmac_f32_e32 v88, v78, v78
	v_fmac_f32_e32 v89, v82, v82
	v_fmac_f32_e32 v86, v71, v71
	v_fmac_f32_e32 v87, v75, v75
	v_fmac_f32_e32 v88, v79, v79
	v_fmac_f32_e32 v89, v83, v83
	v_add_f32_e32 v85, v86, v87
	v_add_f32_e32 v85, v85, v88
	v_add_f32_e32 v85, v85, v89
	v_cvt_pk_bf16_f32 v90, v68, v69
	v_cvt_pk_bf16_f32 v91, v70, v71
	v_add_f32_dpp v85, v85, v85 quad_perm:[1,0,3,2] row_mask:0xf bank_mask:0xf
	v_cvt_pk_bf16_f32 v92, v72, v73
	v_cvt_pk_bf16_f32 v93, v74, v75
	v_add_f32_dpp v85, v85, v85 quad_perm:[2,3,0,1] row_mask:0xf bank_mask:0xf
	v_cvt_pk_bf16_f32 v94, v76, v77
	v_cvt_pk_bf16_f32 v95, v78, v79
	v_add_f32_dpp v85, v85, v85 row_half_mirror row_mask:0xf bank_mask:0xf
	v_cvt_pk_bf16_f32 v96, v80, v81
	v_cvt_pk_bf16_f32 v97, v82, v83
	v_add_f32_dpp v85, v85, v85 row_mirror row_mask:0xf bank_mask:0xf
	s_nop 1
	v_add_f32_dpp v85, v85, v85 row_bcast:15 row_mask:0xa bank_mask:0xf
	s_nop 1
	v_add_f32_dpp v85, v85, v85 row_bcast:31 row_mask:0xc bank_mask:0xf
	global_store_dwordx2 v1, v[90:91], s[74:75] offset:0
	global_store_dwordx2 v1, v[92:93], s[74:75] offset:512
	global_store_dwordx2 v1, v[94:95], s[74:75] offset:1024
	global_store_dwordx2 v1, v[96:97], s[74:75] offset:1536
	v_readlane_b32 s84, v85, 63
	s_add_u32 s74, s74, 0x400000
	s_addc_u32 s75, s75, 0
	s_nop 0
	v_fma_f32 v85, s84, v2, v3
	v_rsq_f32_e32 v85, v85
	s_nop 0
	v_mul_f32_e32 v68, v68, v85
	v_mul_f32_e32 v69, v69, v85
	v_mul_f32_e32 v70, v70, v85
	v_mul_f32_e32 v71, v71, v85
	v_mul_f32_e32 v72, v72, v85
	v_mul_f32_e32 v73, v73, v85
	v_mul_f32_e32 v74, v74, v85
	v_mul_f32_e32 v75, v75, v85
	v_mul_f32_e32 v76, v76, v85
	v_mul_f32_e32 v77, v77, v85
	v_mul_f32_e32 v78, v78, v85
	v_mul_f32_e32 v79, v79, v85
	v_mul_f32_e32 v80, v80, v85
	v_mul_f32_e32 v81, v81, v85
	v_mul_f32_e32 v82, v82, v85
	v_mul_f32_e32 v83, v83, v85
	v_mul_f32_e32 v68, v68, v100
	v_mul_f32_e32 v69, v69, v101
	v_mul_f32_e32 v70, v70, v102
	v_mul_f32_e32 v71, v71, v103
	v_mul_f32_e32 v72, v72, v104
	v_mul_f32_e32 v73, v73, v105
	v_mul_f32_e32 v74, v74, v106
	v_mul_f32_e32 v75, v75, v107
	v_mul_f32_e32 v76, v76, v108
	v_mul_f32_e32 v77, v77, v109
	v_mul_f32_e32 v78, v78, v110
	v_mul_f32_e32 v79, v79, v111
	v_mul_f32_e32 v80, v80, v112
	v_mul_f32_e32 v81, v81, v113
	v_mul_f32_e32 v82, v82, v114
	v_mul_f32_e32 v83, v83, v115
	v_cvt_pk_bf16_f32 v176, v68, v69
	v_cvt_pk_bf16_f32 v177, v70, v71
	v_cvt_pk_bf16_f32 v178, v72, v73
	v_cvt_pk_bf16_f32 v179, v74, v75
	v_cvt_pk_bf16_f32 v180, v76, v77
	v_cvt_pk_bf16_f32 v181, v78, v79
	v_cvt_pk_bf16_f32 v182, v80, v81
	v_cvt_pk_bf16_f32 v183, v82, v83
	global_store_dwordx2 v1, v[176:177], s[76:77] offset:0
	global_store_dwordx2 v1, v[178:179], s[76:77] offset:512
	global_store_dwordx2 v1, v[180:181], s[76:77] offset:1024
	global_store_dwordx2 v1, v[182:183], s[76:77] offset:1536
	s_add_u32 s76, s76, 0x400000
	s_addc_u32 s77, s77, 0
	global_load_dwordx2 v[52:53], v1, s[70:71] offset:0
	global_load_dwordx2 v[54:55], v1, s[70:71] offset:512
	global_load_dwordx2 v[56:57], v1, s[70:71] offset:1024
	global_load_dwordx2 v[58:59], v1, s[70:71] offset:1536
	global_load_dwordx2 v[60:61], v1, s[72:73] offset:0
	global_load_dwordx2 v[62:63], v1, s[72:73] offset:512
	global_load_dwordx2 v[64:65], v1, s[72:73] offset:1024
	global_load_dwordx2 v[66:67], v1, s[72:73] offset:1536
	s_add_u32 s70, s70, 0x400000
	s_addc_u32 s71, s71, 0
	s_add_u32 s72, s72, 0x400000
	s_addc_u32 s73, s73, 0
	s_waitcnt vmcnt(32)
	v_lshlrev_b32_e32 v68, 16, v20
	v_and_b32_e32 v69, 0xffff0000, v20
	v_lshlrev_b32_e32 v70, 16, v21
	v_and_b32_e32 v71, 0xffff0000, v21
	v_lshlrev_b32_e32 v72, 16, v22
	v_and_b32_e32 v73, 0xffff0000, v22
	v_lshlrev_b32_e32 v74, 16, v23
	v_and_b32_e32 v75, 0xffff0000, v23
	v_lshlrev_b32_e32 v76, 16, v24
	v_and_b32_e32 v77, 0xffff0000, v24
	v_lshlrev_b32_e32 v78, 16, v25
	v_and_b32_e32 v79, 0xffff0000, v25
	v_lshlrev_b32_e32 v80, 16, v26
	v_and_b32_e32 v81, 0xffff0000, v26
	v_lshlrev_b32_e32 v82, 16, v27
	v_and_b32_e32 v83, 0xffff0000, v27
	v_mul_f32_e32 v86, v68, v68
	v_mul_f32_e32 v87, v72, v72
	v_mul_f32_e32 v88, v76, v76
	v_mul_f32_e32 v89, v80, v80
	v_fmac_f32_e32 v86, v69, v69
	v_fmac_f32_e32 v87, v73, v73
	v_fmac_f32_e32 v88, v77, v77
	v_fmac_f32_e32 v89, v81, v81
	v_fmac_f32_e32 v86, v70, v70
	v_fmac_f32_e32 v87, v74, v74
	v_fmac_f32_e32 v88, v78, v78
	v_fmac_f32_e32 v89, v82, v82
	v_fmac_f32_e32 v86, v71, v71
	v_fmac_f32_e32 v87, v75, v75
	v_fmac_f32_e32 v88, v79, v79
	v_fmac_f32_e32 v89, v83, v83
	v_add_f32_e32 v84, v86, v87
	v_add_f32_e32 v84, v84, v88
	v_add_f32_e32 v84, v84, v89
	v_lshlrev_b32_e32 v160, 16, v28
	v_and_b32_e32 v161, 0xffff0000, v28
	v_add_f32_dpp v84, v84, v84 quad_perm:[1,0,3,2] row_mask:0xf bank_mask:0xf
	v_lshlrev_b32_e32 v162, 16, v29
	v_and_b32_e32 v163, 0xffff0000, v29
	v_add_f32_dpp v84, v84, v84 quad_perm:[2,3,0,1] row_mask:0xf bank_mask:0xf
	v_lshlrev_b32_e32 v164, 16, v30
	v_and_b32_e32 v165, 0xffff0000, v30
	v_add_f32_dpp v84, v84, v84 row_half_mirror row_mask:0xf bank_mask:0xf
	v_lshlrev_b32_e32 v166, 16, v31
	v_and_b32_e32 v167, 0xffff0000, v31
	v_add_f32_dpp v84, v84, v84 row_mirror row_mask:0xf bank_mask:0xf
	v_lshlrev_b32_e32 v168, 16, v32
	v_and_b32_e32 v169, 0xffff0000, v32
	v_add_f32_dpp v84, v84, v84 row_bcast:15 row_mask:0xa bank_mask:0xf
	v_lshlrev_b32_e32 v170, 16, v33
	v_and_b32_e32 v171, 0xffff0000, v33
	v_add_f32_dpp v84, v84, v84 row_bcast:31 row_mask:0xc bank_mask:0xf
	v_lshlrev_b32_e32 v172, 16, v34
	v_and_b32_e32 v173, 0xffff0000, v34
	v_lshlrev_b32_e32 v174, 16, v35
	v_and_b32_e32 v175, 0xffff0000, v35
	s_nop 0
	v_readlane_b32 s83, v84, 63
	s_nop 2
	v_fma_f32 v84, s83, v2, v3
	v_rsq_f32_e32 v84, v84
	s_nop 0
	v_mul_f32_e32 v68, v68, v84
	v_mul_f32_e32 v69, v69, v84
	v_mul_f32_e32 v70, v70, v84
	v_mul_f32_e32 v71, v71, v84
	v_mul_f32_e32 v72, v72, v84
	v_mul_f32_e32 v73, v73, v84
	v_mul_f32_e32 v74, v74, v84
	v_mul_f32_e32 v75, v75, v84
	v_mul_f32_e32 v76, v76, v84
	v_mul_f32_e32 v77, v77, v84
	v_mul_f32_e32 v78, v78, v84
	v_mul_f32_e32 v79, v79, v84
	v_mul_f32_e32 v80, v80, v84
	v_mul_f32_e32 v81, v81, v84
	v_mul_f32_e32 v82, v82, v84
	v_mul_f32_e32 v83, v83, v84
	v_fma_f32 v68, v68, v4, v160
	v_fma_f32 v69, v69, v5, v161
	v_fma_f32 v70, v70, v6, v162
	v_fma_f32 v71, v71, v7, v163
	v_fma_f32 v72, v72, v8, v164
	v_fma_f32 v73, v73, v9, v165
	v_fma_f32 v74, v74, v10, v166
	v_fma_f32 v75, v75, v11, v167
	v_fma_f32 v76, v76, v12, v168
	v_fma_f32 v77, v77, v13, v169
	v_fma_f32 v78, v78, v14, v170
	v_fma_f32 v79, v79, v15, v171
	v_fma_f32 v80, v80, v16, v172
	v_fma_f32 v81, v81, v17, v173
	v_fma_f32 v82, v82, v18, v174
	v_fma_f32 v83, v83, v19, v175
	v_mul_f32_e32 v86, v68, v68
	v_mul_f32_e32 v87, v72, v72
	v_mul_f32_e32 v88, v76, v76
	v_mul_f32_e32 v89, v80, v80
	v_fmac_f32_e32 v86, v69, v69
	v_fmac_f32_e32 v87, v73, v73
	v_fmac_f32_e32 v88, v77, v77
	v_fmac_f32_e32 v89, v81, v81
	v_fmac_f32_e32 v86, v70, v70
	v_fmac_f32_e32 v87, v74, v74
	v_fmac_f32_e32 v88, v78, v78
	v_fmac_f32_e32 v89, v82, v82
	v_fmac_f32_e32 v86, v71, v71
	v_fmac_f32_e32 v87, v75, v75
	v_fmac_f32_e32 v88, v79, v79
	v_fmac_f32_e32 v89, v83, v83
	v_add_f32_e32 v85, v86, v87
	v_add_f32_e32 v85, v85, v88
	v_add_f32_e32 v85, v85, v89
	v_cvt_pk_bf16_f32 v90, v68, v69
	v_cvt_pk_bf16_f32 v91, v70, v71
	v_add_f32_dpp v85, v85, v85 quad_perm:[1,0,3,2] row_mask:0xf bank_mask:0xf
	v_cvt_pk_bf16_f32 v92, v72, v73
	v_cvt_pk_bf16_f32 v93, v74, v75
	v_add_f32_dpp v85, v85, v85 quad_perm:[2,3,0,1] row_mask:0xf bank_mask:0xf
	v_cvt_pk_bf16_f32 v94, v76, v77
	v_cvt_pk_bf16_f32 v95, v78, v79
	v_add_f32_dpp v85, v85, v85 row_half_mirror row_mask:0xf bank_mask:0xf
	v_cvt_pk_bf16_f32 v96, v80, v81
	v_cvt_pk_bf16_f32 v97, v82, v83
	v_add_f32_dpp v85, v85, v85 row_mirror row_mask:0xf bank_mask:0xf
	s_nop 1
	v_add_f32_dpp v85, v85, v85 row_bcast:15 row_mask:0xa bank_mask:0xf
	s_nop 1
	v_add_f32_dpp v85, v85, v85 row_bcast:31 row_mask:0xc bank_mask:0xf
	global_store_dwordx2 v1, v[90:91], s[74:75] offset:0
	global_store_dwordx2 v1, v[92:93], s[74:75] offset:512
	global_store_dwordx2 v1, v[94:95], s[74:75] offset:1024
	global_store_dwordx2 v1, v[96:97], s[74:75] offset:1536
	v_readlane_b32 s84, v85, 63
	s_add_u32 s74, s74, 0x400000
	s_addc_u32 s75, s75, 0
	s_nop 0
	v_fma_f32 v85, s84, v2, v3
	v_rsq_f32_e32 v85, v85
	s_nop 0
	v_mul_f32_e32 v68, v68, v85
	v_mul_f32_e32 v69, v69, v85
	v_mul_f32_e32 v70, v70, v85
	v_mul_f32_e32 v71, v71, v85
	v_mul_f32_e32 v72, v72, v85
	v_mul_f32_e32 v73, v73, v85
	v_mul_f32_e32 v74, v74, v85
	v_mul_f32_e32 v75, v75, v85
	v_mul_f32_e32 v76, v76, v85
	v_mul_f32_e32 v77, v77, v85
	v_mul_f32_e32 v78, v78, v85
	v_mul_f32_e32 v79, v79, v85
	v_mul_f32_e32 v80, v80, v85
	v_mul_f32_e32 v81, v81, v85
	v_mul_f32_e32 v82, v82, v85
	v_mul_f32_e32 v83, v83, v85
	v_mul_f32_e32 v68, v68, v100
	v_mul_f32_e32 v69, v69, v101
	v_mul_f32_e32 v70, v70, v102
	v_mul_f32_e32 v71, v71, v103
	v_mul_f32_e32 v72, v72, v104
	v_mul_f32_e32 v73, v73, v105
	v_mul_f32_e32 v74, v74, v106
	v_mul_f32_e32 v75, v75, v107
	v_mul_f32_e32 v76, v76, v108
	v_mul_f32_e32 v77, v77, v109
	v_mul_f32_e32 v78, v78, v110
	v_mul_f32_e32 v79, v79, v111
	v_mul_f32_e32 v80, v80, v112
	v_mul_f32_e32 v81, v81, v113
	v_mul_f32_e32 v82, v82, v114
	v_mul_f32_e32 v83, v83, v115
	v_cvt_pk_bf16_f32 v176, v68, v69
	v_cvt_pk_bf16_f32 v177, v70, v71
	v_cvt_pk_bf16_f32 v178, v72, v73
	v_cvt_pk_bf16_f32 v179, v74, v75
	v_cvt_pk_bf16_f32 v180, v76, v77
	v_cvt_pk_bf16_f32 v181, v78, v79
	v_cvt_pk_bf16_f32 v182, v80, v81
	v_cvt_pk_bf16_f32 v183, v82, v83
	global_store_dwordx2 v1, v[176:177], s[76:77] offset:0
	global_store_dwordx2 v1, v[178:179], s[76:77] offset:512
	global_store_dwordx2 v1, v[180:181], s[76:77] offset:1024
	global_store_dwordx2 v1, v[182:183], s[76:77] offset:1536
	s_add_u32 s76, s76, 0x400000
	s_addc_u32 s77, s77, 0
	global_load_dwordx2 v[20:21], v1, s[70:71] offset:0
	global_load_dwordx2 v[22:23], v1, s[70:71] offset:512
	global_load_dwordx2 v[24:25], v1, s[70:71] offset:1024
	global_load_dwordx2 v[26:27], v1, s[70:71] offset:1536
	global_load_dwordx2 v[28:29], v1, s[72:73] offset:0
	global_load_dwordx2 v[30:31], v1, s[72:73] offset:512
	global_load_dwordx2 v[32:33], v1, s[72:73] offset:1024
	global_load_dwordx2 v[34:35], v1, s[72:73] offset:1536
	s_add_u32 s70, s70, 0x400000
	s_addc_u32 s71, s71, 0
	s_add_u32 s72, s72, 0x400000
	s_addc_u32 s73, s73, 0
	s_waitcnt vmcnt(32)
	v_lshlrev_b32_e32 v68, 16, v36
	v_and_b32_e32 v69, 0xffff0000, v36
	v_lshlrev_b32_e32 v70, 16, v37
	v_and_b32_e32 v71, 0xffff0000, v37
	v_lshlrev_b32_e32 v72, 16, v38
	v_and_b32_e32 v73, 0xffff0000, v38
	v_lshlrev_b32_e32 v74, 16, v39
	v_and_b32_e32 v75, 0xffff0000, v39
	v_lshlrev_b32_e32 v76, 16, v40
	v_and_b32_e32 v77, 0xffff0000, v40
	v_lshlrev_b32_e32 v78, 16, v41
	v_and_b32_e32 v79, 0xffff0000, v41
	v_lshlrev_b32_e32 v80, 16, v42
	v_and_b32_e32 v81, 0xffff0000, v42
	v_lshlrev_b32_e32 v82, 16, v43
	v_and_b32_e32 v83, 0xffff0000, v43
	v_mul_f32_e32 v86, v68, v68
	v_mul_f32_e32 v87, v72, v72
	v_mul_f32_e32 v88, v76, v76
	v_mul_f32_e32 v89, v80, v80
	v_fmac_f32_e32 v86, v69, v69
	v_fmac_f32_e32 v87, v73, v73
	v_fmac_f32_e32 v88, v77, v77
	v_fmac_f32_e32 v89, v81, v81
	v_fmac_f32_e32 v86, v70, v70
	v_fmac_f32_e32 v87, v74, v74
	v_fmac_f32_e32 v88, v78, v78
	v_fmac_f32_e32 v89, v82, v82
	v_fmac_f32_e32 v86, v71, v71
	v_fmac_f32_e32 v87, v75, v75
	v_fmac_f32_e32 v88, v79, v79
	v_fmac_f32_e32 v89, v83, v83
	v_add_f32_e32 v84, v86, v87
	v_add_f32_e32 v84, v84, v88
	v_add_f32_e32 v84, v84, v89
	v_lshlrev_b32_e32 v160, 16, v44
	v_and_b32_e32 v161, 0xffff0000, v44
	v_add_f32_dpp v84, v84, v84 quad_perm:[1,0,3,2] row_mask:0xf bank_mask:0xf
	v_lshlrev_b32_e32 v162, 16, v45
	v_and_b32_e32 v163, 0xffff0000, v45
	v_add_f32_dpp v84, v84, v84 quad_perm:[2,3,0,1] row_mask:0xf bank_mask:0xf
	v_lshlrev_b32_e32 v164, 16, v46
	v_and_b32_e32 v165, 0xffff0000, v46
	v_add_f32_dpp v84, v84, v84 row_half_mirror row_mask:0xf bank_mask:0xf
	v_lshlrev_b32_e32 v166, 16, v47
	v_and_b32_e32 v167, 0xffff0000, v47
	v_add_f32_dpp v84, v84, v84 row_mirror row_mask:0xf bank_mask:0xf
	v_lshlrev_b32_e32 v168, 16, v48
	v_and_b32_e32 v169, 0xffff0000, v48
	v_add_f32_dpp v84, v84, v84 row_bcast:15 row_mask:0xa bank_mask:0xf
	v_lshlrev_b32_e32 v170, 16, v49
	v_and_b32_e32 v171, 0xffff0000, v49
	v_add_f32_dpp v84, v84, v84 row_bcast:31 row_mask:0xc bank_mask:0xf
	v_lshlrev_b32_e32 v172, 16, v50
	v_and_b32_e32 v173, 0xffff0000, v50
	v_lshlrev_b32_e32 v174, 16, v51
	v_and_b32_e32 v175, 0xffff0000, v51
	s_nop 0
	v_readlane_b32 s83, v84, 63
	s_nop 2
	v_fma_f32 v84, s83, v2, v3
	v_rsq_f32_e32 v84, v84
	s_nop 0
	v_mul_f32_e32 v68, v68, v84
	v_mul_f32_e32 v69, v69, v84
	v_mul_f32_e32 v70, v70, v84
	v_mul_f32_e32 v71, v71, v84
	v_mul_f32_e32 v72, v72, v84
	v_mul_f32_e32 v73, v73, v84
	v_mul_f32_e32 v74, v74, v84
	v_mul_f32_e32 v75, v75, v84
	v_mul_f32_e32 v76, v76, v84
	v_mul_f32_e32 v77, v77, v84
	v_mul_f32_e32 v78, v78, v84
	v_mul_f32_e32 v79, v79, v84
	v_mul_f32_e32 v80, v80, v84
	v_mul_f32_e32 v81, v81, v84
	v_mul_f32_e32 v82, v82, v84
	v_mul_f32_e32 v83, v83, v84
	v_fma_f32 v68, v68, v4, v160
	v_fma_f32 v69, v69, v5, v161
	v_fma_f32 v70, v70, v6, v162
	v_fma_f32 v71, v71, v7, v163
	v_fma_f32 v72, v72, v8, v164
	v_fma_f32 v73, v73, v9, v165
	v_fma_f32 v74, v74, v10, v166
	v_fma_f32 v75, v75, v11, v167
	v_fma_f32 v76, v76, v12, v168
	v_fma_f32 v77, v77, v13, v169
	v_fma_f32 v78, v78, v14, v170
	v_fma_f32 v79, v79, v15, v171
	v_fma_f32 v80, v80, v16, v172
	v_fma_f32 v81, v81, v17, v173
	v_fma_f32 v82, v82, v18, v174
	v_fma_f32 v83, v83, v19, v175
	v_mul_f32_e32 v86, v68, v68
	v_mul_f32_e32 v87, v72, v72
	v_mul_f32_e32 v88, v76, v76
	v_mul_f32_e32 v89, v80, v80
	v_fmac_f32_e32 v86, v69, v69
	v_fmac_f32_e32 v87, v73, v73
	v_fmac_f32_e32 v88, v77, v77
	v_fmac_f32_e32 v89, v81, v81
	v_fmac_f32_e32 v86, v70, v70
	v_fmac_f32_e32 v87, v74, v74
	v_fmac_f32_e32 v88, v78, v78
	v_fmac_f32_e32 v89, v82, v82
	v_fmac_f32_e32 v86, v71, v71
	v_fmac_f32_e32 v87, v75, v75
	v_fmac_f32_e32 v88, v79, v79
	v_fmac_f32_e32 v89, v83, v83
	v_add_f32_e32 v85, v86, v87
	v_add_f32_e32 v85, v85, v88
	v_add_f32_e32 v85, v85, v89
	v_cvt_pk_bf16_f32 v90, v68, v69
	v_cvt_pk_bf16_f32 v91, v70, v71
	v_add_f32_dpp v85, v85, v85 quad_perm:[1,0,3,2] row_mask:0xf bank_mask:0xf
	v_cvt_pk_bf16_f32 v92, v72, v73
	v_cvt_pk_bf16_f32 v93, v74, v75
	v_add_f32_dpp v85, v85, v85 quad_perm:[2,3,0,1] row_mask:0xf bank_mask:0xf
	v_cvt_pk_bf16_f32 v94, v76, v77
	v_cvt_pk_bf16_f32 v95, v78, v79
	v_add_f32_dpp v85, v85, v85 row_half_mirror row_mask:0xf bank_mask:0xf
	v_cvt_pk_bf16_f32 v96, v80, v81
	v_cvt_pk_bf16_f32 v97, v82, v83
	v_add_f32_dpp v85, v85, v85 row_mirror row_mask:0xf bank_mask:0xf
	s_nop 1
	v_add_f32_dpp v85, v85, v85 row_bcast:15 row_mask:0xa bank_mask:0xf
	s_nop 1
	v_add_f32_dpp v85, v85, v85 row_bcast:31 row_mask:0xc bank_mask:0xf
	global_store_dwordx2 v1, v[90:91], s[74:75] offset:0
	global_store_dwordx2 v1, v[92:93], s[74:75] offset:512
	global_store_dwordx2 v1, v[94:95], s[74:75] offset:1024
	global_store_dwordx2 v1, v[96:97], s[74:75] offset:1536
	v_readlane_b32 s84, v85, 63
	s_add_u32 s74, s74, 0x400000
	s_addc_u32 s75, s75, 0
	s_nop 0
	v_fma_f32 v85, s84, v2, v3
	v_rsq_f32_e32 v85, v85
	s_nop 0
	v_mul_f32_e32 v68, v68, v85
	v_mul_f32_e32 v69, v69, v85
	v_mul_f32_e32 v70, v70, v85
	v_mul_f32_e32 v71, v71, v85
	v_mul_f32_e32 v72, v72, v85
	v_mul_f32_e32 v73, v73, v85
	v_mul_f32_e32 v74, v74, v85
	v_mul_f32_e32 v75, v75, v85
	v_mul_f32_e32 v76, v76, v85
	v_mul_f32_e32 v77, v77, v85
	v_mul_f32_e32 v78, v78, v85
	v_mul_f32_e32 v79, v79, v85
	v_mul_f32_e32 v80, v80, v85
	v_mul_f32_e32 v81, v81, v85
	v_mul_f32_e32 v82, v82, v85
	v_mul_f32_e32 v83, v83, v85
	v_mul_f32_e32 v68, v68, v100
	v_mul_f32_e32 v69, v69, v101
	v_mul_f32_e32 v70, v70, v102
	v_mul_f32_e32 v71, v71, v103
	v_mul_f32_e32 v72, v72, v104
	v_mul_f32_e32 v73, v73, v105
	v_mul_f32_e32 v74, v74, v106
	v_mul_f32_e32 v75, v75, v107
	v_mul_f32_e32 v76, v76, v108
	v_mul_f32_e32 v77, v77, v109
	v_mul_f32_e32 v78, v78, v110
	v_mul_f32_e32 v79, v79, v111
	v_mul_f32_e32 v80, v80, v112
	v_mul_f32_e32 v81, v81, v113
	v_mul_f32_e32 v82, v82, v114
	v_mul_f32_e32 v83, v83, v115
	v_cvt_pk_bf16_f32 v176, v68, v69
	v_cvt_pk_bf16_f32 v177, v70, v71
	v_cvt_pk_bf16_f32 v178, v72, v73
	v_cvt_pk_bf16_f32 v179, v74, v75
	v_cvt_pk_bf16_f32 v180, v76, v77
	v_cvt_pk_bf16_f32 v181, v78, v79
	v_cvt_pk_bf16_f32 v182, v80, v81
	v_cvt_pk_bf16_f32 v183, v82, v83
	global_store_dwordx2 v1, v[176:177], s[76:77] offset:0
	global_store_dwordx2 v1, v[178:179], s[76:77] offset:512
	global_store_dwordx2 v1, v[180:181], s[76:77] offset:1024
	global_store_dwordx2 v1, v[182:183], s[76:77] offset:1536
	s_add_u32 s76, s76, 0x400000
	s_addc_u32 s77, s77, 0
	global_load_dwordx2 v[36:37], v1, s[70:71] offset:0
	global_load_dwordx2 v[38:39], v1, s[70:71] offset:512
	global_load_dwordx2 v[40:41], v1, s[70:71] offset:1024
	global_load_dwordx2 v[42:43], v1, s[70:71] offset:1536
	global_load_dwordx2 v[44:45], v1, s[72:73] offset:0
	global_load_dwordx2 v[46:47], v1, s[72:73] offset:512
	global_load_dwordx2 v[48:49], v1, s[72:73] offset:1024
	global_load_dwordx2 v[50:51], v1, s[72:73] offset:1536
	s_add_u32 s70, s70, 0x400000
	s_addc_u32 s71, s71, 0
	s_add_u32 s72, s72, 0x400000
	s_addc_u32 s73, s73, 0
	s_waitcnt vmcnt(32)
	v_lshlrev_b32_e32 v68, 16, v52
	v_and_b32_e32 v69, 0xffff0000, v52
	v_lshlrev_b32_e32 v70, 16, v53
	v_and_b32_e32 v71, 0xffff0000, v53
	v_lshlrev_b32_e32 v72, 16, v54
	v_and_b32_e32 v73, 0xffff0000, v54
	v_lshlrev_b32_e32 v74, 16, v55
	v_and_b32_e32 v75, 0xffff0000, v55
	v_lshlrev_b32_e32 v76, 16, v56
	v_and_b32_e32 v77, 0xffff0000, v56
	v_lshlrev_b32_e32 v78, 16, v57
	v_and_b32_e32 v79, 0xffff0000, v57
	v_lshlrev_b32_e32 v80, 16, v58
	v_and_b32_e32 v81, 0xffff0000, v58
	v_lshlrev_b32_e32 v82, 16, v59
	v_and_b32_e32 v83, 0xffff0000, v59
	v_mul_f32_e32 v86, v68, v68
	v_mul_f32_e32 v87, v72, v72
	v_mul_f32_e32 v88, v76, v76
	v_mul_f32_e32 v89, v80, v80
	v_fmac_f32_e32 v86, v69, v69
	v_fmac_f32_e32 v87, v73, v73
	v_fmac_f32_e32 v88, v77, v77
	v_fmac_f32_e32 v89, v81, v81
	v_fmac_f32_e32 v86, v70, v70
	v_fmac_f32_e32 v87, v74, v74
	v_fmac_f32_e32 v88, v78, v78
	v_fmac_f32_e32 v89, v82, v82
	v_fmac_f32_e32 v86, v71, v71
	v_fmac_f32_e32 v87, v75, v75
	v_fmac_f32_e32 v88, v79, v79
	v_fmac_f32_e32 v89, v83, v83
	v_add_f32_e32 v84, v86, v87
	v_add_f32_e32 v84, v84, v88
	v_add_f32_e32 v84, v84, v89
	v_lshlrev_b32_e32 v160, 16, v60
	v_and_b32_e32 v161, 0xffff0000, v60
	v_add_f32_dpp v84, v84, v84 quad_perm:[1,0,3,2] row_mask:0xf bank_mask:0xf
	v_lshlrev_b32_e32 v162, 16, v61
	v_and_b32_e32 v163, 0xffff0000, v61
	v_add_f32_dpp v84, v84, v84 quad_perm:[2,3,0,1] row_mask:0xf bank_mask:0xf
	v_lshlrev_b32_e32 v164, 16, v62
	v_and_b32_e32 v165, 0xffff0000, v62
	v_add_f32_dpp v84, v84, v84 row_half_mirror row_mask:0xf bank_mask:0xf
	v_lshlrev_b32_e32 v166, 16, v63
	v_and_b32_e32 v167, 0xffff0000, v63
	v_add_f32_dpp v84, v84, v84 row_mirror row_mask:0xf bank_mask:0xf
	v_lshlrev_b32_e32 v168, 16, v64
	v_and_b32_e32 v169, 0xffff0000, v64
	v_add_f32_dpp v84, v84, v84 row_bcast:15 row_mask:0xa bank_mask:0xf
	v_lshlrev_b32_e32 v170, 16, v65
	v_and_b32_e32 v171, 0xffff0000, v65
	v_add_f32_dpp v84, v84, v84 row_bcast:31 row_mask:0xc bank_mask:0xf
	v_lshlrev_b32_e32 v172, 16, v66
	v_and_b32_e32 v173, 0xffff0000, v66
	v_lshlrev_b32_e32 v174, 16, v67
	v_and_b32_e32 v175, 0xffff0000, v67
	s_nop 0
	v_readlane_b32 s83, v84, 63
	s_nop 2
	v_fma_f32 v84, s83, v2, v3
	v_rsq_f32_e32 v84, v84
	s_nop 0
	v_mul_f32_e32 v68, v68, v84
	v_mul_f32_e32 v69, v69, v84
	v_mul_f32_e32 v70, v70, v84
	v_mul_f32_e32 v71, v71, v84
	v_mul_f32_e32 v72, v72, v84
	v_mul_f32_e32 v73, v73, v84
	v_mul_f32_e32 v74, v74, v84
	v_mul_f32_e32 v75, v75, v84
	v_mul_f32_e32 v76, v76, v84
	v_mul_f32_e32 v77, v77, v84
	v_mul_f32_e32 v78, v78, v84
	v_mul_f32_e32 v79, v79, v84
	v_mul_f32_e32 v80, v80, v84
	v_mul_f32_e32 v81, v81, v84
	v_mul_f32_e32 v82, v82, v84
	v_mul_f32_e32 v83, v83, v84
	v_fma_f32 v68, v68, v4, v160
	v_fma_f32 v69, v69, v5, v161
	v_fma_f32 v70, v70, v6, v162
	v_fma_f32 v71, v71, v7, v163
	v_fma_f32 v72, v72, v8, v164
	v_fma_f32 v73, v73, v9, v165
	v_fma_f32 v74, v74, v10, v166
	v_fma_f32 v75, v75, v11, v167
	v_fma_f32 v76, v76, v12, v168
	v_fma_f32 v77, v77, v13, v169
	v_fma_f32 v78, v78, v14, v170
	v_fma_f32 v79, v79, v15, v171
	v_fma_f32 v80, v80, v16, v172
	v_fma_f32 v81, v81, v17, v173
	v_fma_f32 v82, v82, v18, v174
	v_fma_f32 v83, v83, v19, v175
	v_mul_f32_e32 v86, v68, v68
	v_mul_f32_e32 v87, v72, v72
	v_mul_f32_e32 v88, v76, v76
	v_mul_f32_e32 v89, v80, v80
	v_fmac_f32_e32 v86, v69, v69
	v_fmac_f32_e32 v87, v73, v73
	v_fmac_f32_e32 v88, v77, v77
	v_fmac_f32_e32 v89, v81, v81
	v_fmac_f32_e32 v86, v70, v70
	v_fmac_f32_e32 v87, v74, v74
	v_fmac_f32_e32 v88, v78, v78
	v_fmac_f32_e32 v89, v82, v82
	v_fmac_f32_e32 v86, v71, v71
	v_fmac_f32_e32 v87, v75, v75
	v_fmac_f32_e32 v88, v79, v79
	v_fmac_f32_e32 v89, v83, v83
	v_add_f32_e32 v85, v86, v87
	v_add_f32_e32 v85, v85, v88
	v_add_f32_e32 v85, v85, v89
	v_cvt_pk_bf16_f32 v90, v68, v69
	v_cvt_pk_bf16_f32 v91, v70, v71
	v_add_f32_dpp v85, v85, v85 quad_perm:[1,0,3,2] row_mask:0xf bank_mask:0xf
	v_cvt_pk_bf16_f32 v92, v72, v73
	v_cvt_pk_bf16_f32 v93, v74, v75
	v_add_f32_dpp v85, v85, v85 quad_perm:[2,3,0,1] row_mask:0xf bank_mask:0xf
	v_cvt_pk_bf16_f32 v94, v76, v77
	v_cvt_pk_bf16_f32 v95, v78, v79
	v_add_f32_dpp v85, v85, v85 row_half_mirror row_mask:0xf bank_mask:0xf
	v_cvt_pk_bf16_f32 v96, v80, v81
	v_cvt_pk_bf16_f32 v97, v82, v83
	v_add_f32_dpp v85, v85, v85 row_mirror row_mask:0xf bank_mask:0xf
	s_nop 1
	v_add_f32_dpp v85, v85, v85 row_bcast:15 row_mask:0xa bank_mask:0xf
	s_nop 1
	v_add_f32_dpp v85, v85, v85 row_bcast:31 row_mask:0xc bank_mask:0xf
	global_store_dwordx2 v1, v[90:91], s[74:75] offset:0
	global_store_dwordx2 v1, v[92:93], s[74:75] offset:512
	global_store_dwordx2 v1, v[94:95], s[74:75] offset:1024
	global_store_dwordx2 v1, v[96:97], s[74:75] offset:1536
	v_readlane_b32 s84, v85, 63
	s_add_u32 s74, s74, 0x400000
	s_addc_u32 s75, s75, 0
	s_nop 0
	v_fma_f32 v85, s84, v2, v3
	v_rsq_f32_e32 v85, v85
	s_nop 0
	v_mul_f32_e32 v68, v68, v85
	v_mul_f32_e32 v69, v69, v85
	v_mul_f32_e32 v70, v70, v85
	v_mul_f32_e32 v71, v71, v85
	v_mul_f32_e32 v72, v72, v85
	v_mul_f32_e32 v73, v73, v85
	v_mul_f32_e32 v74, v74, v85
	v_mul_f32_e32 v75, v75, v85
	v_mul_f32_e32 v76, v76, v85
	v_mul_f32_e32 v77, v77, v85
	v_mul_f32_e32 v78, v78, v85
	v_mul_f32_e32 v79, v79, v85
	v_mul_f32_e32 v80, v80, v85
	v_mul_f32_e32 v81, v81, v85
	v_mul_f32_e32 v82, v82, v85
	v_mul_f32_e32 v83, v83, v85
	v_mul_f32_e32 v68, v68, v100
	v_mul_f32_e32 v69, v69, v101
	v_mul_f32_e32 v70, v70, v102
	v_mul_f32_e32 v71, v71, v103
	v_mul_f32_e32 v72, v72, v104
	v_mul_f32_e32 v73, v73, v105
	v_mul_f32_e32 v74, v74, v106
	v_mul_f32_e32 v75, v75, v107
	v_mul_f32_e32 v76, v76, v108
	v_mul_f32_e32 v77, v77, v109
	v_mul_f32_e32 v78, v78, v110
	v_mul_f32_e32 v79, v79, v111
	v_mul_f32_e32 v80, v80, v112
	v_mul_f32_e32 v81, v81, v113
	v_mul_f32_e32 v82, v82, v114
	v_mul_f32_e32 v83, v83, v115
	v_cvt_pk_bf16_f32 v176, v68, v69
	v_cvt_pk_bf16_f32 v177, v70, v71
	v_cvt_pk_bf16_f32 v178, v72, v73
	v_cvt_pk_bf16_f32 v179, v74, v75
	v_cvt_pk_bf16_f32 v180, v76, v77
	v_cvt_pk_bf16_f32 v181, v78, v79
	v_cvt_pk_bf16_f32 v182, v80, v81
	v_cvt_pk_bf16_f32 v183, v82, v83
	global_store_dwordx2 v1, v[176:177], s[76:77] offset:0
	global_store_dwordx2 v1, v[178:179], s[76:77] offset:512
	global_store_dwordx2 v1, v[180:181], s[76:77] offset:1024
	global_store_dwordx2 v1, v[182:183], s[76:77] offset:1536
	s_add_u32 s76, s76, 0x400000
	s_addc_u32 s77, s77, 0
	s_cmp_eq_u32 s82, 0
	s_cbranch_scc0 .Lrows_p9_r8ok
	s_sub_u32 s70, s70, 0x400000
	s_subb_u32 s71, s71, 0
	s_sub_u32 s72, s72, 0x400000
	s_subb_u32 s73, s73, 0

.Lrows_p9_done:
.LBB0_850:
	s_or_b64 exec, exec, s[8:9]
	s_cmp_lt_i32 s25, 11
	s_cbranch_scc1 .LBB0_904
	s_waitcnt vmcnt(0)
	s_waitcnt vmcnt(0) lgkmcnt(0)
	s_barrier
	s_and_saveexec_b64 s[4:5], s[92:93]
	s_cbranch_execz .LBB0_903
	s_add_i32 s8, 0, 0x20000
	v_mov_b32_e32 v0, s8
	s_waitcnt vmcnt(0) expcnt(0) lgkmcnt(0)
	ds_read_b32 v2, v0
	s_add_i32 s8, 0, 0x20004
	v_mov_b32_e32 v0, s8
	ds_read_b32 v0, v0
	s_waitcnt lgkmcnt(1)
	v_cmp_ne_u32_e32 vcc, 0, v2
	s_cbranch_vccnz .LBB0_867
	s_load_dwordx2 s[10:11], s[6:7], 0x4
	s_add_u32 s6, s48, 0x1000
	s_addc_u32 s7, s49, 0
	s_add_u32 s8, s48, 0x1100
	s_addc_u32 s9, s49, 0
	s_waitcnt lgkmcnt(0)
	s_mul_i32 s3, s10, s3
	s_add_u32 s10, s48, 0x1200
	s_mul_i32 s3, s3, s11
	s_addc_u32 s11, s49, 0
	s_add_u32 s12, s48, 0x1300
	s_addc_u32 s13, s49, 0
	s_mov_b32 s20, 1
	v_mov_b32_e32 v16, 0
	s_branch .LBB0_855

.LBB0_1201:
	s_cmp_lt_i32 s24, 14
	s_cselect_b64 s[4:5], -1, 0
	s_cmp_gt_i32 s25, 13
	s_cselect_b64 s[6:7], -1, 0
	s_and_b64 s[4:5], s[4:5], s[6:7]
	s_andn2_b64 vcc, exec, s[4:5]
	s_cbranch_vccnz .LBB0_1263
	s_mov_b64 exec, -1
	s_load_dword s3, s[0:1], 0x148
	s_add_u32 s6, s0, 0x148
	s_addc_u32 s7, s1, 0
	s_load_dwordx2 s[78:79], s[0:1], 0x30
	s_load_dwordx2 s[80:81], s[0:1], 0x38
	v_lshrrev_b32_e32 v0, 6, v129
	v_and_b32_e32 v1, 63, v129
	v_readfirstlane_b32 s68, v0
	v_lshlrev_b32_e32 v0, 4, v1
	v_lshlrev_b32_e32 v1, 3, v1
	v_mov_b32_e32 v2, 0x3a800000
	v_mov_b32_e32 v3, 0x358637bd
	s_lshl_b32 s69, s2, 3
	s_add_u32 s68, s68, s69
	s_waitcnt lgkmcnt(0)
	s_add_u32 s78, s78, 0x1000
	s_addc_u32 s79, s79, 0
	s_add_u32 s80, s80, 0x1000
	s_addc_u32 s81, s81, 0
	global_load_dwordx4 v[4:7], v0, s[78:79] offset:0
	global_load_dwordx4 v[8:11], v0, s[78:79] offset:1024
	global_load_dwordx4 v[12:15], v0, s[78:79] offset:2048
	global_load_dwordx4 v[16:19], v0, s[78:79] offset:3072
	global_load_dwordx4 v[100:103], v0, s[80:81] offset:0
	global_load_dwordx4 v[104:107], v0, s[80:81] offset:1024
	global_load_dwordx4 v[108:111], v0, s[80:81] offset:2048
	global_load_dwordx4 v[112:115], v0, s[80:81] offset:3072
	s_lshl_b32 s86, s68, 11
	s_add_u32 s70, s46, s86
	s_addc_u32 s71, s47, 0
	s_add_u32 s72, s50, s86
	s_addc_u32 s73, s51, 0
	s_mov_b64 s[74:75], s[72:73]
	s_add_u32 s76, s44, s86
	s_addc_u32 s77, s45, 0
	s_cmpk_lt_u32 s68, 0x200
	s_cselect_b32 s82, 1, 0
	global_load_dwordx2 v[20:21], v1, s[70:71] offset:0
	global_load_dwordx2 v[22:23], v1, s[70:71] offset:512
	global_load_dwordx2 v[24:25], v1, s[70:71] offset:1024
	global_load_dwordx2 v[26:27], v1, s[70:71] offset:1536
	global_load_dwordx2 v[28:29], v1, s[72:73] offset:0
	global_load_dwordx2 v[30:31], v1, s[72:73] offset:512
	global_load_dwordx2 v[32:33], v1, s[72:73] offset:1024
	global_load_dwordx2 v[34:35], v1, s[72:73] offset:1536
	s_add_u32 s70, s70, 0x400000
	s_addc_u32 s71, s71, 0
	s_add_u32 s72, s72, 0x400000
	s_addc_u32 s73, s73, 0
	global_load_dwordx2 v[36:37], v1, s[70:71] offset:0
	global_load_dwordx2 v[38:39], v1, s[70:71] offset:512
	global_load_dwordx2 v[40:41], v1, s[70:71] offset:1024
	global_load_dwordx2 v[42:43], v1, s[70:71] offset:1536
	global_load_dwordx2 v[44:45], v1, s[72:73] offset:0
	global_load_dwordx2 v[46:47], v1, s[72:73] offset:512
	global_load_dwordx2 v[48:49], v1, s[72:73] offset:1024
	global_load_dwordx2 v[50:51], v1, s[72:73] offset:1536
	s_add_u32 s70, s70, 0x400000
	s_addc_u32 s71, s71, 0
	s_add_u32 s72, s72, 0x400000
	s_addc_u32 s73, s73, 0
	global_load_dwordx2 v[52:53], v1, s[70:71] offset:0
	global_load_dwordx2 v[54:55], v1, s[70:71] offset:512
	global_load_dwordx2 v[56:57], v1, s[70:71] offset:1024
	global_load_dwordx2 v[58:59], v1, s[70:71] offset:1536
	global_load_dwordx2 v[60:61], v1, s[72:73] offset:0
	global_load_dwordx2 v[62:63], v1, s[72:73] offset:512
	global_load_dwordx2 v[64:65], v1, s[72:73] offset:1024
	global_load_dwordx2 v[66:67], v1, s[72:73] offset:1536
	s_add_u32 s70, s70, 0x400000
	s_addc_u32 s71, s71, 0
	s_add_u32 s72, s72, 0x400000
	s_addc_u32 s73, s73, 0
	s_waitcnt vmcnt(16)
	v_lshlrev_b32_e32 v68, 16, v20
	v_and_b32_e32 v69, 0xffff0000, v20
	v_lshlrev_b32_e32 v70, 16, v21
	v_and_b32_e32 v71, 0xffff0000, v21
	v_lshlrev_b32_e32 v72, 16, v22
	v_and_b32_e32 v73, 0xffff0000, v22
	v_lshlrev_b32_e32 v74, 16, v23
	v_and_b32_e32 v75, 0xffff0000, v23
	v_lshlrev_b32_e32 v76, 16, v24
	v_and_b32_e32 v77, 0xffff0000, v24
	v_lshlrev_b32_e32 v78, 16, v25
	v_and_b32_e32 v79, 0xffff0000, v25
	v_lshlrev_b32_e32 v80, 16, v26
	v_and_b32_e32 v81, 0xffff0000, v26
	v_lshlrev_b32_e32 v82, 16, v27
	v_and_b32_e32 v83, 0xffff0000, v27
	v_mul_f32_e32 v86, v68, v68
	v_mul_f32_e32 v87, v72, v72
	v_mul_f32_e32 v88, v76, v76
	v_mul_f32_e32 v89, v80, v80
	v_fmac_f32_e32 v86, v69, v69
	v_fmac_f32_e32 v87, v73, v73
	v_fmac_f32_e32 v88, v77, v77
	v_fmac_f32_e32 v89, v81, v81
	v_fmac_f32_e32 v86, v70, v70
	v_fmac_f32_e32 v87, v74, v74
	v_fmac_f32_e32 v88, v78, v78
	v_fmac_f32_e32 v89, v82, v82
	v_fmac_f32_e32 v86, v71, v71
	v_fmac_f32_e32 v87, v75, v75
	v_fmac_f32_e32 v88, v79, v79
	v_fmac_f32_e32 v89, v83, v83
	v_add_f32_e32 v84, v86, v87
	v_add_f32_e32 v84, v84, v88
	v_add_f32_e32 v84, v84, v89
	v_lshlrev_b32_e32 v160, 16, v28
	v_and_b32_e32 v161, 0xffff0000, v28
	v_add_f32_dpp v84, v84, v84 quad_perm:[1,0,3,2] row_mask:0xf bank_mask:0xf
	v_lshlrev_b32_e32 v162, 16, v29
	v_and_b32_e32 v163, 0xffff0000, v29
	v_add_f32_dpp v84, v84, v84 quad_perm:[2,3,0,1] row_mask:0xf bank_mask:0xf
	v_lshlrev_b32_e32 v164, 16, v30
	v_and_b32_e32 v165, 0xffff0000, v30
	v_add_f32_dpp v84, v84, v84 row_half_mirror row_mask:0xf bank_mask:0xf
	v_lshlrev_b32_e32 v166, 16, v31
	v_and_b32_e32 v167, 0xffff0000, v31
	v_add_f32_dpp v84, v84, v84 row_mirror row_mask:0xf bank_mask:0xf
	v_lshlrev_b32_e32 v168, 16, v32
	v_and_b32_e32 v169, 0xffff0000, v32
	v_add_f32_dpp v84, v84, v84 row_bcast:15 row_mask:0xa bank_mask:0xf
	v_lshlrev_b32_e32 v170, 16, v33
	v_and_b32_e32 v171, 0xffff0000, v33
	v_add_f32_dpp v84, v84, v84 row_bcast:31 row_mask:0xc bank_mask:0xf
	v_lshlrev_b32_e32 v172, 16, v34
	v_and_b32_e32 v173, 0xffff0000, v34
	v_lshlrev_b32_e32 v174, 16, v35
	v_and_b32_e32 v175, 0xffff0000, v35
	s_nop 0
	v_readlane_b32 s83, v84, 63
	s_nop 2
	v_fma_f32 v84, s83, v2, v3
	v_rsq_f32_e32 v84, v84
	s_nop 0
	v_mul_f32_e32 v68, v68, v84
	v_mul_f32_e32 v69, v69, v84
	v_mul_f32_e32 v70, v70, v84
	v_mul_f32_e32 v71, v71, v84
	v_mul_f32_e32 v72, v72, v84
	v_mul_f32_e32 v73, v73, v84
	v_mul_f32_e32 v74, v74, v84
	v_mul_f32_e32 v75, v75, v84
	v_mul_f32_e32 v76, v76, v84
	v_mul_f32_e32 v77, v77, v84
	v_mul_f32_e32 v78, v78, v84
	v_mul_f32_e32 v79, v79, v84
	v_mul_f32_e32 v80, v80, v84
	v_mul_f32_e32 v81, v81, v84
	v_mul_f32_e32 v82, v82, v84
	v_mul_f32_e32 v83, v83, v84
	v_fma_f32 v68, v68, v4, v160
	v_fma_f32 v69, v69, v5, v161
	v_fma_f32 v70, v70, v6, v162
	v_fma_f32 v71, v71, v7, v163
	v_fma_f32 v72, v72, v8, v164
	v_fma_f32 v73, v73, v9, v165
	v_fma_f32 v74, v74, v10, v166
	v_fma_f32 v75, v75, v11, v167
	v_fma_f32 v76, v76, v12, v168
	v_fma_f32 v77, v77, v13, v169
	v_fma_f32 v78, v78, v14, v170
	v_fma_f32 v79, v79, v15, v171
	v_fma_f32 v80, v80, v16, v172
	v_fma_f32 v81, v81, v17, v173
	v_fma_f32 v82, v82, v18, v174
	v_fma_f32 v83, v83, v19, v175
	v_mul_f32_e32 v86, v68, v68
	v_mul_f32_e32 v87, v72, v72
	v_mul_f32_e32 v88, v76, v76
	v_mul_f32_e32 v89, v80, v80
	v_fmac_f32_e32 v86, v69, v69
	v_fmac_f32_e32 v87, v73, v73
	v_fmac_f32_e32 v88, v77, v77
	v_fmac_f32_e32 v89, v81, v81
	v_fmac_f32_e32 v86, v70, v70
	v_fmac_f32_e32 v87, v74, v74
	v_fmac_f32_e32 v88, v78, v78
	v_fmac_f32_e32 v89, v82, v82
	v_fmac_f32_e32 v86, v71, v71
	v_fmac_f32_e32 v87, v75, v75
	v_fmac_f32_e32 v88, v79, v79
	v_fmac_f32_e32 v89, v83, v83
	v_add_f32_e32 v85, v86, v87
	v_add_f32_e32 v85, v85, v88
	v_add_f32_e32 v85, v85, v89
	v_cvt_pk_bf16_f32 v90, v68, v69
	v_cvt_pk_bf16_f32 v91, v70, v71
	v_add_f32_dpp v85, v85, v85 quad_perm:[1,0,3,2] row_mask:0xf bank_mask:0xf
	v_cvt_pk_bf16_f32 v92, v72, v73
	v_cvt_pk_bf16_f32 v93, v74, v75
	v_add_f32_dpp v85, v85, v85 quad_perm:[2,3,0,1] row_mask:0xf bank_mask:0xf
	v_cvt_pk_bf16_f32 v94, v76, v77
	v_cvt_pk_bf16_f32 v95, v78, v79
	v_add_f32_dpp v85, v85, v85 row_half_mirror row_mask:0xf bank_mask:0xf
	v_cvt_pk_bf16_f32 v96, v80, v81
	v_cvt_pk_bf16_f32 v97, v82, v83
	v_add_f32_dpp v85, v85, v85 row_mirror row_mask:0xf bank_mask:0xf
	s_nop 1
	v_add_f32_dpp v85, v85, v85 row_bcast:15 row_mask:0xa bank_mask:0xf
	s_nop 1
	v_add_f32_dpp v85, v85, v85 row_bcast:31 row_mask:0xc bank_mask:0xf
	global_store_dwordx2 v1, v[90:91], s[74:75] offset:0
	global_store_dwordx2 v1, v[92:93], s[74:75] offset:512
	global_store_dwordx2 v1, v[94:95], s[74:75] offset:1024
	global_store_dwordx2 v1, v[96:97], s[74:75] offset:1536
	v_readlane_b32 s84, v85, 63
	s_add_u32 s74, s74, 0x400000
	s_addc_u32 s75, s75, 0
	s_nop 0
	v_fma_f32 v85, s84, v2, v3
	v_rsq_f32_e32 v85, v85
	s_nop 0
	v_mul_f32_e32 v68, v68, v85
	v_mul_f32_e32 v69, v69, v85
	v_mul_f32_e32 v70, v70, v85
	v_mul_f32_e32 v71, v71, v85
	v_mul_f32_e32 v72, v72, v85
	v_mul_f32_e32 v73, v73, v85
	v_mul_f32_e32 v74, v74, v85
	v_mul_f32_e32 v75, v75, v85
	v_mul_f32_e32 v76, v76, v85
	v_mul_f32_e32 v77, v77, v85
	v_mul_f32_e32 v78, v78, v85
	v_mul_f32_e32 v79, v79, v85
	v_mul_f32_e32 v80, v80, v85
	v_mul_f32_e32 v81, v81, v85
	v_mul_f32_e32 v82, v82, v85
	v_mul_f32_e32 v83, v83, v85
	v_mul_f32_e32 v68, v68, v100
	v_mul_f32_e32 v69, v69, v101
	v_mul_f32_e32 v70, v70, v102
	v_mul_f32_e32 v71, v71, v103
	v_mul_f32_e32 v72, v72, v104
	v_mul_f32_e32 v73, v73, v105
	v_mul_f32_e32 v74, v74, v106
	v_mul_f32_e32 v75, v75, v107
	v_mul_f32_e32 v76, v76, v108
	v_mul_f32_e32 v77, v77, v109
	v_mul_f32_e32 v78, v78, v110
	v_mul_f32_e32 v79, v79, v111
	v_mul_f32_e32 v80, v80, v112
	v_mul_f32_e32 v81, v81, v113
	v_mul_f32_e32 v82, v82, v114
	v_mul_f32_e32 v83, v83, v115
	v_cvt_pk_bf16_f32 v176, v68, v69
	v_cvt_pk_bf16_f32 v177, v70, v71
	v_cvt_pk_bf16_f32 v178, v72, v73
	v_cvt_pk_bf16_f32 v179, v74, v75
	v_cvt_pk_bf16_f32 v180, v76, v77
	v_cvt_pk_bf16_f32 v181, v78, v79
	v_cvt_pk_bf16_f32 v182, v80, v81
	v_cvt_pk_bf16_f32 v183, v82, v83
	global_store_dwordx2 v1, v[176:177], s[76:77] offset:0
	global_store_dwordx2 v1, v[178:179], s[76:77] offset:512
	global_store_dwordx2 v1, v[180:181], s[76:77] offset:1024
	global_store_dwordx2 v1, v[182:183], s[76:77] offset:1536
	s_add_u32 s76, s76, 0x400000
	s_addc_u32 s77, s77, 0
	global_load_dwordx2 v[20:21], v1, s[70:71] offset:0
	global_load_dwordx2 v[22:23], v1, s[70:71] offset:512
	global_load_dwordx2 v[24:25], v1, s[70:71] offset:1024
	global_load_dwordx2 v[26:27], v1, s[70:71] offset:1536
	global_load_dwordx2 v[28:29], v1, s[72:73] offset:0
	global_load_dwordx2 v[30:31], v1, s[72:73] offset:512
	global_load_dwordx2 v[32:33], v1, s[72:73] offset:1024
	global_load_dwordx2 v[34:35], v1, s[72:73] offset:1536
	s_add_u32 s70, s70, 0x400000
	s_addc_u32 s71, s71, 0
	s_add_u32 s72, s72, 0x400000
	s_addc_u32 s73, s73, 0
	s_waitcnt vmcnt(24)
	v_lshlrev_b32_e32 v68, 16, v36
	v_and_b32_e32 v69, 0xffff0000, v36
	v_lshlrev_b32_e32 v70, 16, v37
	v_and_b32_e32 v71, 0xffff0000, v37
	v_lshlrev_b32_e32 v72, 16, v38
	v_and_b32_e32 v73, 0xffff0000, v38
	v_lshlrev_b32_e32 v74, 16, v39
	v_and_b32_e32 v75, 0xffff0000, v39
	v_lshlrev_b32_e32 v76, 16, v40
	v_and_b32_e32 v77, 0xffff0000, v40
	v_lshlrev_b32_e32 v78, 16, v41
	v_and_b32_e32 v79, 0xffff0000, v41
	v_lshlrev_b32_e32 v80, 16, v42
	v_and_b32_e32 v81, 0xffff0000, v42
	v_lshlrev_b32_e32 v82, 16, v43
	v_and_b32_e32 v83, 0xffff0000, v43
	v_mul_f32_e32 v86, v68, v68
	v_mul_f32_e32 v87, v72, v72
	v_mul_f32_e32 v88, v76, v76
	v_mul_f32_e32 v89, v80, v80
	v_fmac_f32_e32 v86, v69, v69
	v_fmac_f32_e32 v87, v73, v73
	v_fmac_f32_e32 v88, v77, v77
	v_fmac_f32_e32 v89, v81, v81
	v_fmac_f32_e32 v86, v70, v70
	v_fmac_f32_e32 v87, v74, v74
	v_fmac_f32_e32 v88, v78, v78
	v_fmac_f32_e32 v89, v82, v82
	v_fmac_f32_e32 v86, v71, v71
	v_fmac_f32_e32 v87, v75, v75
	v_fmac_f32_e32 v88, v79, v79
	v_fmac_f32_e32 v89, v83, v83
	v_add_f32_e32 v84, v86, v87
	v_add_f32_e32 v84, v84, v88
	v_add_f32_e32 v84, v84, v89
	v_lshlrev_b32_e32 v160, 16, v44
	v_and_b32_e32 v161, 0xffff0000, v44
	v_add_f32_dpp v84, v84, v84 quad_perm:[1,0,3,2] row_mask:0xf bank_mask:0xf
	v_lshlrev_b32_e32 v162, 16, v45
	v_and_b32_e32 v163, 0xffff0000, v45
	v_add_f32_dpp v84, v84, v84 quad_perm:[2,3,0,1] row_mask:0xf bank_mask:0xf
	v_lshlrev_b32_e32 v164, 16, v46
	v_and_b32_e32 v165, 0xffff0000, v46
	v_add_f32_dpp v84, v84, v84 row_half_mirror row_mask:0xf bank_mask:0xf
	v_lshlrev_b32_e32 v166, 16, v47
	v_and_b32_e32 v167, 0xffff0000, v47
	v_add_f32_dpp v84, v84, v84 row_mirror row_mask:0xf bank_mask:0xf
	v_lshlrev_b32_e32 v168, 16, v48
	v_and_b32_e32 v169, 0xffff0000, v48
	v_add_f32_dpp v84, v84, v84 row_bcast:15 row_mask:0xa bank_mask:0xf
	v_lshlrev_b32_e32 v170, 16, v49
	v_and_b32_e32 v171, 0xffff0000, v49
	v_add_f32_dpp v84, v84, v84 row_bcast:31 row_mask:0xc bank_mask:0xf
	v_lshlrev_b32_e32 v172, 16, v50
	v_and_b32_e32 v173, 0xffff0000, v50
	v_lshlrev_b32_e32 v174, 16, v51
	v_and_b32_e32 v175, 0xffff0000, v51
	s_nop 0
	v_readlane_b32 s83, v84, 63
	s_nop 2
	v_fma_f32 v84, s83, v2, v3
	v_rsq_f32_e32 v84, v84
	s_nop 0
	v_mul_f32_e32 v68, v68, v84
	v_mul_f32_e32 v69, v69, v84
	v_mul_f32_e32 v70, v70, v84
	v_mul_f32_e32 v71, v71, v84
	v_mul_f32_e32 v72, v72, v84
	v_mul_f32_e32 v73, v73, v84
	v_mul_f32_e32 v74, v74, v84
	v_mul_f32_e32 v75, v75, v84
	v_mul_f32_e32 v76, v76, v84
	v_mul_f32_e32 v77, v77, v84
	v_mul_f32_e32 v78, v78, v84
	v_mul_f32_e32 v79, v79, v84
	v_mul_f32_e32 v80, v80, v84
	v_mul_f32_e32 v81, v81, v84
	v_mul_f32_e32 v82, v82, v84
	v_mul_f32_e32 v83, v83, v84
	v_fma_f32 v68, v68, v4, v160
	v_fma_f32 v69, v69, v5, v161
	v_fma_f32 v70, v70, v6, v162
	v_fma_f32 v71, v71, v7, v163
	v_fma_f32 v72, v72, v8, v164
	v_fma_f32 v73, v73, v9, v165
	v_fma_f32 v74, v74, v10, v166
	v_fma_f32 v75, v75, v11, v167
	v_fma_f32 v76, v76, v12, v168
	v_fma_f32 v77, v77, v13, v169
	v_fma_f32 v78, v78, v14, v170
	v_fma_f32 v79, v79, v15, v171
	v_fma_f32 v80, v80, v16, v172
	v_fma_f32 v81, v81, v17, v173
	v_fma_f32 v82, v82, v18, v174
	v_fma_f32 v83, v83, v19, v175
	v_mul_f32_e32 v86, v68, v68
	v_mul_f32_e32 v87, v72, v72
	v_mul_f32_e32 v88, v76, v76
	v_mul_f32_e32 v89, v80, v80
	v_fmac_f32_e32 v86, v69, v69
	v_fmac_f32_e32 v87, v73, v73
	v_fmac_f32_e32 v88, v77, v77
	v_fmac_f32_e32 v89, v81, v81
	v_fmac_f32_e32 v86, v70, v70
	v_fmac_f32_e32 v87, v74, v74
	v_fmac_f32_e32 v88, v78, v78
	v_fmac_f32_e32 v89, v82, v82
	v_fmac_f32_e32 v86, v71, v71
	v_fmac_f32_e32 v87, v75, v75
	v_fmac_f32_e32 v88, v79, v79
	v_fmac_f32_e32 v89, v83, v83
	v_add_f32_e32 v85, v86, v87
	v_add_f32_e32 v85, v85, v88
	v_add_f32_e32 v85, v85, v89
	v_cvt_pk_bf16_f32 v90, v68, v69
	v_cvt_pk_bf16_f32 v91, v70, v71
	v_add_f32_dpp v85, v85, v85 quad_perm:[1,0,3,2] row_mask:0xf bank_mask:0xf
	v_cvt_pk_bf16_f32 v92, v72, v73
	v_cvt_pk_bf16_f32 v93, v74, v75
	v_add_f32_dpp v85, v85, v85 quad_perm:[2,3,0,1] row_mask:0xf bank_mask:0xf
	v_cvt_pk_bf16_f32 v94, v76, v77
	v_cvt_pk_bf16_f32 v95, v78, v79
	v_add_f32_dpp v85, v85, v85 row_half_mirror row_mask:0xf bank_mask:0xf
	v_cvt_pk_bf16_f32 v96, v80, v81
	v_cvt_pk_bf16_f32 v97, v82, v83
	v_add_f32_dpp v85, v85, v85 row_mirror row_mask:0xf bank_mask:0xf
	s_nop 1
	v_add_f32_dpp v85, v85, v85 row_bcast:15 row_mask:0xa bank_mask:0xf
	s_nop 1
	v_add_f32_dpp v85, v85, v85 row_bcast:31 row_mask:0xc bank_mask:0xf
	global_store_dwordx2 v1, v[90:91], s[74:75] offset:0
	global_store_dwordx2 v1, v[92:93], s[74:75] offset:512
	global_store_dwordx2 v1, v[94:95], s[74:75] offset:1024
	global_store_dwordx2 v1, v[96:97], s[74:75] offset:1536
	v_readlane_b32 s84, v85, 63
	s_add_u32 s74, s74, 0x400000
	s_addc_u32 s75, s75, 0
	s_nop 0
	v_fma_f32 v85, s84, v2, v3
	v_rsq_f32_e32 v85, v85
	s_nop 0
	v_mul_f32_e32 v68, v68, v85
	v_mul_f32_e32 v69, v69, v85
	v_mul_f32_e32 v70, v70, v85
	v_mul_f32_e32 v71, v71, v85
	v_mul_f32_e32 v72, v72, v85
	v_mul_f32_e32 v73, v73, v85
	v_mul_f32_e32 v74, v74, v85
	v_mul_f32_e32 v75, v75, v85
	v_mul_f32_e32 v76, v76, v85
	v_mul_f32_e32 v77, v77, v85
	v_mul_f32_e32 v78, v78, v85
	v_mul_f32_e32 v79, v79, v85
	v_mul_f32_e32 v80, v80, v85
	v_mul_f32_e32 v81, v81, v85
	v_mul_f32_e32 v82, v82, v85
	v_mul_f32_e32 v83, v83, v85
	v_mul_f32_e32 v68, v68, v100
	v_mul_f32_e32 v69, v69, v101
	v_mul_f32_e32 v70, v70, v102
	v_mul_f32_e32 v71, v71, v103
	v_mul_f32_e32 v72, v72, v104
	v_mul_f32_e32 v73, v73, v105
	v_mul_f32_e32 v74, v74, v106
	v_mul_f32_e32 v75, v75, v107
	v_mul_f32_e32 v76, v76, v108
	v_mul_f32_e32 v77, v77, v109
	v_mul_f32_e32 v78, v78, v110
	v_mul_f32_e32 v79, v79, v111
	v_mul_f32_e32 v80, v80, v112
	v_mul_f32_e32 v81, v81, v113
	v_mul_f32_e32 v82, v82, v114
	v_mul_f32_e32 v83, v83, v115
	v_cvt_pk_bf16_f32 v176, v68, v69
	v_cvt_pk_bf16_f32 v177, v70, v71
	v_cvt_pk_bf16_f32 v178, v72, v73
	v_cvt_pk_bf16_f32 v179, v74, v75
	v_cvt_pk_bf16_f32 v180, v76, v77
	v_cvt_pk_bf16_f32 v181, v78, v79
	v_cvt_pk_bf16_f32 v182, v80, v81
	v_cvt_pk_bf16_f32 v183, v82, v83
	global_store_dwordx2 v1, v[176:177], s[76:77] offset:0
	global_store_dwordx2 v1, v[178:179], s[76:77] offset:512
	global_store_dwordx2 v1, v[180:181], s[76:77] offset:1024
	global_store_dwordx2 v1, v[182:183], s[76:77] offset:1536
	s_add_u32 s76, s76, 0x400000
	s_addc_u32 s77, s77, 0
	global_load_dwordx2 v[36:37], v1, s[70:71] offset:0
	global_load_dwordx2 v[38:39], v1, s[70:71] offset:512
	global_load_dwordx2 v[40:41], v1, s[70:71] offset:1024
	global_load_dwordx2 v[42:43], v1, s[70:71] offset:1536
	global_load_dwordx2 v[44:45], v1, s[72:73] offset:0
	global_load_dwordx2 v[46:47], v1, s[72:73] offset:512
	global_load_dwordx2 v[48:49], v1, s[72:73] offset:1024
	global_load_dwordx2 v[50:51], v1, s[72:73] offset:1536
	s_add_u32 s70, s70, 0x400000
	s_addc_u32 s71, s71, 0
	s_add_u32 s72, s72, 0x400000
	s_addc_u32 s73, s73, 0
	s_waitcnt vmcnt(32)
	v_lshlrev_b32_e32 v68, 16, v52
	v_and_b32_e32 v69, 0xffff0000, v52
	v_lshlrev_b32_e32 v70, 16, v53
	v_and_b32_e32 v71, 0xffff0000, v53
	v_lshlrev_b32_e32 v72, 16, v54
	v_and_b32_e32 v73, 0xffff0000, v54
	v_lshlrev_b32_e32 v74, 16, v55
	v_and_b32_e32 v75, 0xffff0000, v55
	v_lshlrev_b32_e32 v76, 16, v56
	v_and_b32_e32 v77, 0xffff0000, v56
	v_lshlrev_b32_e32 v78, 16, v57
	v_and_b32_e32 v79, 0xffff0000, v57
	v_lshlrev_b32_e32 v80, 16, v58
	v_and_b32_e32 v81, 0xffff0000, v58
	v_lshlrev_b32_e32 v82, 16, v59
	v_and_b32_e32 v83, 0xffff0000, v59
	v_mul_f32_e32 v86, v68, v68
	v_mul_f32_e32 v87, v72, v72
	v_mul_f32_e32 v88, v76, v76
	v_mul_f32_e32 v89, v80, v80
	v_fmac_f32_e32 v86, v69, v69
	v_fmac_f32_e32 v87, v73, v73
	v_fmac_f32_e32 v88, v77, v77
	v_fmac_f32_e32 v89, v81, v81
	v_fmac_f32_e32 v86, v70, v70
	v_fmac_f32_e32 v87, v74, v74
	v_fmac_f32_e32 v88, v78, v78
	v_fmac_f32_e32 v89, v82, v82
	v_fmac_f32_e32 v86, v71, v71
	v_fmac_f32_e32 v87, v75, v75
	v_fmac_f32_e32 v88, v79, v79
	v_fmac_f32_e32 v89, v83, v83
	v_add_f32_e32 v84, v86, v87
	v_add_f32_e32 v84, v84, v88
	v_add_f32_e32 v84, v84, v89
	v_lshlrev_b32_e32 v160, 16, v60
	v_and_b32_e32 v161, 0xffff0000, v60
	v_add_f32_dpp v84, v84, v84 quad_perm:[1,0,3,2] row_mask:0xf bank_mask:0xf
	v_lshlrev_b32_e32 v162, 16, v61
	v_and_b32_e32 v163, 0xffff0000, v61
	v_add_f32_dpp v84, v84, v84 quad_perm:[2,3,0,1] row_mask:0xf bank_mask:0xf
	v_lshlrev_b32_e32 v164, 16, v62
	v_and_b32_e32 v165, 0xffff0000, v62
	v_add_f32_dpp v84, v84, v84 row_half_mirror row_mask:0xf bank_mask:0xf
	v_lshlrev_b32_e32 v166, 16, v63
	v_and_b32_e32 v167, 0xffff0000, v63
	v_add_f32_dpp v84, v84, v84 row_mirror row_mask:0xf bank_mask:0xf
	v_lshlrev_b32_e32 v168, 16, v64
	v_and_b32_e32 v169, 0xffff0000, v64
	v_add_f32_dpp v84, v84, v84 row_bcast:15 row_mask:0xa bank_mask:0xf
	v_lshlrev_b32_e32 v170, 16, v65
	v_and_b32_e32 v171, 0xffff0000, v65
	v_add_f32_dpp v84, v84, v84 row_bcast:31 row_mask:0xc bank_mask:0xf
	v_lshlrev_b32_e32 v172, 16, v66
	v_and_b32_e32 v173, 0xffff0000, v66
	v_lshlrev_b32_e32 v174, 16, v67
	v_and_b32_e32 v175, 0xffff0000, v67
	s_nop 0
	v_readlane_b32 s83, v84, 63
	s_nop 2
	v_fma_f32 v84, s83, v2, v3
	v_rsq_f32_e32 v84, v84
	s_nop 0
	v_mul_f32_e32 v68, v68, v84
	v_mul_f32_e32 v69, v69, v84
	v_mul_f32_e32 v70, v70, v84
	v_mul_f32_e32 v71, v71, v84
	v_mul_f32_e32 v72, v72, v84
	v_mul_f32_e32 v73, v73, v84
	v_mul_f32_e32 v74, v74, v84
	v_mul_f32_e32 v75, v75, v84
	v_mul_f32_e32 v76, v76, v84
	v_mul_f32_e32 v77, v77, v84
	v_mul_f32_e32 v78, v78, v84
	v_mul_f32_e32 v79, v79, v84
	v_mul_f32_e32 v80, v80, v84
	v_mul_f32_e32 v81, v81, v84
	v_mul_f32_e32 v82, v82, v84
	v_mul_f32_e32 v83, v83, v84
	v_fma_f32 v68, v68, v4, v160
	v_fma_f32 v69, v69, v5, v161
	v_fma_f32 v70, v70, v6, v162
	v_fma_f32 v71, v71, v7, v163
	v_fma_f32 v72, v72, v8, v164
	v_fma_f32 v73, v73, v9, v165
	v_fma_f32 v74, v74, v10, v166
	v_fma_f32 v75, v75, v11, v167
	v_fma_f32 v76, v76, v12, v168
	v_fma_f32 v77, v77, v13, v169
	v_fma_f32 v78, v78, v14, v170
	v_fma_f32 v79, v79, v15, v171
	v_fma_f32 v80, v80, v16, v172
	v_fma_f32 v81, v81, v17, v173
	v_fma_f32 v82, v82, v18, v174
	v_fma_f32 v83, v83, v19, v175
	v_mul_f32_e32 v86, v68, v68
	v_mul_f32_e32 v87, v72, v72
	v_mul_f32_e32 v88, v76, v76
	v_mul_f32_e32 v89, v80, v80
	v_fmac_f32_e32 v86, v69, v69
	v_fmac_f32_e32 v87, v73, v73
	v_fmac_f32_e32 v88, v77, v77
	v_fmac_f32_e32 v89, v81, v81
	v_fmac_f32_e32 v86, v70, v70
	v_fmac_f32_e32 v87, v74, v74
	v_fmac_f32_e32 v88, v78, v78
	v_fmac_f32_e32 v89, v82, v82
	v_fmac_f32_e32 v86, v71, v71
	v_fmac_f32_e32 v87, v75, v75
	v_fmac_f32_e32 v88, v79, v79
	v_fmac_f32_e32 v89, v83, v83
	v_add_f32_e32 v85, v86, v87
	v_add_f32_e32 v85, v85, v88
	v_add_f32_e32 v85, v85, v89
	v_cvt_pk_bf16_f32 v90, v68, v69
	v_cvt_pk_bf16_f32 v91, v70, v71
	v_add_f32_dpp v85, v85, v85 quad_perm:[1,0,3,2] row_mask:0xf bank_mask:0xf
	v_cvt_pk_bf16_f32 v92, v72, v73
	v_cvt_pk_bf16_f32 v93, v74, v75
	v_add_f32_dpp v85, v85, v85 quad_perm:[2,3,0,1] row_mask:0xf bank_mask:0xf
	v_cvt_pk_bf16_f32 v94, v76, v77
	v_cvt_pk_bf16_f32 v95, v78, v79
	v_add_f32_dpp v85, v85, v85 row_half_mirror row_mask:0xf bank_mask:0xf
	v_cvt_pk_bf16_f32 v96, v80, v81
	v_cvt_pk_bf16_f32 v97, v82, v83
	v_add_f32_dpp v85, v85, v85 row_mirror row_mask:0xf bank_mask:0xf
	s_nop 1
	v_add_f32_dpp v85, v85, v85 row_bcast:15 row_mask:0xa bank_mask:0xf
	s_nop 1
	v_add_f32_dpp v85, v85, v85 row_bcast:31 row_mask:0xc bank_mask:0xf
	global_store_dwordx2 v1, v[90:91], s[74:75] offset:0
	global_store_dwordx2 v1, v[92:93], s[74:75] offset:512
	global_store_dwordx2 v1, v[94:95], s[74:75] offset:1024
	global_store_dwordx2 v1, v[96:97], s[74:75] offset:1536
	v_readlane_b32 s84, v85, 63
	s_add_u32 s74, s74, 0x400000
	s_addc_u32 s75, s75, 0
	s_nop 0
	v_fma_f32 v85, s84, v2, v3
	v_rsq_f32_e32 v85, v85
	s_nop 0
	v_mul_f32_e32 v68, v68, v85
	v_mul_f32_e32 v69, v69, v85
	v_mul_f32_e32 v70, v70, v85
	v_mul_f32_e32 v71, v71, v85
	v_mul_f32_e32 v72, v72, v85
	v_mul_f32_e32 v73, v73, v85
	v_mul_f32_e32 v74, v74, v85
	v_mul_f32_e32 v75, v75, v85
	v_mul_f32_e32 v76, v76, v85
	v_mul_f32_e32 v77, v77, v85
	v_mul_f32_e32 v78, v78, v85
	v_mul_f32_e32 v79, v79, v85
	v_mul_f32_e32 v80, v80, v85
	v_mul_f32_e32 v81, v81, v85
	v_mul_f32_e32 v82, v82, v85
	v_mul_f32_e32 v83, v83, v85
	v_mul_f32_e32 v68, v68, v100
	v_mul_f32_e32 v69, v69, v101
	v_mul_f32_e32 v70, v70, v102
	v_mul_f32_e32 v71, v71, v103
	v_mul_f32_e32 v72, v72, v104
	v_mul_f32_e32 v73, v73, v105
	v_mul_f32_e32 v74, v74, v106
	v_mul_f32_e32 v75, v75, v107
	v_mul_f32_e32 v76, v76, v108
	v_mul_f32_e32 v77, v77, v109
	v_mul_f32_e32 v78, v78, v110
	v_mul_f32_e32 v79, v79, v111
	v_mul_f32_e32 v80, v80, v112
	v_mul_f32_e32 v81, v81, v113
	v_mul_f32_e32 v82, v82, v114
	v_mul_f32_e32 v83, v83, v115
	v_cvt_pk_bf16_f32 v176, v68, v69
	v_cvt_pk_bf16_f32 v177, v70, v71
	v_cvt_pk_bf16_f32 v178, v72, v73
	v_cvt_pk_bf16_f32 v179, v74, v75
	v_cvt_pk_bf16_f32 v180, v76, v77
	v_cvt_pk_bf16_f32 v181, v78, v79
	v_cvt_pk_bf16_f32 v182, v80, v81
	v_cvt_pk_bf16_f32 v183, v82, v83
	global_store_dwordx2 v1, v[176:177], s[76:77] offset:0
	global_store_dwordx2 v1, v[178:179], s[76:77] offset:512
	global_store_dwordx2 v1, v[180:181], s[76:77] offset:1024
	global_store_dwordx2 v1, v[182:183], s[76:77] offset:1536
	s_add_u32 s76, s76, 0x400000
	s_addc_u32 s77, s77, 0
	global_load_dwordx2 v[52:53], v1, s[70:71] offset:0
	global_load_dwordx2 v[54:55], v1, s[70:71] offset:512
	global_load_dwordx2 v[56:57], v1, s[70:71] offset:1024
	global_load_dwordx2 v[58:59], v1, s[70:71] offset:1536
	global_load_dwordx2 v[60:61], v1, s[72:73] offset:0
	global_load_dwordx2 v[62:63], v1, s[72:73] offset:512
	global_load_dwordx2 v[64:65], v1, s[72:73] offset:1024
	global_load_dwordx2 v[66:67], v1, s[72:73] offset:1536
	s_add_u32 s70, s70, 0x400000
	s_addc_u32 s71, s71, 0
	s_add_u32 s72, s72, 0x400000
	s_addc_u32 s73, s73, 0
	s_waitcnt vmcnt(32)
	v_lshlrev_b32_e32 v68, 16, v20
	v_and_b32_e32 v69, 0xffff0000, v20
	v_lshlrev_b32_e32 v70, 16, v21
	v_and_b32_e32 v71, 0xffff0000, v21
	v_lshlrev_b32_e32 v72, 16, v22
	v_and_b32_e32 v73, 0xffff0000, v22
	v_lshlrev_b32_e32 v74, 16, v23
	v_and_b32_e32 v75, 0xffff0000, v23
	v_lshlrev_b32_e32 v76, 16, v24
	v_and_b32_e32 v77, 0xffff0000, v24
	v_lshlrev_b32_e32 v78, 16, v25
	v_and_b32_e32 v79, 0xffff0000, v25
	v_lshlrev_b32_e32 v80, 16, v26
	v_and_b32_e32 v81, 0xffff0000, v26
	v_lshlrev_b32_e32 v82, 16, v27
	v_and_b32_e32 v83, 0xffff0000, v27
	v_mul_f32_e32 v86, v68, v68
	v_mul_f32_e32 v87, v72, v72
	v_mul_f32_e32 v88, v76, v76
	v_mul_f32_e32 v89, v80, v80
	v_fmac_f32_e32 v86, v69, v69
	v_fmac_f32_e32 v87, v73, v73
	v_fmac_f32_e32 v88, v77, v77
	v_fmac_f32_e32 v89, v81, v81
	v_fmac_f32_e32 v86, v70, v70
	v_fmac_f32_e32 v87, v74, v74
	v_fmac_f32_e32 v88, v78, v78
	v_fmac_f32_e32 v89, v82, v82
	v_fmac_f32_e32 v86, v71, v71
	v_fmac_f32_e32 v87, v75, v75
	v_fmac_f32_e32 v88, v79, v79
	v_fmac_f32_e32 v89, v83, v83
	v_add_f32_e32 v84, v86, v87
	v_add_f32_e32 v84, v84, v88
	v_add_f32_e32 v84, v84, v89
	v_lshlrev_b32_e32 v160, 16, v28
	v_and_b32_e32 v161, 0xffff0000, v28
	v_add_f32_dpp v84, v84, v84 quad_perm:[1,0,3,2] row_mask:0xf bank_mask:0xf
	v_lshlrev_b32_e32 v162, 16, v29
	v_and_b32_e32 v163, 0xffff0000, v29
	v_add_f32_dpp v84, v84, v84 quad_perm:[2,3,0,1] row_mask:0xf bank_mask:0xf
	v_lshlrev_b32_e32 v164, 16, v30
	v_and_b32_e32 v165, 0xffff0000, v30
	v_add_f32_dpp v84, v84, v84 row_half_mirror row_mask:0xf bank_mask:0xf
	v_lshlrev_b32_e32 v166, 16, v31
	v_and_b32_e32 v167, 0xffff0000, v31
	v_add_f32_dpp v84, v84, v84 row_mirror row_mask:0xf bank_mask:0xf
	v_lshlrev_b32_e32 v168, 16, v32
	v_and_b32_e32 v169, 0xffff0000, v32
	v_add_f32_dpp v84, v84, v84 row_bcast:15 row_mask:0xa bank_mask:0xf
	v_lshlrev_b32_e32 v170, 16, v33
	v_and_b32_e32 v171, 0xffff0000, v33
	v_add_f32_dpp v84, v84, v84 row_bcast:31 row_mask:0xc bank_mask:0xf
	v_lshlrev_b32_e32 v172, 16, v34
	v_and_b32_e32 v173, 0xffff0000, v34
	v_lshlrev_b32_e32 v174, 16, v35
	v_and_b32_e32 v175, 0xffff0000, v35
	s_nop 0
	v_readlane_b32 s83, v84, 63
	s_nop 2
	v_fma_f32 v84, s83, v2, v3
	v_rsq_f32_e32 v84, v84
	s_nop 0
	v_mul_f32_e32 v68, v68, v84
	v_mul_f32_e32 v69, v69, v84
	v_mul_f32_e32 v70, v70, v84
	v_mul_f32_e32 v71, v71, v84
	v_mul_f32_e32 v72, v72, v84
	v_mul_f32_e32 v73, v73, v84
	v_mul_f32_e32 v74, v74, v84
	v_mul_f32_e32 v75, v75, v84
	v_mul_f32_e32 v76, v76, v84
	v_mul_f32_e32 v77, v77, v84
	v_mul_f32_e32 v78, v78, v84
	v_mul_f32_e32 v79, v79, v84
	v_mul_f32_e32 v80, v80, v84
	v_mul_f32_e32 v81, v81, v84
	v_mul_f32_e32 v82, v82, v84
	v_mul_f32_e32 v83, v83, v84
	v_fma_f32 v68, v68, v4, v160
	v_fma_f32 v69, v69, v5, v161
	v_fma_f32 v70, v70, v6, v162
	v_fma_f32 v71, v71, v7, v163
	v_fma_f32 v72, v72, v8, v164
	v_fma_f32 v73, v73, v9, v165
	v_fma_f32 v74, v74, v10, v166
	v_fma_f32 v75, v75, v11, v167
	v_fma_f32 v76, v76, v12, v168
	v_fma_f32 v77, v77, v13, v169
	v_fma_f32 v78, v78, v14, v170
	v_fma_f32 v79, v79, v15, v171
	v_fma_f32 v80, v80, v16, v172
	v_fma_f32 v81, v81, v17, v173
	v_fma_f32 v82, v82, v18, v174
	v_fma_f32 v83, v83, v19, v175
	v_mul_f32_e32 v86, v68, v68
	v_mul_f32_e32 v87, v72, v72
	v_mul_f32_e32 v88, v76, v76
	v_mul_f32_e32 v89, v80, v80
	v_fmac_f32_e32 v86, v69, v69
	v_fmac_f32_e32 v87, v73, v73
	v_fmac_f32_e32 v88, v77, v77
	v_fmac_f32_e32 v89, v81, v81
	v_fmac_f32_e32 v86, v70, v70
	v_fmac_f32_e32 v87, v74, v74
	v_fmac_f32_e32 v88, v78, v78
	v_fmac_f32_e32 v89, v82, v82
	v_fmac_f32_e32 v86, v71, v71
	v_fmac_f32_e32 v87, v75, v75
	v_fmac_f32_e32 v88, v79, v79
	v_fmac_f32_e32 v89, v83, v83
	v_add_f32_e32 v85, v86, v87
	v_add_f32_e32 v85, v85, v88
	v_add_f32_e32 v85, v85, v89
	v_cvt_pk_bf16_f32 v90, v68, v69
	v_cvt_pk_bf16_f32 v91, v70, v71
	v_add_f32_dpp v85, v85, v85 quad_perm:[1,0,3,2] row_mask:0xf bank_mask:0xf
	v_cvt_pk_bf16_f32 v92, v72, v73
	v_cvt_pk_bf16_f32 v93, v74, v75
	v_add_f32_dpp v85, v85, v85 quad_perm:[2,3,0,1] row_mask:0xf bank_mask:0xf
	v_cvt_pk_bf16_f32 v94, v76, v77
	v_cvt_pk_bf16_f32 v95, v78, v79
	v_add_f32_dpp v85, v85, v85 row_half_mirror row_mask:0xf bank_mask:0xf
	v_cvt_pk_bf16_f32 v96, v80, v81
	v_cvt_pk_bf16_f32 v97, v82, v83
	v_add_f32_dpp v85, v85, v85 row_mirror row_mask:0xf bank_mask:0xf
	s_nop 1
	v_add_f32_dpp v85, v85, v85 row_bcast:15 row_mask:0xa bank_mask:0xf
	s_nop 1
	v_add_f32_dpp v85, v85, v85 row_bcast:31 row_mask:0xc bank_mask:0xf
	global_store_dwordx2 v1, v[90:91], s[74:75] offset:0
	global_store_dwordx2 v1, v[92:93], s[74:75] offset:512
	global_store_dwordx2 v1, v[94:95], s[74:75] offset:1024
	global_store_dwordx2 v1, v[96:97], s[74:75] offset:1536
	v_readlane_b32 s84, v85, 63
	s_add_u32 s74, s74, 0x400000
	s_addc_u32 s75, s75, 0
	s_nop 0
	v_fma_f32 v85, s84, v2, v3
	v_rsq_f32_e32 v85, v85
	s_nop 0
	v_mul_f32_e32 v68, v68, v85
	v_mul_f32_e32 v69, v69, v85
	v_mul_f32_e32 v70, v70, v85
	v_mul_f32_e32 v71, v71, v85
	v_mul_f32_e32 v72, v72, v85
	v_mul_f32_e32 v73, v73, v85
	v_mul_f32_e32 v74, v74, v85
	v_mul_f32_e32 v75, v75, v85
	v_mul_f32_e32 v76, v76, v85
	v_mul_f32_e32 v77, v77, v85
	v_mul_f32_e32 v78, v78, v85
	v_mul_f32_e32 v79, v79, v85
	v_mul_f32_e32 v80, v80, v85
	v_mul_f32_e32 v81, v81, v85
	v_mul_f32_e32 v82, v82, v85
	v_mul_f32_e32 v83, v83, v85
	v_mul_f32_e32 v68, v68, v100
	v_mul_f32_e32 v69, v69, v101
	v_mul_f32_e32 v70, v70, v102
	v_mul_f32_e32 v71, v71, v103
	v_mul_f32_e32 v72, v72, v104
	v_mul_f32_e32 v73, v73, v105
	v_mul_f32_e32 v74, v74, v106
	v_mul_f32_e32 v75, v75, v107
	v_mul_f32_e32 v76, v76, v108
	v_mul_f32_e32 v77, v77, v109
	v_mul_f32_e32 v78, v78, v110
	v_mul_f32_e32 v79, v79, v111
	v_mul_f32_e32 v80, v80, v112
	v_mul_f32_e32 v81, v81, v113
	v_mul_f32_e32 v82, v82, v114
	v_mul_f32_e32 v83, v83, v115
	v_cvt_pk_bf16_f32 v176, v68, v69
	v_cvt_pk_bf16_f32 v177, v70, v71
	v_cvt_pk_bf16_f32 v178, v72, v73
	v_cvt_pk_bf16_f32 v179, v74, v75
	v_cvt_pk_bf16_f32 v180, v76, v77
	v_cvt_pk_bf16_f32 v181, v78, v79
	v_cvt_pk_bf16_f32 v182, v80, v81
	v_cvt_pk_bf16_f32 v183, v82, v83
	global_store_dwordx2 v1, v[176:177], s[76:77] offset:0
	global_store_dwordx2 v1, v[178:179], s[76:77] offset:512
	global_store_dwordx2 v1, v[180:181], s[76:77] offset:1024
	global_store_dwordx2 v1, v[182:183], s[76:77] offset:1536
	s_add_u32 s76, s76, 0x400000
	s_addc_u32 s77, s77, 0
	global_load_dwordx2 v[20:21], v1, s[70:71] offset:0
	global_load_dwordx2 v[22:23], v1, s[70:71] offset:512
	global_load_dwordx2 v[24:25], v1, s[70:71] offset:1024
	global_load_dwordx2 v[26:27], v1, s[70:71] offset:1536
	global_load_dwordx2 v[28:29], v1, s[72:73] offset:0
	global_load_dwordx2 v[30:31], v1, s[72:73] offset:512
	global_load_dwordx2 v[32:33], v1, s[72:73] offset:1024
	global_load_dwordx2 v[34:35], v1, s[72:73] offset:1536
	s_add_u32 s70, s70, 0x400000
	s_addc_u32 s71, s71, 0
	s_add_u32 s72, s72, 0x400000
	s_addc_u32 s73, s73, 0
	s_waitcnt vmcnt(32)
	v_lshlrev_b32_e32 v68, 16, v36
	v_and_b32_e32 v69, 0xffff0000, v36
	v_lshlrev_b32_e32 v70, 16, v37
	v_and_b32_e32 v71, 0xffff0000, v37
	v_lshlrev_b32_e32 v72, 16, v38
	v_and_b32_e32 v73, 0xffff0000, v38
	v_lshlrev_b32_e32 v74, 16, v39
	v_and_b32_e32 v75, 0xffff0000, v39
	v_lshlrev_b32_e32 v76, 16, v40
	v_and_b32_e32 v77, 0xffff0000, v40
	v_lshlrev_b32_e32 v78, 16, v41
	v_and_b32_e32 v79, 0xffff0000, v41
	v_lshlrev_b32_e32 v80, 16, v42
	v_and_b32_e32 v81, 0xffff0000, v42
	v_lshlrev_b32_e32 v82, 16, v43
	v_and_b32_e32 v83, 0xffff0000, v43
	v_mul_f32_e32 v86, v68, v68
	v_mul_f32_e32 v87, v72, v72
	v_mul_f32_e32 v88, v76, v76
	v_mul_f32_e32 v89, v80, v80
	v_fmac_f32_e32 v86, v69, v69
	v_fmac_f32_e32 v87, v73, v73
	v_fmac_f32_e32 v88, v77, v77
	v_fmac_f32_e32 v89, v81, v81
	v_fmac_f32_e32 v86, v70, v70
	v_fmac_f32_e32 v87, v74, v74
	v_fmac_f32_e32 v88, v78, v78
	v_fmac_f32_e32 v89, v82, v82
	v_fmac_f32_e32 v86, v71, v71
	v_fmac_f32_e32 v87, v75, v75
	v_fmac_f32_e32 v88, v79, v79
	v_fmac_f32_e32 v89, v83, v83
	v_add_f32_e32 v84, v86, v87
	v_add_f32_e32 v84, v84, v88
	v_add_f32_e32 v84, v84, v89
	v_lshlrev_b32_e32 v160, 16, v44
	v_and_b32_e32 v161, 0xffff0000, v44
	v_add_f32_dpp v84, v84, v84 quad_perm:[1,0,3,2] row_mask:0xf bank_mask:0xf
	v_lshlrev_b32_e32 v162, 16, v45
	v_and_b32_e32 v163, 0xffff0000, v45
	v_add_f32_dpp v84, v84, v84 quad_perm:[2,3,0,1] row_mask:0xf bank_mask:0xf
	v_lshlrev_b32_e32 v164, 16, v46
	v_and_b32_e32 v165, 0xffff0000, v46
	v_add_f32_dpp v84, v84, v84 row_half_mirror row_mask:0xf bank_mask:0xf
	v_lshlrev_b32_e32 v166, 16, v47
	v_and_b32_e32 v167, 0xffff0000, v47
	v_add_f32_dpp v84, v84, v84 row_mirror row_mask:0xf bank_mask:0xf
	v_lshlrev_b32_e32 v168, 16, v48
	v_and_b32_e32 v169, 0xffff0000, v48
	v_add_f32_dpp v84, v84, v84 row_bcast:15 row_mask:0xa bank_mask:0xf
	v_lshlrev_b32_e32 v170, 16, v49
	v_and_b32_e32 v171, 0xffff0000, v49
	v_add_f32_dpp v84, v84, v84 row_bcast:31 row_mask:0xc bank_mask:0xf
	v_lshlrev_b32_e32 v172, 16, v50
	v_and_b32_e32 v173, 0xffff0000, v50
	v_lshlrev_b32_e32 v174, 16, v51
	v_and_b32_e32 v175, 0xffff0000, v51
	s_nop 0
	v_readlane_b32 s83, v84, 63
	s_nop 2
	v_fma_f32 v84, s83, v2, v3
	v_rsq_f32_e32 v84, v84
	s_nop 0
	v_mul_f32_e32 v68, v68, v84
	v_mul_f32_e32 v69, v69, v84
	v_mul_f32_e32 v70, v70, v84
	v_mul_f32_e32 v71, v71, v84
	v_mul_f32_e32 v72, v72, v84
	v_mul_f32_e32 v73, v73, v84
	v_mul_f32_e32 v74, v74, v84
	v_mul_f32_e32 v75, v75, v84
	v_mul_f32_e32 v76, v76, v84
	v_mul_f32_e32 v77, v77, v84
	v_mul_f32_e32 v78, v78, v84
	v_mul_f32_e32 v79, v79, v84
	v_mul_f32_e32 v80, v80, v84
	v_mul_f32_e32 v81, v81, v84
	v_mul_f32_e32 v82, v82, v84
	v_mul_f32_e32 v83, v83, v84
	v_fma_f32 v68, v68, v4, v160
	v_fma_f32 v69, v69, v5, v161
	v_fma_f32 v70, v70, v6, v162
	v_fma_f32 v71, v71, v7, v163
	v_fma_f32 v72, v72, v8, v164
	v_fma_f32 v73, v73, v9, v165
	v_fma_f32 v74, v74, v10, v166
	v_fma_f32 v75, v75, v11, v167
	v_fma_f32 v76, v76, v12, v168
	v_fma_f32 v77, v77, v13, v169
	v_fma_f32 v78, v78, v14, v170
	v_fma_f32 v79, v79, v15, v171
	v_fma_f32 v80, v80, v16, v172
	v_fma_f32 v81, v81, v17, v173
	v_fma_f32 v82, v82, v18, v174
	v_fma_f32 v83, v83, v19, v175
	v_mul_f32_e32 v86, v68, v68
	v_mul_f32_e32 v87, v72, v72
	v_mul_f32_e32 v88, v76, v76
	v_mul_f32_e32 v89, v80, v80
	v_fmac_f32_e32 v86, v69, v69
	v_fmac_f32_e32 v87, v73, v73
	v_fmac_f32_e32 v88, v77, v77
	v_fmac_f32_e32 v89, v81, v81
	v_fmac_f32_e32 v86, v70, v70
	v_fmac_f32_e32 v87, v74, v74
	v_fmac_f32_e32 v88, v78, v78
	v_fmac_f32_e32 v89, v82, v82
	v_fmac_f32_e32 v86, v71, v71
	v_fmac_f32_e32 v87, v75, v75
	v_fmac_f32_e32 v88, v79, v79
	v_fmac_f32_e32 v89, v83, v83
	v_add_f32_e32 v85, v86, v87
	v_add_f32_e32 v85, v85, v88
	v_add_f32_e32 v85, v85, v89
	v_cvt_pk_bf16_f32 v90, v68, v69
	v_cvt_pk_bf16_f32 v91, v70, v71
	v_add_f32_dpp v85, v85, v85 quad_perm:[1,0,3,2] row_mask:0xf bank_mask:0xf
	v_cvt_pk_bf16_f32 v92, v72, v73
	v_cvt_pk_bf16_f32 v93, v74, v75
	v_add_f32_dpp v85, v85, v85 quad_perm:[2,3,0,1] row_mask:0xf bank_mask:0xf
	v_cvt_pk_bf16_f32 v94, v76, v77
	v_cvt_pk_bf16_f32 v95, v78, v79
	v_add_f32_dpp v85, v85, v85 row_half_mirror row_mask:0xf bank_mask:0xf
	v_cvt_pk_bf16_f32 v96, v80, v81
	v_cvt_pk_bf16_f32 v97, v82, v83
	v_add_f32_dpp v85, v85, v85 row_mirror row_mask:0xf bank_mask:0xf
	s_nop 1
	v_add_f32_dpp v85, v85, v85 row_bcast:15 row_mask:0xa bank_mask:0xf
	s_nop 1
	v_add_f32_dpp v85, v85, v85 row_bcast:31 row_mask:0xc bank_mask:0xf
	global_store_dwordx2 v1, v[90:91], s[74:75] offset:0
	global_store_dwordx2 v1, v[92:93], s[74:75] offset:512
	global_store_dwordx2 v1, v[94:95], s[74:75] offset:1024
	global_store_dwordx2 v1, v[96:97], s[74:75] offset:1536
	v_readlane_b32 s84, v85, 63
	s_add_u32 s74, s74, 0x400000
	s_addc_u32 s75, s75, 0
	s_nop 0
	v_fma_f32 v85, s84, v2, v3
	v_rsq_f32_e32 v85, v85
	s_nop 0
	v_mul_f32_e32 v68, v68, v85
	v_mul_f32_e32 v69, v69, v85
	v_mul_f32_e32 v70, v70, v85
	v_mul_f32_e32 v71, v71, v85
	v_mul_f32_e32 v72, v72, v85
	v_mul_f32_e32 v73, v73, v85
	v_mul_f32_e32 v74, v74, v85
	v_mul_f32_e32 v75, v75, v85
	v_mul_f32_e32 v76, v76, v85
	v_mul_f32_e32 v77, v77, v85
	v_mul_f32_e32 v78, v78, v85
	v_mul_f32_e32 v79, v79, v85
	v_mul_f32_e32 v80, v80, v85
	v_mul_f32_e32 v81, v81, v85
	v_mul_f32_e32 v82, v82, v85
	v_mul_f32_e32 v83, v83, v85
	v_mul_f32_e32 v68, v68, v100
	v_mul_f32_e32 v69, v69, v101
	v_mul_f32_e32 v70, v70, v102
	v_mul_f32_e32 v71, v71, v103
	v_mul_f32_e32 v72, v72, v104
	v_mul_f32_e32 v73, v73, v105
	v_mul_f32_e32 v74, v74, v106
	v_mul_f32_e32 v75, v75, v107
	v_mul_f32_e32 v76, v76, v108
	v_mul_f32_e32 v77, v77, v109
	v_mul_f32_e32 v78, v78, v110
	v_mul_f32_e32 v79, v79, v111
	v_mul_f32_e32 v80, v80, v112
	v_mul_f32_e32 v81, v81, v113
	v_mul_f32_e32 v82, v82, v114
	v_mul_f32_e32 v83, v83, v115
	v_cvt_pk_bf16_f32 v176, v68, v69
	v_cvt_pk_bf16_f32 v177, v70, v71
	v_cvt_pk_bf16_f32 v178, v72, v73
	v_cvt_pk_bf16_f32 v179, v74, v75
	v_cvt_pk_bf16_f32 v180, v76, v77
	v_cvt_pk_bf16_f32 v181, v78, v79
	v_cvt_pk_bf16_f32 v182, v80, v81
	v_cvt_pk_bf16_f32 v183, v82, v83
	global_store_dwordx2 v1, v[176:177], s[76:77] offset:0
	global_store_dwordx2 v1, v[178:179], s[76:77] offset:512
	global_store_dwordx2 v1, v[180:181], s[76:77] offset:1024
	global_store_dwordx2 v1, v[182:183], s[76:77] offset:1536
	s_add_u32 s76, s76, 0x400000
	s_addc_u32 s77, s77, 0
	global_load_dwordx2 v[36:37], v1, s[70:71] offset:0
	global_load_dwordx2 v[38:39], v1, s[70:71] offset:512
	global_load_dwordx2 v[40:41], v1, s[70:71] offset:1024
	global_load_dwordx2 v[42:43], v1, s[70:71] offset:1536
	global_load_dwordx2 v[44:45], v1, s[72:73] offset:0
	global_load_dwordx2 v[46:47], v1, s[72:73] offset:512
	global_load_dwordx2 v[48:49], v1, s[72:73] offset:1024
	global_load_dwordx2 v[50:51], v1, s[72:73] offset:1536
	s_add_u32 s70, s70, 0x400000
	s_addc_u32 s71, s71, 0
	s_add_u32 s72, s72, 0x400000
	s_addc_u32 s73, s73, 0
	s_waitcnt vmcnt(32)
	v_lshlrev_b32_e32 v68, 16, v52
	v_and_b32_e32 v69, 0xffff0000, v52
	v_lshlrev_b32_e32 v70, 16, v53
	v_and_b32_e32 v71, 0xffff0000, v53
	v_lshlrev_b32_e32 v72, 16, v54
	v_and_b32_e32 v73, 0xffff0000, v54
	v_lshlrev_b32_e32 v74, 16, v55
	v_and_b32_e32 v75, 0xffff0000, v55
	v_lshlrev_b32_e32 v76, 16, v56
	v_and_b32_e32 v77, 0xffff0000, v56
	v_lshlrev_b32_e32 v78, 16, v57
	v_and_b32_e32 v79, 0xffff0000, v57
	v_lshlrev_b32_e32 v80, 16, v58
	v_and_b32_e32 v81, 0xffff0000, v58
	v_lshlrev_b32_e32 v82, 16, v59
	v_and_b32_e32 v83, 0xffff0000, v59
	v_mul_f32_e32 v86, v68, v68
	v_mul_f32_e32 v87, v72, v72
	v_mul_f32_e32 v88, v76, v76
	v_mul_f32_e32 v89, v80, v80
	v_fmac_f32_e32 v86, v69, v69
	v_fmac_f32_e32 v87, v73, v73
	v_fmac_f32_e32 v88, v77, v77
	v_fmac_f32_e32 v89, v81, v81
	v_fmac_f32_e32 v86, v70, v70
	v_fmac_f32_e32 v87, v74, v74
	v_fmac_f32_e32 v88, v78, v78
	v_fmac_f32_e32 v89, v82, v82
	v_fmac_f32_e32 v86, v71, v71
	v_fmac_f32_e32 v87, v75, v75
	v_fmac_f32_e32 v88, v79, v79
	v_fmac_f32_e32 v89, v83, v83
	v_add_f32_e32 v84, v86, v87
	v_add_f32_e32 v84, v84, v88
	v_add_f32_e32 v84, v84, v89
	v_lshlrev_b32_e32 v160, 16, v60
	v_and_b32_e32 v161, 0xffff0000, v60
	v_add_f32_dpp v84, v84, v84 quad_perm:[1,0,3,2] row_mask:0xf bank_mask:0xf
	v_lshlrev_b32_e32 v162, 16, v61
	v_and_b32_e32 v163, 0xffff0000, v61
	v_add_f32_dpp v84, v84, v84 quad_perm:[2,3,0,1] row_mask:0xf bank_mask:0xf
	v_lshlrev_b32_e32 v164, 16, v62
	v_and_b32_e32 v165, 0xffff0000, v62
	v_add_f32_dpp v84, v84, v84 row_half_mirror row_mask:0xf bank_mask:0xf
	v_lshlrev_b32_e32 v166, 16, v63
	v_and_b32_e32 v167, 0xffff0000, v63
	v_add_f32_dpp v84, v84, v84 row_mirror row_mask:0xf bank_mask:0xf
	v_lshlrev_b32_e32 v168, 16, v64
	v_and_b32_e32 v169, 0xffff0000, v64
	v_add_f32_dpp v84, v84, v84 row_bcast:15 row_mask:0xa bank_mask:0xf
	v_lshlrev_b32_e32 v170, 16, v65
	v_and_b32_e32 v171, 0xffff0000, v65
	v_add_f32_dpp v84, v84, v84 row_bcast:31 row_mask:0xc bank_mask:0xf
	v_lshlrev_b32_e32 v172, 16, v66
	v_and_b32_e32 v173, 0xffff0000, v66
	v_lshlrev_b32_e32 v174, 16, v67
	v_and_b32_e32 v175, 0xffff0000, v67
	s_nop 0
	v_readlane_b32 s83, v84, 63
	s_nop 2
	v_fma_f32 v84, s83, v2, v3
	v_rsq_f32_e32 v84, v84
	s_nop 0
	v_mul_f32_e32 v68, v68, v84
	v_mul_f32_e32 v69, v69, v84
	v_mul_f32_e32 v70, v70, v84
	v_mul_f32_e32 v71, v71, v84
	v_mul_f32_e32 v72, v72, v84
	v_mul_f32_e32 v73, v73, v84
	v_mul_f32_e32 v74, v74, v84
	v_mul_f32_e32 v75, v75, v84
	v_mul_f32_e32 v76, v76, v84
	v_mul_f32_e32 v77, v77, v84
	v_mul_f32_e32 v78, v78, v84
	v_mul_f32_e32 v79, v79, v84
	v_mul_f32_e32 v80, v80, v84
	v_mul_f32_e32 v81, v81, v84
	v_mul_f32_e32 v82, v82, v84
	v_mul_f32_e32 v83, v83, v84
	v_fma_f32 v68, v68, v4, v160
	v_fma_f32 v69, v69, v5, v161
	v_fma_f32 v70, v70, v6, v162
	v_fma_f32 v71, v71, v7, v163
	v_fma_f32 v72, v72, v8, v164
	v_fma_f32 v73, v73, v9, v165
	v_fma_f32 v74, v74, v10, v166
	v_fma_f32 v75, v75, v11, v167
	v_fma_f32 v76, v76, v12, v168
	v_fma_f32 v77, v77, v13, v169
	v_fma_f32 v78, v78, v14, v170
	v_fma_f32 v79, v79, v15, v171
	v_fma_f32 v80, v80, v16, v172
	v_fma_f32 v81, v81, v17, v173
	v_fma_f32 v82, v82, v18, v174
	v_fma_f32 v83, v83, v19, v175
	v_mul_f32_e32 v86, v68, v68
	v_mul_f32_e32 v87, v72, v72
	v_mul_f32_e32 v88, v76, v76
	v_mul_f32_e32 v89, v80, v80
	v_fmac_f32_e32 v86, v69, v69
	v_fmac_f32_e32 v87, v73, v73
	v_fmac_f32_e32 v88, v77, v77
	v_fmac_f32_e32 v89, v81, v81
	v_fmac_f32_e32 v86, v70, v70
	v_fmac_f32_e32 v87, v74, v74
	v_fmac_f32_e32 v88, v78, v78
	v_fmac_f32_e32 v89, v82, v82
	v_fmac_f32_e32 v86, v71, v71
	v_fmac_f32_e32 v87, v75, v75
	v_fmac_f32_e32 v88, v79, v79
	v_fmac_f32_e32 v89, v83, v83
	v_add_f32_e32 v85, v86, v87
	v_add_f32_e32 v85, v85, v88
	v_add_f32_e32 v85, v85, v89
	v_cvt_pk_bf16_f32 v90, v68, v69
	v_cvt_pk_bf16_f32 v91, v70, v71
	v_add_f32_dpp v85, v85, v85 quad_perm:[1,0,3,2] row_mask:0xf bank_mask:0xf
	v_cvt_pk_bf16_f32 v92, v72, v73
	v_cvt_pk_bf16_f32 v93, v74, v75
	v_add_f32_dpp v85, v85, v85 quad_perm:[2,3,0,1] row_mask:0xf bank_mask:0xf
	v_cvt_pk_bf16_f32 v94, v76, v77
	v_cvt_pk_bf16_f32 v95, v78, v79
	v_add_f32_dpp v85, v85, v85 row_half_mirror row_mask:0xf bank_mask:0xf
	v_cvt_pk_bf16_f32 v96, v80, v81
	v_cvt_pk_bf16_f32 v97, v82, v83
	v_add_f32_dpp v85, v85, v85 row_mirror row_mask:0xf bank_mask:0xf
	s_nop 1
	v_add_f32_dpp v85, v85, v85 row_bcast:15 row_mask:0xa bank_mask:0xf
	s_nop 1
	v_add_f32_dpp v85, v85, v85 row_bcast:31 row_mask:0xc bank_mask:0xf
	global_store_dwordx2 v1, v[90:91], s[74:75] offset:0
	global_store_dwordx2 v1, v[92:93], s[74:75] offset:512
	global_store_dwordx2 v1, v[94:95], s[74:75] offset:1024
	global_store_dwordx2 v1, v[96:97], s[74:75] offset:1536
	v_readlane_b32 s84, v85, 63
	s_add_u32 s74, s74, 0x400000
	s_addc_u32 s75, s75, 0
	s_nop 0
	v_fma_f32 v85, s84, v2, v3
	v_rsq_f32_e32 v85, v85
	s_nop 0
	v_mul_f32_e32 v68, v68, v85
	v_mul_f32_e32 v69, v69, v85
	v_mul_f32_e32 v70, v70, v85
	v_mul_f32_e32 v71, v71, v85
	v_mul_f32_e32 v72, v72, v85
	v_mul_f32_e32 v73, v73, v85
	v_mul_f32_e32 v74, v74, v85
	v_mul_f32_e32 v75, v75, v85
	v_mul_f32_e32 v76, v76, v85
	v_mul_f32_e32 v77, v77, v85
	v_mul_f32_e32 v78, v78, v85
	v_mul_f32_e32 v79, v79, v85
	v_mul_f32_e32 v80, v80, v85
	v_mul_f32_e32 v81, v81, v85
	v_mul_f32_e32 v82, v82, v85
	v_mul_f32_e32 v83, v83, v85
	v_mul_f32_e32 v68, v68, v100
	v_mul_f32_e32 v69, v69, v101
	v_mul_f32_e32 v70, v70, v102
	v_mul_f32_e32 v71, v71, v103
	v_mul_f32_e32 v72, v72, v104
	v_mul_f32_e32 v73, v73, v105
	v_mul_f32_e32 v74, v74, v106
	v_mul_f32_e32 v75, v75, v107
	v_mul_f32_e32 v76, v76, v108
	v_mul_f32_e32 v77, v77, v109
	v_mul_f32_e32 v78, v78, v110
	v_mul_f32_e32 v79, v79, v111
	v_mul_f32_e32 v80, v80, v112
	v_mul_f32_e32 v81, v81, v113
	v_mul_f32_e32 v82, v82, v114
	v_mul_f32_e32 v83, v83, v115
	v_cvt_pk_bf16_f32 v176, v68, v69
	v_cvt_pk_bf16_f32 v177, v70, v71
	v_cvt_pk_bf16_f32 v178, v72, v73
	v_cvt_pk_bf16_f32 v179, v74, v75
	v_cvt_pk_bf16_f32 v180, v76, v77
	v_cvt_pk_bf16_f32 v181, v78, v79
	v_cvt_pk_bf16_f32 v182, v80, v81
	v_cvt_pk_bf16_f32 v183, v82, v83
	global_store_dwordx2 v1, v[176:177], s[76:77] offset:0
	global_store_dwordx2 v1, v[178:179], s[76:77] offset:512
	global_store_dwordx2 v1, v[180:181], s[76:77] offset:1024
	global_store_dwordx2 v1, v[182:183], s[76:77] offset:1536
	s_add_u32 s76, s76, 0x400000
	s_addc_u32 s77, s77, 0
	s_cmp_eq_u32 s82, 0
	s_cbranch_scc0 .Lrows_p13_r8ok
	s_sub_u32 s70, s70, 0x400000
	s_subb_u32 s71, s71, 0
	s_sub_u32 s72, s72, 0x400000
	s_subb_u32 s73, s73, 0

.Lrows_p13_done:
.LBB0_1209:
	s_or_b64 exec, exec, s[8:9]
	s_cmp_lt_i32 s25, 15
	s_cbranch_scc1 .LBB0_1263
	s_waitcnt vmcnt(0)
	s_waitcnt vmcnt(0) lgkmcnt(0)
	s_barrier
	s_and_saveexec_b64 s[4:5], s[92:93]
	s_cbranch_execz .LBB0_1262
	s_add_i32 s8, 0, 0x20000
	v_mov_b32_e32 v0, s8
	s_waitcnt vmcnt(0) expcnt(0) lgkmcnt(0)
	ds_read_b32 v2, v0
	s_add_i32 s8, 0, 0x20004
	v_mov_b32_e32 v0, s8
	ds_read_b32 v0, v0
	s_waitcnt lgkmcnt(1)
	v_cmp_ne_u32_e32 vcc, 0, v2
	s_cbranch_vccnz .LBB0_1226
	s_load_dwordx2 s[10:11], s[6:7], 0x4
	s_add_u32 s6, s48, 0x1000
	s_addc_u32 s7, s49, 0
	s_add_u32 s8, s48, 0x1100
	s_addc_u32 s9, s49, 0
	s_waitcnt lgkmcnt(0)
	s_mul_i32 s3, s10, s3
	s_add_u32 s10, s48, 0x1200
	s_mul_i32 s3, s3, s11
	s_addc_u32 s11, s49, 0
	s_add_u32 s12, s48, 0x1300
	s_addc_u32 s13, s49, 0
	s_mov_b32 s20, 1
	v_mov_b32_e32 v16, 0
	s_branch .LBB0_1214

.LBB0_1450:
	s_cmp_lt_i32 s24, 17
	s_cselect_b64 s[4:5], -1, 0
	s_cmp_gt_i32 s25, 16
	s_cselect_b64 s[6:7], -1, 0
	s_and_b64 s[4:5], s[4:5], s[6:7]
	s_andn2_b64 vcc, exec, s[4:5]
	s_cbranch_vccnz .LBB0_1512
	s_mov_b64 exec, -1
	s_load_dword s8, s[0:1], 0x148
	s_add_u32 s4, s0, 0x148
	s_addc_u32 s5, s1, 0
	s_load_dwordx2 s[78:79], s[0:1], 0x40
	v_lshrrev_b32_e32 v0, 6, v129
	v_and_b32_e32 v1, 63, v129
	v_readfirstlane_b32 s68, v0
	v_lshlrev_b32_e32 v0, 4, v1
	v_lshlrev_b32_e32 v1, 3, v1
	v_mov_b32_e32 v2, 0x3a800000
	v_mov_b32_e32 v3, 0x358637bd
	s_lshl_b32 s69, s2, 3
	s_add_u32 s68, s68, s69
	s_waitcnt lgkmcnt(0)
	s_add_u32 s78, s78, 0x1000
	s_addc_u32 s79, s79, 0
	global_load_dwordx4 v[4:7], v0, s[78:79] offset:0
	global_load_dwordx4 v[8:11], v0, s[78:79] offset:1024
	global_load_dwordx4 v[12:15], v0, s[78:79] offset:2048
	global_load_dwordx4 v[16:19], v0, s[78:79] offset:3072
	s_lshl_b32 s86, s68, 11
	s_add_u32 s70, s44, s86
	s_addc_u32 s71, s45, 0
	s_add_u32 s72, s50, s86
	s_addc_u32 s73, s51, 0
	s_lshl_b32 s87, s68, 12
	s_add_u32 s76, s58, s87
	s_addc_u32 s77, s59, 0
	s_cmpk_lt_u32 s68, 0x200
	s_cselect_b32 s82, 1, 0
	global_load_dwordx2 v[20:21], v1, s[70:71] offset:0
	global_load_dwordx2 v[22:23], v1, s[70:71] offset:512
	global_load_dwordx2 v[24:25], v1, s[70:71] offset:1024
	global_load_dwordx2 v[26:27], v1, s[70:71] offset:1536
	global_load_dwordx2 v[28:29], v1, s[72:73] offset:0
	global_load_dwordx2 v[30:31], v1, s[72:73] offset:512
	global_load_dwordx2 v[32:33], v1, s[72:73] offset:1024
	global_load_dwordx2 v[34:35], v1, s[72:73] offset:1536
	s_add_u32 s70, s70, 0x400000
	s_addc_u32 s71, s71, 0
	s_add_u32 s72, s72, 0x400000
	s_addc_u32 s73, s73, 0
	global_load_dwordx2 v[36:37], v1, s[70:71] offset:0
	global_load_dwordx2 v[38:39], v1, s[70:71] offset:512
	global_load_dwordx2 v[40:41], v1, s[70:71] offset:1024
	global_load_dwordx2 v[42:43], v1, s[70:71] offset:1536
	global_load_dwordx2 v[44:45], v1, s[72:73] offset:0
	global_load_dwordx2 v[46:47], v1, s[72:73] offset:512
	global_load_dwordx2 v[48:49], v1, s[72:73] offset:1024
	global_load_dwordx2 v[50:51], v1, s[72:73] offset:1536
	s_add_u32 s70, s70, 0x400000
	s_addc_u32 s71, s71, 0
	s_add_u32 s72, s72, 0x400000
	s_addc_u32 s73, s73, 0
	global_load_dwordx2 v[52:53], v1, s[70:71] offset:0
	global_load_dwordx2 v[54:55], v1, s[70:71] offset:512
	global_load_dwordx2 v[56:57], v1, s[70:71] offset:1024
	global_load_dwordx2 v[58:59], v1, s[70:71] offset:1536
	global_load_dwordx2 v[60:61], v1, s[72:73] offset:0
	global_load_dwordx2 v[62:63], v1, s[72:73] offset:512
	global_load_dwordx2 v[64:65], v1, s[72:73] offset:1024
	global_load_dwordx2 v[66:67], v1, s[72:73] offset:1536
	s_add_u32 s70, s70, 0x400000
	s_addc_u32 s71, s71, 0
	s_add_u32 s72, s72, 0x400000
	s_addc_u32 s73, s73, 0
	s_waitcnt vmcnt(16)
	v_lshlrev_b32_e32 v68, 16, v20
	v_and_b32_e32 v69, 0xffff0000, v20
	v_lshlrev_b32_e32 v70, 16, v21
	v_and_b32_e32 v71, 0xffff0000, v21
	v_lshlrev_b32_e32 v72, 16, v22
	v_and_b32_e32 v73, 0xffff0000, v22
	v_lshlrev_b32_e32 v74, 16, v23
	v_and_b32_e32 v75, 0xffff0000, v23
	v_lshlrev_b32_e32 v76, 16, v24
	v_and_b32_e32 v77, 0xffff0000, v24
	v_lshlrev_b32_e32 v78, 16, v25
	v_and_b32_e32 v79, 0xffff0000, v25
	v_lshlrev_b32_e32 v80, 16, v26
	v_and_b32_e32 v81, 0xffff0000, v26
	v_lshlrev_b32_e32 v82, 16, v27
	v_and_b32_e32 v83, 0xffff0000, v27
	v_mul_f32_e32 v86, v68, v68
	v_mul_f32_e32 v87, v72, v72
	v_mul_f32_e32 v88, v76, v76
	v_mul_f32_e32 v89, v80, v80
	v_fmac_f32_e32 v86, v69, v69
	v_fmac_f32_e32 v87, v73, v73
	v_fmac_f32_e32 v88, v77, v77
	v_fmac_f32_e32 v89, v81, v81
	v_fmac_f32_e32 v86, v70, v70
	v_fmac_f32_e32 v87, v74, v74
	v_fmac_f32_e32 v88, v78, v78
	v_fmac_f32_e32 v89, v82, v82
	v_fmac_f32_e32 v86, v71, v71
	v_fmac_f32_e32 v87, v75, v75
	v_fmac_f32_e32 v88, v79, v79
	v_fmac_f32_e32 v89, v83, v83
	v_add_f32_e32 v84, v86, v87
	v_add_f32_e32 v84, v84, v88
	v_add_f32_e32 v84, v84, v89
	v_lshlrev_b32_e32 v160, 16, v28
	v_and_b32_e32 v161, 0xffff0000, v28
	v_add_f32_dpp v84, v84, v84 quad_perm:[1,0,3,2] row_mask:0xf bank_mask:0xf
	v_lshlrev_b32_e32 v162, 16, v29
	v_and_b32_e32 v163, 0xffff0000, v29
	v_add_f32_dpp v84, v84, v84 quad_perm:[2,3,0,1] row_mask:0xf bank_mask:0xf
	v_lshlrev_b32_e32 v164, 16, v30
	v_and_b32_e32 v165, 0xffff0000, v30
	v_add_f32_dpp v84, v84, v84 row_half_mirror row_mask:0xf bank_mask:0xf
	v_lshlrev_b32_e32 v166, 16, v31
	v_and_b32_e32 v167, 0xffff0000, v31
	v_add_f32_dpp v84, v84, v84 row_mirror row_mask:0xf bank_mask:0xf
	v_lshlrev_b32_e32 v168, 16, v32
	v_and_b32_e32 v169, 0xffff0000, v32
	v_add_f32_dpp v84, v84, v84 row_bcast:15 row_mask:0xa bank_mask:0xf
	v_lshlrev_b32_e32 v170, 16, v33
	v_and_b32_e32 v171, 0xffff0000, v33
	v_add_f32_dpp v84, v84, v84 row_bcast:31 row_mask:0xc bank_mask:0xf
	v_lshlrev_b32_e32 v172, 16, v34
	v_and_b32_e32 v173, 0xffff0000, v34
	v_lshlrev_b32_e32 v174, 16, v35
	v_and_b32_e32 v175, 0xffff0000, v35
	s_nop 0
	v_readlane_b32 s83, v84, 63
	s_nop 2
	v_fma_f32 v84, s83, v2, v3
	v_rsq_f32_e32 v84, v84
	s_nop 0
	v_mul_f32_e32 v68, v68, v84
	v_mul_f32_e32 v69, v69, v84
	v_mul_f32_e32 v70, v70, v84
	v_mul_f32_e32 v71, v71, v84
	v_mul_f32_e32 v72, v72, v84
	v_mul_f32_e32 v73, v73, v84
	v_mul_f32_e32 v74, v74, v84
	v_mul_f32_e32 v75, v75, v84
	v_mul_f32_e32 v76, v76, v84
	v_mul_f32_e32 v77, v77, v84
	v_mul_f32_e32 v78, v78, v84
	v_mul_f32_e32 v79, v79, v84
	v_mul_f32_e32 v80, v80, v84
	v_mul_f32_e32 v81, v81, v84
	v_mul_f32_e32 v82, v82, v84
	v_mul_f32_e32 v83, v83, v84
	v_fma_f32 v68, v68, v4, v160
	v_fma_f32 v69, v69, v5, v161
	v_fma_f32 v70, v70, v6, v162
	v_fma_f32 v71, v71, v7, v163
	v_fma_f32 v72, v72, v8, v164
	v_fma_f32 v73, v73, v9, v165
	v_fma_f32 v74, v74, v10, v166
	v_fma_f32 v75, v75, v11, v167
	v_fma_f32 v76, v76, v12, v168
	v_fma_f32 v77, v77, v13, v169
	v_fma_f32 v78, v78, v14, v170
	v_fma_f32 v79, v79, v15, v171
	v_fma_f32 v80, v80, v16, v172
	v_fma_f32 v81, v81, v17, v173
	v_fma_f32 v82, v82, v18, v174
	v_fma_f32 v83, v83, v19, v175
	global_store_dwordx4 v0, v[68:71], s[76:77] offset:0
	global_store_dwordx4 v0, v[72:75], s[76:77] offset:1024
	global_store_dwordx4 v0, v[76:79], s[76:77] offset:2048
	global_store_dwordx4 v0, v[80:83], s[76:77] offset:3072
	s_add_u32 s76, s76, 0x800000
	s_addc_u32 s77, s77, 0
	global_load_dwordx2 v[20:21], v1, s[70:71] offset:0
	global_load_dwordx2 v[22:23], v1, s[70:71] offset:512
	global_load_dwordx2 v[24:25], v1, s[70:71] offset:1024
	global_load_dwordx2 v[26:27], v1, s[70:71] offset:1536
	global_load_dwordx2 v[28:29], v1, s[72:73] offset:0
	global_load_dwordx2 v[30:31], v1, s[72:73] offset:512
	global_load_dwordx2 v[32:33], v1, s[72:73] offset:1024
	global_load_dwordx2 v[34:35], v1, s[72:73] offset:1536
	s_add_u32 s70, s70, 0x400000
	s_addc_u32 s71, s71, 0
	s_add_u32 s72, s72, 0x400000
	s_addc_u32 s73, s73, 0
	s_waitcnt vmcnt(20)
	v_lshlrev_b32_e32 v68, 16, v36
	v_and_b32_e32 v69, 0xffff0000, v36
	v_lshlrev_b32_e32 v70, 16, v37
	v_and_b32_e32 v71, 0xffff0000, v37
	v_lshlrev_b32_e32 v72, 16, v38
	v_and_b32_e32 v73, 0xffff0000, v38
	v_lshlrev_b32_e32 v74, 16, v39
	v_and_b32_e32 v75, 0xffff0000, v39
	v_lshlrev_b32_e32 v76, 16, v40
	v_and_b32_e32 v77, 0xffff0000, v40
	v_lshlrev_b32_e32 v78, 16, v41
	v_and_b32_e32 v79, 0xffff0000, v41
	v_lshlrev_b32_e32 v80, 16, v42
	v_and_b32_e32 v81, 0xffff0000, v42
	v_lshlrev_b32_e32 v82, 16, v43
	v_and_b32_e32 v83, 0xffff0000, v43
	v_mul_f32_e32 v86, v68, v68
	v_mul_f32_e32 v87, v72, v72
	v_mul_f32_e32 v88, v76, v76
	v_mul_f32_e32 v89, v80, v80
	v_fmac_f32_e32 v86, v69, v69
	v_fmac_f32_e32 v87, v73, v73
	v_fmac_f32_e32 v88, v77, v77
	v_fmac_f32_e32 v89, v81, v81
	v_fmac_f32_e32 v86, v70, v70
	v_fmac_f32_e32 v87, v74, v74
	v_fmac_f32_e32 v88, v78, v78
	v_fmac_f32_e32 v89, v82, v82
	v_fmac_f32_e32 v86, v71, v71
	v_fmac_f32_e32 v87, v75, v75
	v_fmac_f32_e32 v88, v79, v79
	v_fmac_f32_e32 v89, v83, v83
	v_add_f32_e32 v84, v86, v87
	v_add_f32_e32 v84, v84, v88
	v_add_f32_e32 v84, v84, v89
	v_lshlrev_b32_e32 v160, 16, v44
	v_and_b32_e32 v161, 0xffff0000, v44
	v_add_f32_dpp v84, v84, v84 quad_perm:[1,0,3,2] row_mask:0xf bank_mask:0xf
	v_lshlrev_b32_e32 v162, 16, v45
	v_and_b32_e32 v163, 0xffff0000, v45
	v_add_f32_dpp v84, v84, v84 quad_perm:[2,3,0,1] row_mask:0xf bank_mask:0xf
	v_lshlrev_b32_e32 v164, 16, v46
	v_and_b32_e32 v165, 0xffff0000, v46
	v_add_f32_dpp v84, v84, v84 row_half_mirror row_mask:0xf bank_mask:0xf
	v_lshlrev_b32_e32 v166, 16, v47
	v_and_b32_e32 v167, 0xffff0000, v47
	v_add_f32_dpp v84, v84, v84 row_mirror row_mask:0xf bank_mask:0xf
	v_lshlrev_b32_e32 v168, 16, v48
	v_and_b32_e32 v169, 0xffff0000, v48
	v_add_f32_dpp v84, v84, v84 row_bcast:15 row_mask:0xa bank_mask:0xf
	v_lshlrev_b32_e32 v170, 16, v49
	v_and_b32_e32 v171, 0xffff0000, v49
	v_add_f32_dpp v84, v84, v84 row_bcast:31 row_mask:0xc bank_mask:0xf
	v_lshlrev_b32_e32 v172, 16, v50
	v_and_b32_e32 v173, 0xffff0000, v50
	v_lshlrev_b32_e32 v174, 16, v51
	v_and_b32_e32 v175, 0xffff0000, v51
	s_nop 0
	v_readlane_b32 s83, v84, 63
	s_nop 2
	v_fma_f32 v84, s83, v2, v3
	v_rsq_f32_e32 v84, v84
	s_nop 0
	v_mul_f32_e32 v68, v68, v84
	v_mul_f32_e32 v69, v69, v84
	v_mul_f32_e32 v70, v70, v84
	v_mul_f32_e32 v71, v71, v84
	v_mul_f32_e32 v72, v72, v84
	v_mul_f32_e32 v73, v73, v84
	v_mul_f32_e32 v74, v74, v84
	v_mul_f32_e32 v75, v75, v84
	v_mul_f32_e32 v76, v76, v84
	v_mul_f32_e32 v77, v77, v84
	v_mul_f32_e32 v78, v78, v84
	v_mul_f32_e32 v79, v79, v84
	v_mul_f32_e32 v80, v80, v84
	v_mul_f32_e32 v81, v81, v84
	v_mul_f32_e32 v82, v82, v84
	v_mul_f32_e32 v83, v83, v84
	v_fma_f32 v68, v68, v4, v160
	v_fma_f32 v69, v69, v5, v161
	v_fma_f32 v70, v70, v6, v162
	v_fma_f32 v71, v71, v7, v163
	v_fma_f32 v72, v72, v8, v164
	v_fma_f32 v73, v73, v9, v165
	v_fma_f32 v74, v74, v10, v166
	v_fma_f32 v75, v75, v11, v167
	v_fma_f32 v76, v76, v12, v168
	v_fma_f32 v77, v77, v13, v169
	v_fma_f32 v78, v78, v14, v170
	v_fma_f32 v79, v79, v15, v171
	v_fma_f32 v80, v80, v16, v172
	v_fma_f32 v81, v81, v17, v173
	v_fma_f32 v82, v82, v18, v174
	v_fma_f32 v83, v83, v19, v175
	global_store_dwordx4 v0, v[68:71], s[76:77] offset:0
	global_store_dwordx4 v0, v[72:75], s[76:77] offset:1024
	global_store_dwordx4 v0, v[76:79], s[76:77] offset:2048
	global_store_dwordx4 v0, v[80:83], s[76:77] offset:3072
	s_add_u32 s76, s76, 0x800000
	s_addc_u32 s77, s77, 0
	global_load_dwordx2 v[36:37], v1, s[70:71] offset:0
	global_load_dwordx2 v[38:39], v1, s[70:71] offset:512
	global_load_dwordx2 v[40:41], v1, s[70:71] offset:1024
	global_load_dwordx2 v[42:43], v1, s[70:71] offset:1536
	global_load_dwordx2 v[44:45], v1, s[72:73] offset:0
	global_load_dwordx2 v[46:47], v1, s[72:73] offset:512
	global_load_dwordx2 v[48:49], v1, s[72:73] offset:1024
	global_load_dwordx2 v[50:51], v1, s[72:73] offset:1536
	s_add_u32 s70, s70, 0x400000
	s_addc_u32 s71, s71, 0
	s_add_u32 s72, s72, 0x400000
	s_addc_u32 s73, s73, 0
	s_waitcnt vmcnt(24)
	v_lshlrev_b32_e32 v68, 16, v52
	v_and_b32_e32 v69, 0xffff0000, v52
	v_lshlrev_b32_e32 v70, 16, v53
	v_and_b32_e32 v71, 0xffff0000, v53
	v_lshlrev_b32_e32 v72, 16, v54
	v_and_b32_e32 v73, 0xffff0000, v54
	v_lshlrev_b32_e32 v74, 16, v55
	v_and_b32_e32 v75, 0xffff0000, v55
	v_lshlrev_b32_e32 v76, 16, v56
	v_and_b32_e32 v77, 0xffff0000, v56
	v_lshlrev_b32_e32 v78, 16, v57
	v_and_b32_e32 v79, 0xffff0000, v57
	v_lshlrev_b32_e32 v80, 16, v58
	v_and_b32_e32 v81, 0xffff0000, v58
	v_lshlrev_b32_e32 v82, 16, v59
	v_and_b32_e32 v83, 0xffff0000, v59
	v_mul_f32_e32 v86, v68, v68
	v_mul_f32_e32 v87, v72, v72
	v_mul_f32_e32 v88, v76, v76
	v_mul_f32_e32 v89, v80, v80
	v_fmac_f32_e32 v86, v69, v69
	v_fmac_f32_e32 v87, v73, v73
	v_fmac_f32_e32 v88, v77, v77
	v_fmac_f32_e32 v89, v81, v81
	v_fmac_f32_e32 v86, v70, v70
	v_fmac_f32_e32 v87, v74, v74
	v_fmac_f32_e32 v88, v78, v78
	v_fmac_f32_e32 v89, v82, v82
	v_fmac_f32_e32 v86, v71, v71
	v_fmac_f32_e32 v87, v75, v75
	v_fmac_f32_e32 v88, v79, v79
	v_fmac_f32_e32 v89, v83, v83
	v_add_f32_e32 v84, v86, v87
	v_add_f32_e32 v84, v84, v88
	v_add_f32_e32 v84, v84, v89
	v_lshlrev_b32_e32 v160, 16, v60
	v_and_b32_e32 v161, 0xffff0000, v60
	v_add_f32_dpp v84, v84, v84 quad_perm:[1,0,3,2] row_mask:0xf bank_mask:0xf
	v_lshlrev_b32_e32 v162, 16, v61
	v_and_b32_e32 v163, 0xffff0000, v61
	v_add_f32_dpp v84, v84, v84 quad_perm:[2,3,0,1] row_mask:0xf bank_mask:0xf
	v_lshlrev_b32_e32 v164, 16, v62
	v_and_b32_e32 v165, 0xffff0000, v62
	v_add_f32_dpp v84, v84, v84 row_half_mirror row_mask:0xf bank_mask:0xf
	v_lshlrev_b32_e32 v166, 16, v63
	v_and_b32_e32 v167, 0xffff0000, v63
	v_add_f32_dpp v84, v84, v84 row_mirror row_mask:0xf bank_mask:0xf
	v_lshlrev_b32_e32 v168, 16, v64
	v_and_b32_e32 v169, 0xffff0000, v64
	v_add_f32_dpp v84, v84, v84 row_bcast:15 row_mask:0xa bank_mask:0xf
	v_lshlrev_b32_e32 v170, 16, v65
	v_and_b32_e32 v171, 0xffff0000, v65
	v_add_f32_dpp v84, v84, v84 row_bcast:31 row_mask:0xc bank_mask:0xf
	v_lshlrev_b32_e32 v172, 16, v66
	v_and_b32_e32 v173, 0xffff0000, v66
	v_lshlrev_b32_e32 v174, 16, v67
	v_and_b32_e32 v175, 0xffff0000, v67
	s_nop 0
	v_readlane_b32 s83, v84, 63
	s_nop 2
	v_fma_f32 v84, s83, v2, v3
	v_rsq_f32_e32 v84, v84
	s_nop 0
	v_mul_f32_e32 v68, v68, v84
	v_mul_f32_e32 v69, v69, v84
	v_mul_f32_e32 v70, v70, v84
	v_mul_f32_e32 v71, v71, v84
	v_mul_f32_e32 v72, v72, v84
	v_mul_f32_e32 v73, v73, v84
	v_mul_f32_e32 v74, v74, v84
	v_mul_f32_e32 v75, v75, v84
	v_mul_f32_e32 v76, v76, v84
	v_mul_f32_e32 v77, v77, v84
	v_mul_f32_e32 v78, v78, v84
	v_mul_f32_e32 v79, v79, v84
	v_mul_f32_e32 v80, v80, v84
	v_mul_f32_e32 v81, v81, v84
	v_mul_f32_e32 v82, v82, v84
	v_mul_f32_e32 v83, v83, v84
	v_fma_f32 v68, v68, v4, v160
	v_fma_f32 v69, v69, v5, v161
	v_fma_f32 v70, v70, v6, v162
	v_fma_f32 v71, v71, v7, v163
	v_fma_f32 v72, v72, v8, v164
	v_fma_f32 v73, v73, v9, v165
	v_fma_f32 v74, v74, v10, v166
	v_fma_f32 v75, v75, v11, v167
	v_fma_f32 v76, v76, v12, v168
	v_fma_f32 v77, v77, v13, v169
	v_fma_f32 v78, v78, v14, v170
	v_fma_f32 v79, v79, v15, v171
	v_fma_f32 v80, v80, v16, v172
	v_fma_f32 v81, v81, v17, v173
	v_fma_f32 v82, v82, v18, v174
	v_fma_f32 v83, v83, v19, v175
	global_store_dwordx4 v0, v[68:71], s[76:77] offset:0
	global_store_dwordx4 v0, v[72:75], s[76:77] offset:1024
	global_store_dwordx4 v0, v[76:79], s[76:77] offset:2048
	global_store_dwordx4 v0, v[80:83], s[76:77] offset:3072
	s_add_u32 s76, s76, 0x800000
	s_addc_u32 s77, s77, 0
	global_load_dwordx2 v[52:53], v1, s[70:71] offset:0
	global_load_dwordx2 v[54:55], v1, s[70:71] offset:512
	global_load_dwordx2 v[56:57], v1, s[70:71] offset:1024
	global_load_dwordx2 v[58:59], v1, s[70:71] offset:1536
	global_load_dwordx2 v[60:61], v1, s[72:73] offset:0
	global_load_dwordx2 v[62:63], v1, s[72:73] offset:512
	global_load_dwordx2 v[64:65], v1, s[72:73] offset:1024
	global_load_dwordx2 v[66:67], v1, s[72:73] offset:1536
	s_add_u32 s70, s70, 0x400000
	s_addc_u32 s71, s71, 0
	s_add_u32 s72, s72, 0x400000
	s_addc_u32 s73, s73, 0
	s_waitcnt vmcnt(24)
	v_lshlrev_b32_e32 v68, 16, v20
	v_and_b32_e32 v69, 0xffff0000, v20
	v_lshlrev_b32_e32 v70, 16, v21
	v_and_b32_e32 v71, 0xffff0000, v21
	v_lshlrev_b32_e32 v72, 16, v22
	v_and_b32_e32 v73, 0xffff0000, v22
	v_lshlrev_b32_e32 v74, 16, v23
	v_and_b32_e32 v75, 0xffff0000, v23
	v_lshlrev_b32_e32 v76, 16, v24
	v_and_b32_e32 v77, 0xffff0000, v24
	v_lshlrev_b32_e32 v78, 16, v25
	v_and_b32_e32 v79, 0xffff0000, v25
	v_lshlrev_b32_e32 v80, 16, v26
	v_and_b32_e32 v81, 0xffff0000, v26
	v_lshlrev_b32_e32 v82, 16, v27
	v_and_b32_e32 v83, 0xffff0000, v27
	v_mul_f32_e32 v86, v68, v68
	v_mul_f32_e32 v87, v72, v72
	v_mul_f32_e32 v88, v76, v76
	v_mul_f32_e32 v89, v80, v80
	v_fmac_f32_e32 v86, v69, v69
	v_fmac_f32_e32 v87, v73, v73
	v_fmac_f32_e32 v88, v77, v77
	v_fmac_f32_e32 v89, v81, v81
	v_fmac_f32_e32 v86, v70, v70
	v_fmac_f32_e32 v87, v74, v74
	v_fmac_f32_e32 v88, v78, v78
	v_fmac_f32_e32 v89, v82, v82
	v_fmac_f32_e32 v86, v71, v71
	v_fmac_f32_e32 v87, v75, v75
	v_fmac_f32_e32 v88, v79, v79
	v_fmac_f32_e32 v89, v83, v83
	v_add_f32_e32 v84, v86, v87
	v_add_f32_e32 v84, v84, v88
	v_add_f32_e32 v84, v84, v89
	v_lshlrev_b32_e32 v160, 16, v28
	v_and_b32_e32 v161, 0xffff0000, v28
	v_add_f32_dpp v84, v84, v84 quad_perm:[1,0,3,2] row_mask:0xf bank_mask:0xf
	v_lshlrev_b32_e32 v162, 16, v29
	v_and_b32_e32 v163, 0xffff0000, v29
	v_add_f32_dpp v84, v84, v84 quad_perm:[2,3,0,1] row_mask:0xf bank_mask:0xf
	v_lshlrev_b32_e32 v164, 16, v30
	v_and_b32_e32 v165, 0xffff0000, v30
	v_add_f32_dpp v84, v84, v84 row_half_mirror row_mask:0xf bank_mask:0xf
	v_lshlrev_b32_e32 v166, 16, v31
	v_and_b32_e32 v167, 0xffff0000, v31
	v_add_f32_dpp v84, v84, v84 row_mirror row_mask:0xf bank_mask:0xf
	v_lshlrev_b32_e32 v168, 16, v32
	v_and_b32_e32 v169, 0xffff0000, v32
	v_add_f32_dpp v84, v84, v84 row_bcast:15 row_mask:0xa bank_mask:0xf
	v_lshlrev_b32_e32 v170, 16, v33
	v_and_b32_e32 v171, 0xffff0000, v33
	v_add_f32_dpp v84, v84, v84 row_bcast:31 row_mask:0xc bank_mask:0xf
	v_lshlrev_b32_e32 v172, 16, v34
	v_and_b32_e32 v173, 0xffff0000, v34
	v_lshlrev_b32_e32 v174, 16, v35
	v_and_b32_e32 v175, 0xffff0000, v35
	s_nop 0
	v_readlane_b32 s83, v84, 63
	s_nop 2
	v_fma_f32 v84, s83, v2, v3
	v_rsq_f32_e32 v84, v84
	s_nop 0
	v_mul_f32_e32 v68, v68, v84
	v_mul_f32_e32 v69, v69, v84
	v_mul_f32_e32 v70, v70, v84
	v_mul_f32_e32 v71, v71, v84
	v_mul_f32_e32 v72, v72, v84
	v_mul_f32_e32 v73, v73, v84
	v_mul_f32_e32 v74, v74, v84
	v_mul_f32_e32 v75, v75, v84
	v_mul_f32_e32 v76, v76, v84
	v_mul_f32_e32 v77, v77, v84
	v_mul_f32_e32 v78, v78, v84
	v_mul_f32_e32 v79, v79, v84
	v_mul_f32_e32 v80, v80, v84
	v_mul_f32_e32 v81, v81, v84
	v_mul_f32_e32 v82, v82, v84
	v_mul_f32_e32 v83, v83, v84
	v_fma_f32 v68, v68, v4, v160
	v_fma_f32 v69, v69, v5, v161
	v_fma_f32 v70, v70, v6, v162
	v_fma_f32 v71, v71, v7, v163
	v_fma_f32 v72, v72, v8, v164
	v_fma_f32 v73, v73, v9, v165
	v_fma_f32 v74, v74, v10, v166
	v_fma_f32 v75, v75, v11, v167
	v_fma_f32 v76, v76, v12, v168
	v_fma_f32 v77, v77, v13, v169
	v_fma_f32 v78, v78, v14, v170
	v_fma_f32 v79, v79, v15, v171
	v_fma_f32 v80, v80, v16, v172
	v_fma_f32 v81, v81, v17, v173
	v_fma_f32 v82, v82, v18, v174
	v_fma_f32 v83, v83, v19, v175
	global_store_dwordx4 v0, v[68:71], s[76:77] offset:0
	global_store_dwordx4 v0, v[72:75], s[76:77] offset:1024
	global_store_dwordx4 v0, v[76:79], s[76:77] offset:2048
	global_store_dwordx4 v0, v[80:83], s[76:77] offset:3072
	s_add_u32 s76, s76, 0x800000
	s_addc_u32 s77, s77, 0
	global_load_dwordx2 v[20:21], v1, s[70:71] offset:0
	global_load_dwordx2 v[22:23], v1, s[70:71] offset:512
	global_load_dwordx2 v[24:25], v1, s[70:71] offset:1024
	global_load_dwordx2 v[26:27], v1, s[70:71] offset:1536
	global_load_dwordx2 v[28:29], v1, s[72:73] offset:0
	global_load_dwordx2 v[30:31], v1, s[72:73] offset:512
	global_load_dwordx2 v[32:33], v1, s[72:73] offset:1024
	global_load_dwordx2 v[34:35], v1, s[72:73] offset:1536
	s_add_u32 s70, s70, 0x400000
	s_addc_u32 s71, s71, 0
	s_add_u32 s72, s72, 0x400000
	s_addc_u32 s73, s73, 0
	s_waitcnt vmcnt(24)
	v_lshlrev_b32_e32 v68, 16, v36
	v_and_b32_e32 v69, 0xffff0000, v36
	v_lshlrev_b32_e32 v70, 16, v37
	v_and_b32_e32 v71, 0xffff0000, v37
	v_lshlrev_b32_e32 v72, 16, v38
	v_and_b32_e32 v73, 0xffff0000, v38
	v_lshlrev_b32_e32 v74, 16, v39
	v_and_b32_e32 v75, 0xffff0000, v39
	v_lshlrev_b32_e32 v76, 16, v40
	v_and_b32_e32 v77, 0xffff0000, v40
	v_lshlrev_b32_e32 v78, 16, v41
	v_and_b32_e32 v79, 0xffff0000, v41
	v_lshlrev_b32_e32 v80, 16, v42
	v_and_b32_e32 v81, 0xffff0000, v42
	v_lshlrev_b32_e32 v82, 16, v43
	v_and_b32_e32 v83, 0xffff0000, v43
	v_mul_f32_e32 v86, v68, v68
	v_mul_f32_e32 v87, v72, v72
	v_mul_f32_e32 v88, v76, v76
	v_mul_f32_e32 v89, v80, v80
	v_fmac_f32_e32 v86, v69, v69
	v_fmac_f32_e32 v87, v73, v73
	v_fmac_f32_e32 v88, v77, v77
	v_fmac_f32_e32 v89, v81, v81
	v_fmac_f32_e32 v86, v70, v70
	v_fmac_f32_e32 v87, v74, v74
	v_fmac_f32_e32 v88, v78, v78
	v_fmac_f32_e32 v89, v82, v82
	v_fmac_f32_e32 v86, v71, v71
	v_fmac_f32_e32 v87, v75, v75
	v_fmac_f32_e32 v88, v79, v79
	v_fmac_f32_e32 v89, v83, v83
	v_add_f32_e32 v84, v86, v87
	v_add_f32_e32 v84, v84, v88
	v_add_f32_e32 v84, v84, v89
	v_lshlrev_b32_e32 v160, 16, v44
	v_and_b32_e32 v161, 0xffff0000, v44
	v_add_f32_dpp v84, v84, v84 quad_perm:[1,0,3,2] row_mask:0xf bank_mask:0xf
	v_lshlrev_b32_e32 v162, 16, v45
	v_and_b32_e32 v163, 0xffff0000, v45
	v_add_f32_dpp v84, v84, v84 quad_perm:[2,3,0,1] row_mask:0xf bank_mask:0xf
	v_lshlrev_b32_e32 v164, 16, v46
	v_and_b32_e32 v165, 0xffff0000, v46
	v_add_f32_dpp v84, v84, v84 row_half_mirror row_mask:0xf bank_mask:0xf
	v_lshlrev_b32_e32 v166, 16, v47
	v_and_b32_e32 v167, 0xffff0000, v47
	v_add_f32_dpp v84, v84, v84 row_mirror row_mask:0xf bank_mask:0xf
	v_lshlrev_b32_e32 v168, 16, v48
	v_and_b32_e32 v169, 0xffff0000, v48
	v_add_f32_dpp v84, v84, v84 row_bcast:15 row_mask:0xa bank_mask:0xf
	v_lshlrev_b32_e32 v170, 16, v49
	v_and_b32_e32 v171, 0xffff0000, v49
	v_add_f32_dpp v84, v84, v84 row_bcast:31 row_mask:0xc bank_mask:0xf
	v_lshlrev_b32_e32 v172, 16, v50
	v_and_b32_e32 v173, 0xffff0000, v50
	v_lshlrev_b32_e32 v174, 16, v51
	v_and_b32_e32 v175, 0xffff0000, v51
	s_nop 0
	v_readlane_b32 s83, v84, 63
	s_nop 2
	v_fma_f32 v84, s83, v2, v3
	v_rsq_f32_e32 v84, v84
	s_nop 0
	v_mul_f32_e32 v68, v68, v84
	v_mul_f32_e32 v69, v69, v84
	v_mul_f32_e32 v70, v70, v84
	v_mul_f32_e32 v71, v71, v84
	v_mul_f32_e32 v72, v72, v84
	v_mul_f32_e32 v73, v73, v84
	v_mul_f32_e32 v74, v74, v84
	v_mul_f32_e32 v75, v75, v84
	v_mul_f32_e32 v76, v76, v84
	v_mul_f32_e32 v77, v77, v84
	v_mul_f32_e32 v78, v78, v84
	v_mul_f32_e32 v79, v79, v84
	v_mul_f32_e32 v80, v80, v84
	v_mul_f32_e32 v81, v81, v84
	v_mul_f32_e32 v82, v82, v84
	v_mul_f32_e32 v83, v83, v84
	v_fma_f32 v68, v68, v4, v160
	v_fma_f32 v69, v69, v5, v161
	v_fma_f32 v70, v70, v6, v162
	v_fma_f32 v71, v71, v7, v163
	v_fma_f32 v72, v72, v8, v164
	v_fma_f32 v73, v73, v9, v165
	v_fma_f32 v74, v74, v10, v166
	v_fma_f32 v75, v75, v11, v167
	v_fma_f32 v76, v76, v12, v168
	v_fma_f32 v77, v77, v13, v169
	v_fma_f32 v78, v78, v14, v170
	v_fma_f32 v79, v79, v15, v171
	v_fma_f32 v80, v80, v16, v172
	v_fma_f32 v81, v81, v17, v173
	v_fma_f32 v82, v82, v18, v174
	v_fma_f32 v83, v83, v19, v175
	global_store_dwordx4 v0, v[68:71], s[76:77] offset:0
	global_store_dwordx4 v0, v[72:75], s[76:77] offset:1024
	global_store_dwordx4 v0, v[76:79], s[76:77] offset:2048
	global_store_dwordx4 v0, v[80:83], s[76:77] offset:3072
	s_add_u32 s76, s76, 0x800000
	s_addc_u32 s77, s77, 0
	global_load_dwordx2 v[36:37], v1, s[70:71] offset:0
	global_load_dwordx2 v[38:39], v1, s[70:71] offset:512
	global_load_dwordx2 v[40:41], v1, s[70:71] offset:1024
	global_load_dwordx2 v[42:43], v1, s[70:71] offset:1536
	global_load_dwordx2 v[44:45], v1, s[72:73] offset:0
	global_load_dwordx2 v[46:47], v1, s[72:73] offset:512
	global_load_dwordx2 v[48:49], v1, s[72:73] offset:1024
	global_load_dwordx2 v[50:51], v1, s[72:73] offset:1536
	s_add_u32 s70, s70, 0x400000
	s_addc_u32 s71, s71, 0
	s_add_u32 s72, s72, 0x400000
	s_addc_u32 s73, s73, 0
	s_waitcnt vmcnt(24)
	v_lshlrev_b32_e32 v68, 16, v52
	v_and_b32_e32 v69, 0xffff0000, v52
	v_lshlrev_b32_e32 v70, 16, v53
	v_and_b32_e32 v71, 0xffff0000, v53
	v_lshlrev_b32_e32 v72, 16, v54
	v_and_b32_e32 v73, 0xffff0000, v54
	v_lshlrev_b32_e32 v74, 16, v55
	v_and_b32_e32 v75, 0xffff0000, v55
	v_lshlrev_b32_e32 v76, 16, v56
	v_and_b32_e32 v77, 0xffff0000, v56
	v_lshlrev_b32_e32 v78, 16, v57
	v_and_b32_e32 v79, 0xffff0000, v57
	v_lshlrev_b32_e32 v80, 16, v58
	v_and_b32_e32 v81, 0xffff0000, v58
	v_lshlrev_b32_e32 v82, 16, v59
	v_and_b32_e32 v83, 0xffff0000, v59
	v_mul_f32_e32 v86, v68, v68
	v_mul_f32_e32 v87, v72, v72
	v_mul_f32_e32 v88, v76, v76
	v_mul_f32_e32 v89, v80, v80
	v_fmac_f32_e32 v86, v69, v69
	v_fmac_f32_e32 v87, v73, v73
	v_fmac_f32_e32 v88, v77, v77
	v_fmac_f32_e32 v89, v81, v81
	v_fmac_f32_e32 v86, v70, v70
	v_fmac_f32_e32 v87, v74, v74
	v_fmac_f32_e32 v88, v78, v78
	v_fmac_f32_e32 v89, v82, v82
	v_fmac_f32_e32 v86, v71, v71
	v_fmac_f32_e32 v87, v75, v75
	v_fmac_f32_e32 v88, v79, v79
	v_fmac_f32_e32 v89, v83, v83
	v_add_f32_e32 v84, v86, v87
	v_add_f32_e32 v84, v84, v88
	v_add_f32_e32 v84, v84, v89
	v_lshlrev_b32_e32 v160, 16, v60
	v_and_b32_e32 v161, 0xffff0000, v60
	v_add_f32_dpp v84, v84, v84 quad_perm:[1,0,3,2] row_mask:0xf bank_mask:0xf
	v_lshlrev_b32_e32 v162, 16, v61
	v_and_b32_e32 v163, 0xffff0000, v61
	v_add_f32_dpp v84, v84, v84 quad_perm:[2,3,0,1] row_mask:0xf bank_mask:0xf
	v_lshlrev_b32_e32 v164, 16, v62
	v_and_b32_e32 v165, 0xffff0000, v62
	v_add_f32_dpp v84, v84, v84 row_half_mirror row_mask:0xf bank_mask:0xf
	v_lshlrev_b32_e32 v166, 16, v63
	v_and_b32_e32 v167, 0xffff0000, v63
	v_add_f32_dpp v84, v84, v84 row_mirror row_mask:0xf bank_mask:0xf
	v_lshlrev_b32_e32 v168, 16, v64
	v_and_b32_e32 v169, 0xffff0000, v64
	v_add_f32_dpp v84, v84, v84 row_bcast:15 row_mask:0xa bank_mask:0xf
	v_lshlrev_b32_e32 v170, 16, v65
	v_and_b32_e32 v171, 0xffff0000, v65
	v_add_f32_dpp v84, v84, v84 row_bcast:31 row_mask:0xc bank_mask:0xf
	v_lshlrev_b32_e32 v172, 16, v66
	v_and_b32_e32 v173, 0xffff0000, v66
	v_lshlrev_b32_e32 v174, 16, v67
	v_and_b32_e32 v175, 0xffff0000, v67
	s_nop 0
	v_readlane_b32 s83, v84, 63
	s_nop 2
	v_fma_f32 v84, s83, v2, v3
	v_rsq_f32_e32 v84, v84
	s_nop 0
	v_mul_f32_e32 v68, v68, v84
	v_mul_f32_e32 v69, v69, v84
	v_mul_f32_e32 v70, v70, v84
	v_mul_f32_e32 v71, v71, v84
	v_mul_f32_e32 v72, v72, v84
	v_mul_f32_e32 v73, v73, v84
	v_mul_f32_e32 v74, v74, v84
	v_mul_f32_e32 v75, v75, v84
	v_mul_f32_e32 v76, v76, v84
	v_mul_f32_e32 v77, v77, v84
	v_mul_f32_e32 v78, v78, v84
	v_mul_f32_e32 v79, v79, v84
	v_mul_f32_e32 v80, v80, v84
	v_mul_f32_e32 v81, v81, v84
	v_mul_f32_e32 v82, v82, v84
	v_mul_f32_e32 v83, v83, v84
	v_fma_f32 v68, v68, v4, v160
	v_fma_f32 v69, v69, v5, v161
	v_fma_f32 v70, v70, v6, v162
	v_fma_f32 v71, v71, v7, v163
	v_fma_f32 v72, v72, v8, v164
	v_fma_f32 v73, v73, v9, v165
	v_fma_f32 v74, v74, v10, v166
	v_fma_f32 v75, v75, v11, v167
	v_fma_f32 v76, v76, v12, v168
	v_fma_f32 v77, v77, v13, v169
	v_fma_f32 v78, v78, v14, v170
	v_fma_f32 v79, v79, v15, v171
	v_fma_f32 v80, v80, v16, v172
	v_fma_f32 v81, v81, v17, v173
	v_fma_f32 v82, v82, v18, v174
	v_fma_f32 v83, v83, v19, v175
	global_store_dwordx4 v0, v[68:71], s[76:77] offset:0
	global_store_dwordx4 v0, v[72:75], s[76:77] offset:1024
	global_store_dwordx4 v0, v[76:79], s[76:77] offset:2048
	global_store_dwordx4 v0, v[80:83], s[76:77] offset:3072
	s_add_u32 s76, s76, 0x800000
	s_addc_u32 s77, s77, 0
	s_cmp_eq_u32 s82, 0
	s_cbranch_scc0 .Lrows_p16_r8ok
	s_sub_u32 s70, s70, 0x400000
	s_subb_u32 s71, s71, 0
	s_sub_u32 s72, s72, 0x400000
	s_subb_u32 s73, s73, 0
.Lrows_p16_r8ok:
	global_load_dwordx2 v[52:53], v1, s[70:71] offset:0
	global_load_dwordx2 v[54:55], v1, s[70:71] offset:512
	global_load_dwordx2 v[56:57], v1, s[70:71] offset:1024
	global_load_dwordx2 v[58:59], v1, s[70:71] offset:1536
	global_load_dwordx2 v[60:61], v1, s[72:73] offset:0
	global_load_dwordx2 v[62:63], v1, s[72:73] offset:512
	global_load_dwordx2 v[64:65], v1, s[72:73] offset:1024
	global_load_dwordx2 v[66:67], v1, s[72:73] offset:1536
	s_add_u32 s70, s70, 0x400000
	s_addc_u32 s71, s71, 0
	s_add_u32 s72, s72, 0x400000
	s_addc_u32 s73, s73, 0
	s_waitcnt vmcnt(24)
	v_lshlrev_b32_e32 v68, 16, v20
	v_and_b32_e32 v69, 0xffff0000, v20
	v_lshlrev_b32_e32 v70, 16, v21
	v_and_b32_e32 v71, 0xffff0000, v21
	v_lshlrev_b32_e32 v72, 16, v22
	v_and_b32_e32 v73, 0xffff0000, v22
	v_lshlrev_b32_e32 v74, 16, v23
	v_and_b32_e32 v75, 0xffff0000, v23
	v_lshlrev_b32_e32 v76, 16, v24
	v_and_b32_e32 v77, 0xffff0000, v24
	v_lshlrev_b32_e32 v78, 16, v25
	v_and_b32_e32 v79, 0xffff0000, v25
	v_lshlrev_b32_e32 v80, 16, v26
	v_and_b32_e32 v81, 0xffff0000, v26
	v_lshlrev_b32_e32 v82, 16, v27
	v_and_b32_e32 v83, 0xffff0000, v27
	v_mul_f32_e32 v86, v68, v68
	v_mul_f32_e32 v87, v72, v72
	v_mul_f32_e32 v88, v76, v76
	v_mul_f32_e32 v89, v80, v80
	v_fmac_f32_e32 v86, v69, v69
	v_fmac_f32_e32 v87, v73, v73
	v_fmac_f32_e32 v88, v77, v77
	v_fmac_f32_e32 v89, v81, v81
	v_fmac_f32_e32 v86, v70, v70
	v_fmac_f32_e32 v87, v74, v74
	v_fmac_f32_e32 v88, v78, v78
	v_fmac_f32_e32 v89, v82, v82
	v_fmac_f32_e32 v86, v71, v71
	v_fmac_f32_e32 v87, v75, v75
	v_fmac_f32_e32 v88, v79, v79
	v_fmac_f32_e32 v89, v83, v83
	v_add_f32_e32 v84, v86, v87
	v_add_f32_e32 v84, v84, v88
	v_add_f32_e32 v84, v84, v89
	v_lshlrev_b32_e32 v160, 16, v28
	v_and_b32_e32 v161, 0xffff0000, v28
	v_add_f32_dpp v84, v84, v84 quad_perm:[1,0,3,2] row_mask:0xf bank_mask:0xf
	v_lshlrev_b32_e32 v162, 16, v29
	v_and_b32_e32 v163, 0xffff0000, v29
	v_add_f32_dpp v84, v84, v84 quad_perm:[2,3,0,1] row_mask:0xf bank_mask:0xf
	v_lshlrev_b32_e32 v164, 16, v30
	v_and_b32_e32 v165, 0xffff0000, v30
	v_add_f32_dpp v84, v84, v84 row_half_mirror row_mask:0xf bank_mask:0xf
	v_lshlrev_b32_e32 v166, 16, v31
	v_and_b32_e32 v167, 0xffff0000, v31
	v_add_f32_dpp v84, v84, v84 row_mirror row_mask:0xf bank_mask:0xf
	v_lshlrev_b32_e32 v168, 16, v32
	v_and_b32_e32 v169, 0xffff0000, v32
	v_add_f32_dpp v84, v84, v84 row_bcast:15 row_mask:0xa bank_mask:0xf
	v_lshlrev_b32_e32 v170, 16, v33
	v_and_b32_e32 v171, 0xffff0000, v33
	v_add_f32_dpp v84, v84, v84 row_bcast:31 row_mask:0xc bank_mask:0xf
	v_lshlrev_b32_e32 v172, 16, v34
	v_and_b32_e32 v173, 0xffff0000, v34
	v_lshlrev_b32_e32 v174, 16, v35
	v_and_b32_e32 v175, 0xffff0000, v35
	s_nop 0
	v_readlane_b32 s83, v84, 63
	s_nop 2
	v_fma_f32 v84, s83, v2, v3
	v_rsq_f32_e32 v84, v84
	s_nop 0
	v_mul_f32_e32 v68, v68, v84
	v_mul_f32_e32 v69, v69, v84
	v_mul_f32_e32 v70, v70, v84
	v_mul_f32_e32 v71, v71, v84
	v_mul_f32_e32 v72, v72, v84
	v_mul_f32_e32 v73, v73, v84
	v_mul_f32_e32 v74, v74, v84
	v_mul_f32_e32 v75, v75, v84
	v_mul_f32_e32 v76, v76, v84
	v_mul_f32_e32 v77, v77, v84
	v_mul_f32_e32 v78, v78, v84
	v_mul_f32_e32 v79, v79, v84
	v_mul_f32_e32 v80, v80, v84
	v_mul_f32_e32 v81, v81, v84
	v_mul_f32_e32 v82, v82, v84
	v_mul_f32_e32 v83, v83, v84
	v_fma_f32 v68, v68, v4, v160
	v_fma_f32 v69, v69, v5, v161
	v_fma_f32 v70, v70, v6, v162
	v_fma_f32 v71, v71, v7, v163
	v_fma_f32 v72, v72, v8, v164
	v_fma_f32 v73, v73, v9, v165
	v_fma_f32 v74, v74, v10, v166
	v_fma_f32 v75, v75, v11, v167
	v_fma_f32 v76, v76, v12, v168
	v_fma_f32 v77, v77, v13, v169
	v_fma_f32 v78, v78, v14, v170
	v_fma_f32 v79, v79, v15, v171
	v_fma_f32 v80, v80, v16, v172
	v_fma_f32 v81, v81, v17, v173
	v_fma_f32 v82, v82, v18, v174
	v_fma_f32 v83, v83, v19, v175
	global_store_dwordx4 v0, v[68:71], s[76:77] offset:0
	global_store_dwordx4 v0, v[72:75], s[76:77] offset:1024
	global_store_dwordx4 v0, v[76:79], s[76:77] offset:2048
	global_store_dwordx4 v0, v[80:83], s[76:77] offset:3072
	s_add_u32 s76, s76, 0x800000
	s_addc_u32 s77, s77, 0
	s_waitcnt vmcnt(16)
	v_lshlrev_b32_e32 v68, 16, v36
	v_and_b32_e32 v69, 0xffff0000, v36
	v_lshlrev_b32_e32 v70, 16, v37
	v_and_b32_e32 v71, 0xffff0000, v37
	v_lshlrev_b32_e32 v72, 16, v38
	v_and_b32_e32 v73, 0xffff0000, v38
	v_lshlrev_b32_e32 v74, 16, v39
	v_and_b32_e32 v75, 0xffff0000, v39
	v_lshlrev_b32_e32 v76, 16, v40
	v_and_b32_e32 v77, 0xffff0000, v40
	v_lshlrev_b32_e32 v78, 16, v41
	v_and_b32_e32 v79, 0xffff0000, v41
	v_lshlrev_b32_e32 v80, 16, v42
	v_and_b32_e32 v81, 0xffff0000, v42
	v_lshlrev_b32_e32 v82, 16, v43
	v_and_b32_e32 v83, 0xffff0000, v43
	v_mul_f32_e32 v86, v68, v68
	v_mul_f32_e32 v87, v72, v72
	v_mul_f32_e32 v88, v76, v76
	v_mul_f32_e32 v89, v80, v80
	v_fmac_f32_e32 v86, v69, v69
	v_fmac_f32_e32 v87, v73, v73
	v_fmac_f32_e32 v88, v77, v77
	v_fmac_f32_e32 v89, v81, v81
	v_fmac_f32_e32 v86, v70, v70
	v_fmac_f32_e32 v87, v74, v74
	v_fmac_f32_e32 v88, v78, v78
	v_fmac_f32_e32 v89, v82, v82
	v_fmac_f32_e32 v86, v71, v71
	v_fmac_f32_e32 v87, v75, v75
	v_fmac_f32_e32 v88, v79, v79
	v_fmac_f32_e32 v89, v83, v83
	v_add_f32_e32 v84, v86, v87
	v_add_f32_e32 v84, v84, v88
	v_add_f32_e32 v84, v84, v89
	v_lshlrev_b32_e32 v160, 16, v44
	v_and_b32_e32 v161, 0xffff0000, v44
	v_add_f32_dpp v84, v84, v84 quad_perm:[1,0,3,2] row_mask:0xf bank_mask:0xf
	v_lshlrev_b32_e32 v162, 16, v45
	v_and_b32_e32 v163, 0xffff0000, v45
	v_add_f32_dpp v84, v84, v84 quad_perm:[2,3,0,1] row_mask:0xf bank_mask:0xf
	v_lshlrev_b32_e32 v164, 16, v46
	v_and_b32_e32 v165, 0xffff0000, v46
	v_add_f32_dpp v84, v84, v84 row_half_mirror row_mask:0xf bank_mask:0xf
	v_lshlrev_b32_e32 v166, 16, v47
	v_and_b32_e32 v167, 0xffff0000, v47
	v_add_f32_dpp v84, v84, v84 row_mirror row_mask:0xf bank_mask:0xf
	v_lshlrev_b32_e32 v168, 16, v48
	v_and_b32_e32 v169, 0xffff0000, v48
	v_add_f32_dpp v84, v84, v84 row_bcast:15 row_mask:0xa bank_mask:0xf
	v_lshlrev_b32_e32 v170, 16, v49
	v_and_b32_e32 v171, 0xffff0000, v49
	v_add_f32_dpp v84, v84, v84 row_bcast:31 row_mask:0xc bank_mask:0xf
	v_lshlrev_b32_e32 v172, 16, v50
	v_and_b32_e32 v173, 0xffff0000, v50
	v_lshlrev_b32_e32 v174, 16, v51
	v_and_b32_e32 v175, 0xffff0000, v51
	s_nop 0
	v_readlane_b32 s83, v84, 63
	s_nop 2
	v_fma_f32 v84, s83, v2, v3
	v_rsq_f32_e32 v84, v84
	s_nop 0
	v_mul_f32_e32 v68, v68, v84
	v_mul_f32_e32 v69, v69, v84
	v_mul_f32_e32 v70, v70, v84
	v_mul_f32_e32 v71, v71, v84
	v_mul_f32_e32 v72, v72, v84
	v_mul_f32_e32 v73, v73, v84
	v_mul_f32_e32 v74, v74, v84
	v_mul_f32_e32 v75, v75, v84
	v_mul_f32_e32 v76, v76, v84
	v_mul_f32_e32 v77, v77, v84
	v_mul_f32_e32 v78, v78, v84
	v_mul_f32_e32 v79, v79, v84
	v_mul_f32_e32 v80, v80, v84
	v_mul_f32_e32 v81, v81, v84
	v_mul_f32_e32 v82, v82, v84
	v_mul_f32_e32 v83, v83, v84
	v_fma_f32 v68, v68, v4, v160
	v_fma_f32 v69, v69, v5, v161
	v_fma_f32 v70, v70, v6, v162
	v_fma_f32 v71, v71, v7, v163
	v_fma_f32 v72, v72, v8, v164
	v_fma_f32 v73, v73, v9, v165
	v_fma_f32 v74, v74, v10, v166
	v_fma_f32 v75, v75, v11, v167
	v_fma_f32 v76, v76, v12, v168
	v_fma_f32 v77, v77, v13, v169
	v_fma_f32 v78, v78, v14, v170
	v_fma_f32 v79, v79, v15, v171
	v_fma_f32 v80, v80, v16, v172
	v_fma_f32 v81, v81, v17, v173
	v_fma_f32 v82, v82, v18, v174
	v_fma_f32 v83, v83, v19, v175
	global_store_dwordx4 v0, v[68:71], s[76:77] offset:0
	global_store_dwordx4 v0, v[72:75], s[76:77] offset:1024
	global_store_dwordx4 v0, v[76:79], s[76:77] offset:2048
	global_store_dwordx4 v0, v[80:83], s[76:77] offset:3072
	s_add_u32 s76, s76, 0x800000
	s_addc_u32 s77, s77, 0
	s_cmp_eq_u32 s82, 0
	s_cbranch_scc1 .Lrows_p16_done
	s_waitcnt vmcnt(8)
	v_lshlrev_b32_e32 v68, 16, v52
	v_and_b32_e32 v69, 0xffff0000, v52
	v_lshlrev_b32_e32 v70, 16, v53
	v_and_b32_e32 v71, 0xffff0000, v53
	v_lshlrev_b32_e32 v72, 16, v54
	v_and_b32_e32 v73, 0xffff0000, v54
	v_lshlrev_b32_e32 v74, 16, v55
	v_and_b32_e32 v75, 0xffff0000, v55
	v_lshlrev_b32_e32 v76, 16, v56
	v_and_b32_e32 v77, 0xffff0000, v56
	v_lshlrev_b32_e32 v78, 16, v57
	v_and_b32_e32 v79, 0xffff0000, v57
	v_lshlrev_b32_e32 v80, 16, v58
	v_and_b32_e32 v81, 0xffff0000, v58
	v_lshlrev_b32_e32 v82, 16, v59
	v_and_b32_e32 v83, 0xffff0000, v59
	v_mul_f32_e32 v86, v68, v68
	v_mul_f32_e32 v87, v72, v72
	v_mul_f32_e32 v88, v76, v76
	v_mul_f32_e32 v89, v80, v80
	v_fmac_f32_e32 v86, v69, v69
	v_fmac_f32_e32 v87, v73, v73
	v_fmac_f32_e32 v88, v77, v77
	v_fmac_f32_e32 v89, v81, v81
	v_fmac_f32_e32 v86, v70, v70
	v_fmac_f32_e32 v87, v74, v74
	v_fmac_f32_e32 v88, v78, v78
	v_fmac_f32_e32 v89, v82, v82
	v_fmac_f32_e32 v86, v71, v71
	v_fmac_f32_e32 v87, v75, v75
	v_fmac_f32_e32 v88, v79, v79
	v_fmac_f32_e32 v89, v83, v83
	v_add_f32_e32 v84, v86, v87
	v_add_f32_e32 v84, v84, v88
	v_add_f32_e32 v84, v84, v89
	v_lshlrev_b32_e32 v160, 16, v60
	v_and_b32_e32 v161, 0xffff0000, v60
	v_add_f32_dpp v84, v84, v84 quad_perm:[1,0,3,2] row_mask:0xf bank_mask:0xf
	v_lshlrev_b32_e32 v162, 16, v61
	v_and_b32_e32 v163, 0xffff0000, v61
	v_add_f32_dpp v84, v84, v84 quad_perm:[2,3,0,1] row_mask:0xf bank_mask:0xf
	v_lshlrev_b32_e32 v164, 16, v62
	v_and_b32_e32 v165, 0xffff0000, v62
	v_add_f32_dpp v84, v84, v84 row_half_mirror row_mask:0xf bank_mask:0xf
	v_lshlrev_b32_e32 v166, 16, v63
	v_and_b32_e32 v167, 0xffff0000, v63
	v_add_f32_dpp v84, v84, v84 row_mirror row_mask:0xf bank_mask:0xf
	v_lshlrev_b32_e32 v168, 16, v64
	v_and_b32_e32 v169, 0xffff0000, v64
	v_add_f32_dpp v84, v84, v84 row_bcast:15 row_mask:0xa bank_mask:0xf
	v_lshlrev_b32_e32 v170, 16, v65
	v_and_b32_e32 v171, 0xffff0000, v65
	v_add_f32_dpp v84, v84, v84 row_bcast:31 row_mask:0xc bank_mask:0xf
	v_lshlrev_b32_e32 v172, 16, v66
	v_and_b32_e32 v173, 0xffff0000, v66
	v_lshlrev_b32_e32 v174, 16, v67
	v_and_b32_e32 v175, 0xffff0000, v67
	s_nop 0
	v_readlane_b32 s83, v84, 63
	s_nop 2
	v_fma_f32 v84, s83, v2, v3
	v_rsq_f32_e32 v84, v84
	s_nop 0
	v_mul_f32_e32 v68, v68, v84
	v_mul_f32_e32 v69, v69, v84
	v_mul_f32_e32 v70, v70, v84
	v_mul_f32_e32 v71, v71, v84
	v_mul_f32_e32 v72, v72, v84
	v_mul_f32_e32 v73, v73, v84
	v_mul_f32_e32 v74, v74, v84
	v_mul_f32_e32 v75, v75, v84
	v_mul_f32_e32 v76, v76, v84
	v_mul_f32_e32 v77, v77, v84
	v_mul_f32_e32 v78, v78, v84
	v_mul_f32_e32 v79, v79, v84
	v_mul_f32_e32 v80, v80, v84
	v_mul_f32_e32 v81, v81, v84
	v_mul_f32_e32 v82, v82, v84
	v_mul_f32_e32 v83, v83, v84
	v_fma_f32 v68, v68, v4, v160
	v_fma_f32 v69, v69, v5, v161
	v_fma_f32 v70, v70, v6, v162
	v_fma_f32 v71, v71, v7, v163
	v_fma_f32 v72, v72, v8, v164
	v_fma_f32 v73, v73, v9, v165
	v_fma_f32 v74, v74, v10, v166
	v_fma_f32 v75, v75, v11, v167
	v_fma_f32 v76, v76, v12, v168
	v_fma_f32 v77, v77, v13, v169
	v_fma_f32 v78, v78, v14, v170
	v_fma_f32 v79, v79, v15, v171
	v_fma_f32 v80, v80, v16, v172
	v_fma_f32 v81, v81, v17, v173
	v_fma_f32 v82, v82, v18, v174
	v_fma_f32 v83, v83, v19, v175
	global_store_dwordx4 v0, v[68:71], s[76:77] offset:0
	global_store_dwordx4 v0, v[72:75], s[76:77] offset:1024
	global_store_dwordx4 v0, v[76:79], s[76:77] offset:2048
	global_store_dwordx4 v0, v[80:83], s[76:77] offset:3072
	s_add_u32 s76, s76, 0x800000
	s_addc_u32 s77, s77, 0
.Lrows_p16_done:
.LBB0_1458:
	s_or_b64 exec, exec, s[2:3]
	s_cmp_lt_i32 s25, 18
	s_cbranch_scc1 .LBB0_1512
	s_waitcnt vmcnt(0)
	s_waitcnt vmcnt(0)
	s_barrier
	s_and_saveexec_b64 s[0:1], s[92:93]
	s_cbranch_execz .LBB0_1511
	s_add_i32 s2, 0, 0x20000
	v_mov_b32_e32 v0, s2
	s_waitcnt vmcnt(0) expcnt(0) lgkmcnt(0)
	ds_read_b32 v2, v0
	s_add_i32 s2, 0, 0x20004
	v_mov_b32_e32 v0, s2
	ds_read_b32 v0, v0
	s_waitcnt lgkmcnt(1)
	v_cmp_ne_u32_e32 vcc, 0, v2
	s_cbranch_vccnz .LBB0_1475
	s_load_dwordx2 s[6:7], s[4:5], 0x4
	s_add_u32 s2, s48, 0x1000
	s_addc_u32 s3, s49, 0
	s_add_u32 s4, s48, 0x1100
	s_addc_u32 s5, s49, 0
	s_waitcnt lgkmcnt(0)
	s_mul_i32 s16, s6, s8
	s_add_u32 s6, s48, 0x1200
	s_mul_i32 s16, s16, s7
	s_addc_u32 s7, s49, 0
	s_add_u32 s8, s48, 0x1300
	s_addc_u32 s9, s49, 0
	s_mov_b32 s17, 1
	v_mov_b32_e32 v16, 0
	s_branch .LBB0_1463
